# ssq hoist + K-loop M-block: setprio 1 before the barrier, redundant lgkmcnt(0) and mid-block setprio flips removed
# speedup vs baseline: 1.0077x; 1.0020x over previous
; #define PG8_STAGE(bufoff, gbase, voff) do { _Pragma("unroll") for (int _i = 0; _i < 2; ++_i) \
;         __builtin_amdgcn_global_load_lds((const unsigned*)((const char*)(gbase) + (voff)[_i]), (PG8_LAS unsigned*)(lds + (bufoff) + ldsw + _i * 8192), 16, 0, 0); } while (0)
; #define PG8_LDA(dst, b, h) do { _Pragma("unroll") for (int m = 0; m < 4; ++m) _Pragma("unroll") for (int k = 0; k < 2; ++k) dst[m][k] = *(const PG8_LAS bf16x8*)(lds + PG8_SA(b, h) + aoff + m * 2048 + k * 1024); } while (0)
; #define PG8_LDB(dst, b, h) do { _Pragma("unroll") for (int n = 0; n < 2; ++n) _Pragma("unroll") for (int k = 0; k < 2; ++k) dst[n][k] = *(const PG8_LAS bf16x8*)(lds + PG8_SB(b, h) + boff + n * 2048 + k * 1024); } while (0)
; #define PG8_MMA(ai, bj, At, Bt) do { __builtin_amdgcn_s_setprio(1); _Pragma("unroll") for (int m = 0; m < 4; ++m) _Pragma("unroll") for (int n = 0; n < 2; ++n) _Pragma("unroll") for (int k = 0; k < 2; ++k) \
;         acc[ai][bj][m][n] = __builtin_amdgcn_mfma_f32_16x16x32_bf16(Bt[n][k], At[m][k], acc[ai][bj][m][n], 0, 0, 0); __builtin_amdgcn_s_setprio(0); } while (0)
; #define PG8_BAR __builtin_amdgcn_s_barrier()
; template <class Epi, class Sched, bool ALIGN_EPI = false, bool SP2 = false>
; __device__ __forceinline__ void gemm_phase(PG8_LAS unsigned char* lds, const Gemm g, const Sched& S, const Epi& E, const int wid) {
;     ...
;             PG8_LDB(B0, 0, 0); PG8_LDB(B1, 0, 1); PG8_SCHED; PG8_LDA(At, 0, 0); PG8_STAGE(PG8_SA(1, 1), a1 + hstep, voffA);
;             PG8_WAIT_V(8); PG8_WAIT_L(0); PG8_BAR; PG8_MMA(0, 0, At, B0); PG8_MMA(0, 1, At, B1); PG8_BAR; PG8_SCHED;
;             PG8_LDA(At, 0, 1); PG8_STAGE(PG8_SB(0, 0), b2, voffB); PG8_STAGE(PG8_SB(0, 1), b2 + hstep, voffB); PG8_STAGE(PG8_SA(0, 0), a2, voffA);
;             PG8_WAIT_V(8); PG8_WAIT_L(0); PG8_BAR; PG8_MMA(1, 0, At, B0); PG8_MMA(1, 1, At, B1); PG8_BAR; PG8_SCHED;
;             PG8_LDB(B0, 1, 0); PG8_LDB(B1, 1, 1); PG8_SCHED; PG8_LDA(At, 1, 0); PG8_STAGE(PG8_SA(0, 1), a2 + hstep, voffA);
;             PG8_WAIT_V(8); PG8_WAIT_L(0); PG8_BAR; PG8_MMA(0, 0, At, B0); PG8_MMA(0, 1, At, B1); PG8_BAR; PG8_SCHED;
;             PG8_LDA(At, 1, 1); PG8_STAGE(PG8_SB(1, 0), b3, voffB); PG8_STAGE(PG8_SB(1, 1), b3 + hstep, voffB); PG8_STAGE(PG8_SA(1, 0), a3, voffA);
;             PG8_WAIT_V(8); PG8_WAIT_L(0); PG8_BAR; PG8_MMA(1, 0, At, B0); PG8_MMA(1, 1, At, B1); PG8_BAR; PG8_SCHED;
.LBB0_249:
	ds_read_b128 v[148:151], v160
	ds_read_b128 v[152:155], v160 offset:1024
	ds_read_b128 v[164:167], v160 offset:2048
	ds_read_b128 v[168:171], v160 offset:3072
	ds_read_b128 v[172:175], v161
	ds_read_b128 v[176:179], v161 offset:1024
	ds_read_b128 v[180:183], v161 offset:2048
	ds_read_b128 v[184:187], v161 offset:3072
	s_add_u32 s24, s22, 0xfff00080
	s_addc_u32 s25, s23, -1
	s_cmp_eq_u32 s48, 60
	s_cselect_b32 s27, s15, s25
	s_cselect_b32 s26, s21, s24
	s_cselect_b32 s25, s13, s47
	s_cselect_b32 s24, s45, s46
	v_lshl_add_u64 v[220:221], s[22:23], 0, v[140:141]
	s_add_i32 m0, s30, 0xc000
	ds_read_b128 v[188:191], v162
	ds_read_b128 v[192:195], v162 offset:1024
	ds_read_b128 v[196:199], v162 offset:2048
	ds_read_b128 v[200:203], v162 offset:3072
	ds_read_b128 v[204:207], v162 offset:4096
	ds_read_b128 v[208:211], v162 offset:5120
	ds_read_b128 v[212:215], v162 offset:6144
	ds_read_b128 v[216:219], v162 offset:7168
	global_load_lds_dwordx4 v[220:221], off
	v_lshl_add_u64 v[220:221], s[22:23], 0, v[142:143]
	s_add_i32 m0, s30, 0xe000
	s_nop 0
	global_load_lds_dwordx4 v[220:221], off
	s_waitcnt vmcnt(8)
	s_waitcnt lgkmcnt(0)
	s_setprio 1
	s_barrier
	v_mfma_f32_16x16x32_bf16 v[124:127], v[148:151], v[188:191], v[124:127]
	v_mfma_f32_16x16x32_bf16 v[120:123], v[164:167], v[188:191], v[120:123]
	v_mfma_f32_16x16x32_bf16 v[108:111], v[148:151], v[196:199], v[108:111]
	v_mfma_f32_16x16x32_bf16 v[104:107], v[164:167], v[196:199], v[104:107]
	v_mfma_f32_16x16x32_bf16 v[92:95], v[148:151], v[204:207], v[92:95]
	v_mfma_f32_16x16x32_bf16 v[88:91], v[164:167], v[204:207], v[88:91]
	v_mfma_f32_16x16x32_bf16 v[76:79], v[148:151], v[212:215], v[76:79]
	v_mfma_f32_16x16x32_bf16 v[72:75], v[164:167], v[212:215], v[72:75]
	v_mfma_f32_16x16x32_bf16 v[124:127], v[152:155], v[192:195], v[124:127]
	v_mfma_f32_16x16x32_bf16 v[120:123], v[168:171], v[192:195], v[120:123]
	v_mfma_f32_16x16x32_bf16 v[108:111], v[152:155], v[200:203], v[108:111]
	v_mfma_f32_16x16x32_bf16 v[104:107], v[168:171], v[200:203], v[104:107]
	v_mfma_f32_16x16x32_bf16 v[92:95], v[152:155], v[208:211], v[92:95]
	v_mfma_f32_16x16x32_bf16 v[88:91], v[168:171], v[208:211], v[88:91]
	v_mfma_f32_16x16x32_bf16 v[76:79], v[152:155], v[216:219], v[76:79]
	v_mfma_f32_16x16x32_bf16 v[72:75], v[168:171], v[216:219], v[72:75]
	v_mfma_f32_16x16x32_bf16 v[116:119], v[172:175], v[188:191], v[116:119]
	v_mfma_f32_16x16x32_bf16 v[112:115], v[180:183], v[188:191], v[112:115]
	v_mfma_f32_16x16x32_bf16 v[100:103], v[172:175], v[196:199], v[100:103]
	v_mfma_f32_16x16x32_bf16 v[96:99], v[180:183], v[196:199], v[96:99]
	v_mfma_f32_16x16x32_bf16 v[84:87], v[172:175], v[204:207], v[84:87]
	v_mfma_f32_16x16x32_bf16 v[80:83], v[180:183], v[204:207], v[80:83]
	v_mfma_f32_16x16x32_bf16 v[68:71], v[172:175], v[212:215], v[68:71]
	v_mfma_f32_16x16x32_bf16 v[64:67], v[180:183], v[212:215], v[64:67]
	v_mfma_f32_16x16x32_bf16 v[116:119], v[176:179], v[192:195], v[116:119]
	v_mfma_f32_16x16x32_bf16 v[112:115], v[184:187], v[192:195], v[112:115]
	v_mfma_f32_16x16x32_bf16 v[100:103], v[176:179], v[200:203], v[100:103]
	v_mfma_f32_16x16x32_bf16 v[96:99], v[184:187], v[200:203], v[96:99]
	v_mfma_f32_16x16x32_bf16 v[84:87], v[176:179], v[208:211], v[84:87]
	v_mfma_f32_16x16x32_bf16 v[80:83], v[184:187], v[208:211], v[80:83]
	v_mfma_f32_16x16x32_bf16 v[68:71], v[176:179], v[216:219], v[68:71]
	v_mfma_f32_16x16x32_bf16 v[64:67], v[184:187], v[216:219], v[64:67]
	s_barrier
	s_setprio 0
	s_add_i32 s49, s40, s29
	v_lshl_add_u64 v[220:221], s[24:25], 0, v[130:131]
	s_mov_b32 m0, s49
	ds_read_b128 v[188:191], v162 offset:16384
	ds_read_b128 v[192:195], v162 offset:17408
	ds_read_b128 v[196:199], v162 offset:18432
	ds_read_b128 v[200:203], v162 offset:19456
	ds_read_b128 v[204:207], v162 offset:20480
	ds_read_b128 v[208:211], v162 offset:21504
	ds_read_b128 v[212:215], v162 offset:22528
	ds_read_b128 v[216:219], v162 offset:23552
	global_load_lds_dwordx4 v[220:221], off
	s_add_i32 m0, s49, 0x2000
	s_add_u32 s50, s24, 0x100000
	v_lshl_add_u64 v[222:223], s[24:25], 0, v[134:135]
	s_addc_u32 s51, s25, 0
	s_add_i32 s49, s41, s29
	global_load_lds_dwordx4 v[222:223], off
	v_lshl_add_u64 v[224:225], s[50:51], 0, v[130:131]
	s_mov_b32 m0, s49
	v_lshl_add_u64 v[226:227], s[26:27], 0, v[132:133]
	global_load_lds_dwordx4 v[224:225], off
	v_lshl_add_u64 v[224:225], s[50:51], 0, v[134:135]
	s_add_i32 m0, s49, 0x2000
	s_nop 0
	global_load_lds_dwordx4 v[224:225], off
	v_lshl_add_u64 v[224:225], s[26:27], 0, v[128:129]
	s_mov_b32 m0, s30
	s_nop 0
	global_load_lds_dwordx4 v[224:225], off
	s_mov_b32 m0, s31
	s_nop 0
	global_load_lds_dwordx4 v[226:227], off
	s_waitcnt vmcnt(8)
	s_waitcnt lgkmcnt(0)
	s_setprio 1
	s_barrier
; #define PG8_STAGE(bufoff, gbase, voff) do { _Pragma("unroll") for (int _i = 0; _i < 2; ++_i) \
;         __builtin_amdgcn_global_load_lds((const unsigned*)((const char*)(gbase) + (voff)[_i]), (PG8_LAS unsigned*)(lds + (bufoff) + ldsw + _i * 8192), 16, 0, 0); } while (0)
; #define PG8_LDA(dst, b, h) do { _Pragma("unroll") for (int m = 0; m < 4; ++m) _Pragma("unroll") for (int k = 0; k < 2; ++k) dst[m][k] = *(const PG8_LAS bf16x8*)(lds + PG8_SA(b, h) + aoff + m * 2048 + k * 1024); } while (0)
; #define PG8_LDB(dst, b, h) do { _Pragma("unroll") for (int n = 0; n < 2; ++n) _Pragma("unroll") for (int k = 0; k < 2; ++k) dst[n][k] = *(const PG8_LAS bf16x8*)(lds + PG8_SB(b, h) + boff + n * 2048 + k * 1024); } while (0)
; #define PG8_MMA(ai, bj, At, Bt) do { __builtin_amdgcn_s_setprio(1); _Pragma("unroll") for (int m = 0; m < 4; ++m) _Pragma("unroll") for (int n = 0; n < 2; ++n) _Pragma("unroll") for (int k = 0; k < 2; ++k) \
;         acc[ai][bj][m][n] = __builtin_amdgcn_mfma_f32_16x16x32_bf16(Bt[n][k], At[m][k], acc[ai][bj][m][n], 0, 0, 0); __builtin_amdgcn_s_setprio(0); } while (0)
; #define PG8_BAR __builtin_amdgcn_s_barrier()
; template <class Epi, class Sched, bool ALIGN_EPI = false, bool SP2 = false>
; __device__ __forceinline__ void gemm_phase(PG8_LAS unsigned char* lds, const Gemm g, const Sched& S, const Epi& E, const int wid) {
;     ...
;             PG8_LDB(B0, 0, 0); PG8_LDB(B1, 0, 1); PG8_SCHED; PG8_LDA(At, 0, 0); PG8_STAGE(PG8_SA(1, 1), a1 + hstep, voffA);
;             PG8_WAIT_V(8); PG8_WAIT_L(0); PG8_BAR; PG8_MMA(0, 0, At, B0); PG8_MMA(0, 1, At, B1); PG8_BAR; PG8_SCHED;
;             PG8_LDA(At, 0, 1); PG8_STAGE(PG8_SB(0, 0), b2, voffB); PG8_STAGE(PG8_SB(0, 1), b2 + hstep, voffB); PG8_STAGE(PG8_SA(0, 0), a2, voffA);
;             PG8_WAIT_V(8); PG8_WAIT_L(0); PG8_BAR; PG8_MMA(1, 0, At, B0); PG8_MMA(1, 1, At, B1); PG8_BAR; PG8_SCHED;
;             PG8_LDB(B0, 1, 0); PG8_LDB(B1, 1, 1); PG8_SCHED; PG8_LDA(At, 1, 0); PG8_STAGE(PG8_SA(0, 1), a2 + hstep, voffA);
;             PG8_WAIT_V(8); PG8_WAIT_L(0); PG8_BAR; PG8_MMA(0, 0, At, B0); PG8_MMA(0, 1, At, B1); PG8_BAR; PG8_SCHED;
;             PG8_LDA(At, 1, 1); PG8_STAGE(PG8_SB(1, 0), b3, voffB); PG8_STAGE(PG8_SB(1, 1), b3 + hstep, voffB); PG8_STAGE(PG8_SA(1, 0), a3, voffA);
;             PG8_WAIT_V(8); PG8_WAIT_L(0); PG8_BAR; PG8_MMA(1, 0, At, B0); PG8_MMA(1, 1, At, B1); PG8_BAR; PG8_SCHED;
	v_mfma_f32_16x16x32_bf16 v[60:63], v[148:151], v[188:191], v[60:63]
	v_mfma_f32_16x16x32_bf16 v[56:59], v[164:167], v[188:191], v[56:59]
	v_mfma_f32_16x16x32_bf16 v[44:47], v[148:151], v[196:199], v[44:47]
	v_mfma_f32_16x16x32_bf16 v[40:43], v[164:167], v[196:199], v[40:43]
	v_mfma_f32_16x16x32_bf16 v[28:31], v[148:151], v[204:207], v[28:31]
	v_mfma_f32_16x16x32_bf16 v[24:27], v[164:167], v[204:207], v[24:27]
	v_mfma_f32_16x16x32_bf16 v[12:15], v[148:151], v[212:215], v[12:15]
	v_mfma_f32_16x16x32_bf16 v[8:11], v[164:167], v[212:215], v[8:11]
	v_mfma_f32_16x16x32_bf16 v[60:63], v[152:155], v[192:195], v[60:63]
	v_mfma_f32_16x16x32_bf16 v[56:59], v[168:171], v[192:195], v[56:59]
	v_mfma_f32_16x16x32_bf16 v[44:47], v[152:155], v[200:203], v[44:47]
	v_mfma_f32_16x16x32_bf16 v[40:43], v[168:171], v[200:203], v[40:43]
	v_mfma_f32_16x16x32_bf16 v[28:31], v[152:155], v[208:211], v[28:31]
	v_mfma_f32_16x16x32_bf16 v[24:27], v[168:171], v[208:211], v[24:27]
	v_mfma_f32_16x16x32_bf16 v[12:15], v[152:155], v[216:219], v[12:15]
	v_mfma_f32_16x16x32_bf16 v[8:11], v[168:171], v[216:219], v[8:11]
	v_mfma_f32_16x16x32_bf16 v[52:55], v[172:175], v[188:191], v[52:55]
	v_mfma_f32_16x16x32_bf16 v[48:51], v[180:183], v[188:191], v[48:51]
	v_mfma_f32_16x16x32_bf16 v[36:39], v[172:175], v[196:199], v[36:39]
	v_mfma_f32_16x16x32_bf16 v[32:35], v[180:183], v[196:199], v[32:35]
	v_mfma_f32_16x16x32_bf16 v[20:23], v[172:175], v[204:207], v[20:23]
	v_mfma_f32_16x16x32_bf16 v[16:19], v[180:183], v[204:207], v[16:19]
	v_mfma_f32_16x16x32_bf16 v[4:7], v[172:175], v[212:215], v[4:7]
	v_mfma_f32_16x16x32_bf16 v[0:3], v[180:183], v[212:215], v[0:3]
	v_mfma_f32_16x16x32_bf16 v[52:55], v[176:179], v[192:195], v[52:55]
	v_mfma_f32_16x16x32_bf16 v[48:51], v[184:187], v[192:195], v[48:51]
	v_mfma_f32_16x16x32_bf16 v[36:39], v[176:179], v[200:203], v[36:39]
	v_mfma_f32_16x16x32_bf16 v[32:35], v[184:187], v[200:203], v[32:35]
	v_mfma_f32_16x16x32_bf16 v[20:23], v[176:179], v[208:211], v[20:23]
	v_mfma_f32_16x16x32_bf16 v[16:19], v[184:187], v[208:211], v[16:19]
	v_mfma_f32_16x16x32_bf16 v[4:7], v[176:179], v[216:219], v[4:7]
	v_mfma_f32_16x16x32_bf16 v[0:3], v[184:187], v[216:219], v[0:3]
	s_barrier
	s_setprio 0
	s_add_i32 s49, 0, 0x18000
	v_add_u32_e32 v136, s49, v158
	s_add_i32 s50, 0, 0x1c000
	ds_read_b128 v[148:151], v136
	ds_read_b128 v[152:155], v136 offset:1024
	ds_read_b128 v[164:167], v136 offset:2048
	ds_read_b128 v[168:171], v136 offset:3072
	v_add_u32_e32 v136, s50, v158
	ds_read_b128 v[172:175], v136
	ds_read_b128 v[176:179], v136 offset:1024
	ds_read_b128 v[180:183], v136 offset:2048
	ds_read_b128 v[184:187], v136 offset:3072
	s_add_u32 s26, s26, 0x100000
	s_addc_u32 s27, s27, 0
	s_mov_b32 m0, s34
	v_lshl_add_u64 v[228:229], s[26:27], 0, v[128:129]
	ds_read_b128 v[188:191], v162 offset:32768
	ds_read_b128 v[192:195], v162 offset:33792
	ds_read_b128 v[196:199], v162 offset:34816
	ds_read_b128 v[200:203], v162 offset:35840
	ds_read_b128 v[204:207], v162 offset:36864
	ds_read_b128 v[208:211], v162 offset:37888
	ds_read_b128 v[212:215], v162 offset:38912
	ds_read_b128 v[216:219], v162 offset:39936
	global_load_lds_dwordx4 v[228:229], off
	v_lshl_add_u64 v[228:229], s[26:27], 0, v[132:133]
	s_mov_b32 m0, s35
	s_nop 0
	global_load_lds_dwordx4 v[228:229], off
	s_waitcnt vmcnt(8)
	s_waitcnt lgkmcnt(0)
	s_setprio 1
	s_barrier
	v_mfma_f32_16x16x32_bf16 v[124:127], v[148:151], v[188:191], v[124:127]
	v_mfma_f32_16x16x32_bf16 v[120:123], v[164:167], v[188:191], v[120:123]
	v_mfma_f32_16x16x32_bf16 v[108:111], v[148:151], v[196:199], v[108:111]
	v_mfma_f32_16x16x32_bf16 v[104:107], v[164:167], v[196:199], v[104:107]
	v_mfma_f32_16x16x32_bf16 v[92:95], v[148:151], v[204:207], v[92:95]
	v_mfma_f32_16x16x32_bf16 v[88:91], v[164:167], v[204:207], v[88:91]
	v_mfma_f32_16x16x32_bf16 v[76:79], v[148:151], v[212:215], v[76:79]
	v_mfma_f32_16x16x32_bf16 v[72:75], v[164:167], v[212:215], v[72:75]
	v_mfma_f32_16x16x32_bf16 v[124:127], v[152:155], v[192:195], v[124:127]
	v_mfma_f32_16x16x32_bf16 v[120:123], v[168:171], v[192:195], v[120:123]
	v_mfma_f32_16x16x32_bf16 v[108:111], v[152:155], v[200:203], v[108:111]
	v_mfma_f32_16x16x32_bf16 v[104:107], v[168:171], v[200:203], v[104:107]
	v_mfma_f32_16x16x32_bf16 v[92:95], v[152:155], v[208:211], v[92:95]
	v_mfma_f32_16x16x32_bf16 v[88:91], v[168:171], v[208:211], v[88:91]
	v_mfma_f32_16x16x32_bf16 v[76:79], v[152:155], v[216:219], v[76:79]
	v_mfma_f32_16x16x32_bf16 v[72:75], v[168:171], v[216:219], v[72:75]
	v_mfma_f32_16x16x32_bf16 v[116:119], v[172:175], v[188:191], v[116:119]
	v_mfma_f32_16x16x32_bf16 v[112:115], v[180:183], v[188:191], v[112:115]
	v_mfma_f32_16x16x32_bf16 v[100:103], v[172:175], v[196:199], v[100:103]
	v_mfma_f32_16x16x32_bf16 v[96:99], v[180:183], v[196:199], v[96:99]
	v_mfma_f32_16x16x32_bf16 v[84:87], v[172:175], v[204:207], v[84:87]
	v_mfma_f32_16x16x32_bf16 v[80:83], v[180:183], v[204:207], v[80:83]
	v_mfma_f32_16x16x32_bf16 v[68:71], v[172:175], v[212:215], v[68:71]
	v_mfma_f32_16x16x32_bf16 v[64:67], v[180:183], v[212:215], v[64:67]
	v_mfma_f32_16x16x32_bf16 v[116:119], v[176:179], v[192:195], v[116:119]
	v_mfma_f32_16x16x32_bf16 v[112:115], v[184:187], v[192:195], v[112:115]
	v_mfma_f32_16x16x32_bf16 v[100:103], v[176:179], v[200:203], v[100:103]
	v_mfma_f32_16x16x32_bf16 v[96:99], v[184:187], v[200:203], v[96:99]
	v_mfma_f32_16x16x32_bf16 v[84:87], v[176:179], v[208:211], v[84:87]
	v_mfma_f32_16x16x32_bf16 v[80:83], v[184:187], v[208:211], v[80:83]
	v_mfma_f32_16x16x32_bf16 v[68:71], v[176:179], v[216:219], v[68:71]
	v_mfma_f32_16x16x32_bf16 v[64:67], v[184:187], v[216:219], v[64:67]
	s_barrier
; #define PG8_STAGE(bufoff, gbase, voff) do { _Pragma("unroll") for (int _i = 0; _i < 2; ++_i) \
;         __builtin_amdgcn_global_load_lds((const unsigned*)((const char*)(gbase) + (voff)[_i]), (PG8_LAS unsigned*)(lds + (bufoff) + ldsw + _i * 8192), 16, 0, 0); } while (0)
; #define PG8_LDA(dst, b, h) do { _Pragma("unroll") for (int m = 0; m < 4; ++m) _Pragma("unroll") for (int k = 0; k < 2; ++k) dst[m][k] = *(const PG8_LAS bf16x8*)(lds + PG8_SA(b, h) + aoff + m * 2048 + k * 1024); } while (0)
; #define PG8_WAIT_V(n) asm volatile("s_waitcnt vmcnt(" #n ")" ::: "memory")
; #define PG8_WAIT_L(n) asm volatile("s_waitcnt lgkmcnt(" #n ")" ::: "memory")
; #define PG8_BAR __builtin_amdgcn_s_barrier()
; template <class Epi, class Sched, bool ALIGN_EPI = false, bool SP2 = false>
; __device__ __forceinline__ void gemm_phase(PG8_LAS unsigned char* lds, const Gemm g, const Sched& S, const Epi& E, const int wid) {
;     ...
;         for (int t = 0; t < nt; t += 2) {
;             const bool last = (t == nt - 2);
;             const char* a1 = cA + (size_t)(t + 1) * kstep;
;             const char* a2 = last ? nA : cA + (size_t)(t + 2) * kstep; const char* b2 = last ? nB : cB + (size_t)(t + 2) * kstep;
;             const char* a3 = a2 + kstep; const char* b3 = b2 + kstep;
;             if (last && has_next) S.a_ready(nxt);
;             if constexpr (SP2) {
;             PG8_LDB(B0, 0, 0); PG8_LDB(B1, 0, 1); PG8_SCHED; PG8_LDA(At, 0, 0); PG8_STAGE(PG8_SA(1, 1), a1 + hstep, voffA);
;             PG8_WAIT_V(8); PG8_WAIT_L(0); PG8_BAR; PG8_MMA(0, 0, At, B0); PG8_MMA(0, 1, At, B1); PG8_BAR; PG8_SCHED;
;             PG8_LDA(At, 0, 1); PG8_STAGE(PG8_SB(0, 0), b2, voffB); PG8_STAGE(PG8_SB(0, 1), b2 + hstep, voffB); PG8_STAGE(PG8_SA(0, 0), a2, voffA);
;             PG8_WAIT_V(8); PG8_WAIT_L(0); PG8_BAR; PG8_MMA(1, 0, At, B0); PG8_MMA(1, 1, At, B1); PG8_BAR; PG8_SCHED;
;             PG8_LDB(B0, 1, 0); PG8_LDB(B1, 1, 1); PG8_SCHED; PG8_LDA(At, 1, 0); PG8_STAGE(PG8_SA(0, 1), a2 + hstep, voffA);
;             PG8_WAIT_V(8); PG8_WAIT_L(0); PG8_BAR; PG8_MMA(0, 0, At, B0); PG8_MMA(0, 1, At, B1); PG8_BAR; PG8_SCHED;
;             PG8_LDA(At, 1, 1); PG8_STAGE(PG8_SB(1, 0), b3, voffB); PG8_STAGE(PG8_SB(1, 1), b3 + hstep, voffB); PG8_STAGE(PG8_SA(1, 0), a3, voffA);
;             PG8_WAIT_V(8); PG8_WAIT_L(0); PG8_BAR; PG8_MMA(1, 0, At, B0); PG8_MMA(1, 1, At, B1); PG8_BAR; PG8_SCHED;
	s_setprio 0
	s_add_i32 s26, s49, s29
	v_lshl_add_u64 v[220:221], v[220:221], 0, s[6:7]
	s_mov_b32 m0, s26
	ds_read_b128 v[188:191], v162 offset:49152
	ds_read_b128 v[192:195], v162 offset:50176
	ds_read_b128 v[196:199], v162 offset:51200
	ds_read_b128 v[200:203], v162 offset:52224
	ds_read_b128 v[204:207], v162 offset:53248
	ds_read_b128 v[208:211], v162 offset:54272
	ds_read_b128 v[212:215], v162 offset:55296
	ds_read_b128 v[216:219], v162 offset:56320
	global_load_lds_dwordx4 v[220:221], off
	s_add_i32 m0, s26, 0x2000
	s_add_u32 s24, s24, 0x100080
	v_lshl_add_u64 v[220:221], v[222:223], 0, s[6:7]
	s_addc_u32 s25, s25, 0
	s_add_i32 s26, s50, s29
	global_load_lds_dwordx4 v[220:221], off
	v_lshl_add_u64 v[220:221], s[24:25], 0, v[130:131]
	s_mov_b32 m0, s26
	s_nop 0
	global_load_lds_dwordx4 v[220:221], off
	v_lshl_add_u64 v[220:221], s[24:25], 0, v[134:135]
	s_add_i32 m0, s26, 0x2000
	s_nop 0
	global_load_lds_dwordx4 v[220:221], off
	v_lshl_add_u64 v[220:221], v[224:225], 0, s[6:7]
	s_mov_b32 m0, s37
	s_nop 0
	global_load_lds_dwordx4 v[220:221], off
	v_lshl_add_u64 v[220:221], v[226:227], 0, s[6:7]
	s_mov_b32 m0, s38
	s_nop 0
	global_load_lds_dwordx4 v[220:221], off
	s_waitcnt vmcnt(8)
	s_waitcnt lgkmcnt(0)
	s_setprio 1
	s_barrier
	v_mfma_f32_16x16x32_bf16 v[60:63], v[148:151], v[188:191], v[60:63]
	v_mfma_f32_16x16x32_bf16 v[56:59], v[164:167], v[188:191], v[56:59]
	v_mfma_f32_16x16x32_bf16 v[44:47], v[148:151], v[196:199], v[44:47]
	v_mfma_f32_16x16x32_bf16 v[40:43], v[164:167], v[196:199], v[40:43]
	v_mfma_f32_16x16x32_bf16 v[28:31], v[148:151], v[204:207], v[28:31]
	v_mfma_f32_16x16x32_bf16 v[24:27], v[164:167], v[204:207], v[24:27]
	v_mfma_f32_16x16x32_bf16 v[12:15], v[148:151], v[212:215], v[12:15]
	v_mfma_f32_16x16x32_bf16 v[8:11], v[164:167], v[212:215], v[8:11]
	v_mfma_f32_16x16x32_bf16 v[60:63], v[152:155], v[192:195], v[60:63]
	v_mfma_f32_16x16x32_bf16 v[56:59], v[168:171], v[192:195], v[56:59]
	v_mfma_f32_16x16x32_bf16 v[44:47], v[152:155], v[200:203], v[44:47]
	v_mfma_f32_16x16x32_bf16 v[40:43], v[168:171], v[200:203], v[40:43]
	v_mfma_f32_16x16x32_bf16 v[28:31], v[152:155], v[208:211], v[28:31]
	v_mfma_f32_16x16x32_bf16 v[24:27], v[168:171], v[208:211], v[24:27]
	v_mfma_f32_16x16x32_bf16 v[12:15], v[152:155], v[216:219], v[12:15]
	v_mfma_f32_16x16x32_bf16 v[8:11], v[168:171], v[216:219], v[8:11]
	v_mfma_f32_16x16x32_bf16 v[52:55], v[172:175], v[188:191], v[52:55]
	v_mfma_f32_16x16x32_bf16 v[48:51], v[180:183], v[188:191], v[48:51]
	v_mfma_f32_16x16x32_bf16 v[36:39], v[172:175], v[196:199], v[36:39]
	v_mfma_f32_16x16x32_bf16 v[32:35], v[180:183], v[196:199], v[32:35]
	v_mfma_f32_16x16x32_bf16 v[20:23], v[172:175], v[204:207], v[20:23]
	v_mfma_f32_16x16x32_bf16 v[16:19], v[180:183], v[204:207], v[16:19]
	v_mfma_f32_16x16x32_bf16 v[4:7], v[172:175], v[212:215], v[4:7]
	v_mfma_f32_16x16x32_bf16 v[0:3], v[180:183], v[212:215], v[0:3]
	v_mfma_f32_16x16x32_bf16 v[52:55], v[176:179], v[192:195], v[52:55]
	v_mfma_f32_16x16x32_bf16 v[48:51], v[184:187], v[192:195], v[48:51]
	v_mfma_f32_16x16x32_bf16 v[36:39], v[176:179], v[200:203], v[36:39]
	v_mfma_f32_16x16x32_bf16 v[32:35], v[184:187], v[200:203], v[32:35]
	v_mfma_f32_16x16x32_bf16 v[20:23], v[176:179], v[208:211], v[20:23]
	v_mfma_f32_16x16x32_bf16 v[16:19], v[184:187], v[208:211], v[16:19]
	v_mfma_f32_16x16x32_bf16 v[4:7], v[176:179], v[216:219], v[4:7]
	v_mfma_f32_16x16x32_bf16 v[0:3], v[184:187], v[216:219], v[0:3]
	s_barrier
	s_setprio 0
	s_add_i32 s48, s48, 2
	s_add_u32 s22, s22, 0x100
	s_addc_u32 s23, s23, 0
	s_add_u32 s46, s46, 0x100
	s_addc_u32 s47, s47, 0
	s_cmp_gt_u32 s48, 61
	s_cbranch_scc0 .LBB0_249
	s_and_b64 vcc, exec, s[8:9]
	s_cbranch_vccnz .LBB0_254
	v_lshl_add_u32 v148, s20, 8, v157
	s_cmp_gt_i32 s44, 39
	s_mov_b64 s[20:21], -1
	s_cbranch_scc1 .LBB0_255

; #define PG8_STAGE(bufoff, gbase, voff) do { _Pragma("unroll") for (int _i = 0; _i < 2; ++_i) \
;         __builtin_amdgcn_global_load_lds((const unsigned*)((const char*)(gbase) + (voff)[_i]), (PG8_LAS unsigned*)(lds + (bufoff) + ldsw + _i * 8192), 16, 0, 0); } while (0)
; #define PG8_LDA(dst, b, h) do { _Pragma("unroll") for (int m = 0; m < 4; ++m) _Pragma("unroll") for (int k = 0; k < 2; ++k) dst[m][k] = *(const PG8_LAS bf16x8*)(lds + PG8_SA(b, h) + aoff + m * 2048 + k * 1024); } while (0)
; #define PG8_LDB(dst, b, h) do { _Pragma("unroll") for (int n = 0; n < 2; ++n) _Pragma("unroll") for (int k = 0; k < 2; ++k) dst[n][k] = *(const PG8_LAS bf16x8*)(lds + PG8_SB(b, h) + boff + n * 2048 + k * 1024); } while (0)
; #define PG8_MMA(ai, bj, At, Bt) do { __builtin_amdgcn_s_setprio(1); _Pragma("unroll") for (int m = 0; m < 4; ++m) _Pragma("unroll") for (int n = 0; n < 2; ++n) _Pragma("unroll") for (int k = 0; k < 2; ++k) \
;         acc[ai][bj][m][n] = __builtin_amdgcn_mfma_f32_16x16x32_bf16(Bt[n][k], At[m][k], acc[ai][bj][m][n], 0, 0, 0); __builtin_amdgcn_s_setprio(0); } while (0)
; #define PG8_BAR __builtin_amdgcn_s_barrier()
; template <class Epi, class Sched, bool ALIGN_EPI = false, bool SP2 = false>
; __device__ __forceinline__ void gemm_phase(PG8_LAS unsigned char* lds, const Gemm g, const Sched& S, const Epi& E, const int wid) {
;     ...
;             PG8_LDB(B0, 0, 0); PG8_LDB(B1, 0, 1); PG8_SCHED; PG8_LDA(At, 0, 0); PG8_STAGE(PG8_SA(1, 1), a1 + hstep, voffA);
;             PG8_WAIT_V(8); PG8_WAIT_L(0); PG8_BAR; PG8_MMA(0, 0, At, B0); PG8_MMA(0, 1, At, B1); PG8_BAR; PG8_SCHED;
;             PG8_LDA(At, 0, 1); PG8_STAGE(PG8_SB(0, 0), b2, voffB); PG8_STAGE(PG8_SB(0, 1), b2 + hstep, voffB); PG8_STAGE(PG8_SA(0, 0), a2, voffA);
;             PG8_WAIT_V(8); PG8_WAIT_L(0); PG8_BAR; PG8_MMA(1, 0, At, B0); PG8_MMA(1, 1, At, B1); PG8_BAR; PG8_SCHED;
;             PG8_LDB(B0, 1, 0); PG8_LDB(B1, 1, 1); PG8_SCHED; PG8_LDA(At, 1, 0); PG8_STAGE(PG8_SA(0, 1), a2 + hstep, voffA);
;             PG8_WAIT_V(8); PG8_WAIT_L(0); PG8_BAR; PG8_MMA(0, 0, At, B0); PG8_MMA(0, 1, At, B1); PG8_BAR; PG8_SCHED;
;             PG8_LDA(At, 1, 1); PG8_STAGE(PG8_SB(1, 0), b3, voffB); PG8_STAGE(PG8_SB(1, 1), b3 + hstep, voffB); PG8_STAGE(PG8_SA(1, 0), a3, voffA);
;             PG8_WAIT_V(8); PG8_WAIT_L(0); PG8_BAR; PG8_MMA(1, 0, At, B0); PG8_MMA(1, 1, At, B1); PG8_BAR; PG8_SCHED;
.LBB0_843:
	ds_read_b128 v[128:131], v181
	ds_read_b128 v[132:135], v181 offset:1024
	ds_read_b128 v[136:139], v181 offset:2048
	ds_read_b128 v[140:143], v181 offset:3072
	ds_read_b128 v[166:169], v182
	ds_read_b128 v[170:173], v182 offset:1024
	ds_read_b128 v[184:187], v182 offset:2048
	ds_read_b128 v[188:191], v182 offset:3072
	s_add_i32 s58, s28, 2
	s_add_u32 s29, s26, 0xfff00080
	s_addc_u32 s30, s27, -1
	s_cmp_eq_u32 s25, s28
	s_cselect_b32 s28, s23, s56
	s_cselect_b32 s31, s11, s30
	s_cselect_b32 s30, s15, s29
	s_cselect_b32 s29, s13, s57
	v_lshl_add_u64 v[174:175], s[26:27], 0, v[160:161]
	s_add_i32 m0, s37, 0xc000
	ds_read_b128 v[192:195], v183
	ds_read_b128 v[196:199], v183 offset:1024
	ds_read_b128 v[200:203], v183 offset:2048
	ds_read_b128 v[204:207], v183 offset:3072
	ds_read_b128 v[208:211], v183 offset:4096
	ds_read_b128 v[212:215], v183 offset:5120
	ds_read_b128 v[216:219], v183 offset:6144
	ds_read_b128 v[220:223], v183 offset:7168
	global_load_lds_dwordx4 v[174:175], off
	v_lshl_add_u64 v[174:175], s[26:27], 0, v[162:163]
	s_add_i32 m0, s37, 0xe000
	s_nop 0
	global_load_lds_dwordx4 v[174:175], off
	s_waitcnt vmcnt(8)
	s_waitcnt lgkmcnt(0)
	s_setprio 1
	s_barrier
	v_mfma_f32_16x16x32_bf16 v[60:63], v[128:131], v[192:195], v[60:63]
	v_mfma_f32_16x16x32_bf16 v[56:59], v[136:139], v[192:195], v[56:59]
	v_mfma_f32_16x16x32_bf16 v[44:47], v[128:131], v[200:203], v[44:47]
	v_mfma_f32_16x16x32_bf16 v[40:43], v[136:139], v[200:203], v[40:43]
	v_mfma_f32_16x16x32_bf16 v[28:31], v[128:131], v[208:211], v[28:31]
	v_mfma_f32_16x16x32_bf16 v[24:27], v[136:139], v[208:211], v[24:27]
	v_mfma_f32_16x16x32_bf16 v[12:15], v[128:131], v[216:219], v[12:15]
	v_mfma_f32_16x16x32_bf16 v[8:11], v[136:139], v[216:219], v[8:11]
	v_mfma_f32_16x16x32_bf16 v[60:63], v[132:135], v[196:199], v[60:63]
	v_mfma_f32_16x16x32_bf16 v[56:59], v[140:143], v[196:199], v[56:59]
	v_mfma_f32_16x16x32_bf16 v[44:47], v[132:135], v[204:207], v[44:47]
	v_mfma_f32_16x16x32_bf16 v[40:43], v[140:143], v[204:207], v[40:43]
	v_mfma_f32_16x16x32_bf16 v[28:31], v[132:135], v[212:215], v[28:31]
	v_mfma_f32_16x16x32_bf16 v[24:27], v[140:143], v[212:215], v[24:27]
	v_mfma_f32_16x16x32_bf16 v[12:15], v[132:135], v[220:223], v[12:15]
	v_mfma_f32_16x16x32_bf16 v[8:11], v[140:143], v[220:223], v[8:11]
	v_mfma_f32_16x16x32_bf16 v[52:55], v[166:169], v[192:195], v[52:55]
	v_mfma_f32_16x16x32_bf16 v[48:51], v[184:187], v[192:195], v[48:51]
	v_mfma_f32_16x16x32_bf16 v[36:39], v[166:169], v[200:203], v[36:39]
	v_mfma_f32_16x16x32_bf16 v[32:35], v[184:187], v[200:203], v[32:35]
	v_mfma_f32_16x16x32_bf16 v[20:23], v[166:169], v[208:211], v[20:23]
	v_mfma_f32_16x16x32_bf16 v[16:19], v[184:187], v[208:211], v[16:19]
	v_mfma_f32_16x16x32_bf16 v[4:7], v[166:169], v[216:219], v[4:7]
	v_mfma_f32_16x16x32_bf16 v[0:3], v[184:187], v[216:219], v[0:3]
	v_mfma_f32_16x16x32_bf16 v[52:55], v[170:173], v[196:199], v[52:55]
	v_mfma_f32_16x16x32_bf16 v[48:51], v[188:191], v[196:199], v[48:51]
	v_mfma_f32_16x16x32_bf16 v[36:39], v[170:173], v[204:207], v[36:39]
	v_mfma_f32_16x16x32_bf16 v[32:35], v[188:191], v[204:207], v[32:35]
	v_mfma_f32_16x16x32_bf16 v[20:23], v[170:173], v[212:215], v[20:23]
	v_mfma_f32_16x16x32_bf16 v[16:19], v[188:191], v[212:215], v[16:19]
	v_mfma_f32_16x16x32_bf16 v[4:7], v[170:173], v[220:223], v[4:7]
	v_mfma_f32_16x16x32_bf16 v[0:3], v[188:191], v[220:223], v[0:3]
	s_barrier
	s_setprio 0
	s_add_i32 s59, s48, s36
	v_lshl_add_u64 v[174:175], s[28:29], 0, v[146:147]
	s_mov_b32 m0, s59
	ds_read_b128 v[192:195], v183 offset:16384
	ds_read_b128 v[196:199], v183 offset:17408
	ds_read_b128 v[200:203], v183 offset:18432
	ds_read_b128 v[204:207], v183 offset:19456
	ds_read_b128 v[208:211], v183 offset:20480
	ds_read_b128 v[212:215], v183 offset:21504
	ds_read_b128 v[216:219], v183 offset:22528
	ds_read_b128 v[220:223], v183 offset:23552
	global_load_lds_dwordx4 v[174:175], off
	s_add_i32 m0, s59, 0x2000
	s_add_u32 s60, s28, 0x100000
	v_lshl_add_u64 v[224:225], s[28:29], 0, v[150:151]
	s_addc_u32 s61, s29, 0
	s_add_i32 s59, s49, s36
	global_load_lds_dwordx4 v[224:225], off
	v_lshl_add_u64 v[226:227], s[60:61], 0, v[146:147]
	s_mov_b32 m0, s59
	v_lshl_add_u64 v[228:229], s[30:31], 0, v[148:149]
	global_load_lds_dwordx4 v[226:227], off
	v_lshl_add_u64 v[226:227], s[60:61], 0, v[150:151]
	s_add_i32 m0, s59, 0x2000
	s_nop 0
	global_load_lds_dwordx4 v[226:227], off
	v_lshl_add_u64 v[226:227], s[30:31], 0, v[144:145]
	s_mov_b32 m0, s37
	s_nop 0
	global_load_lds_dwordx4 v[226:227], off
	s_mov_b32 m0, s38
	s_nop 0
	global_load_lds_dwordx4 v[228:229], off
	s_waitcnt vmcnt(8)
	s_waitcnt lgkmcnt(0)
	s_setprio 1
	s_barrier
; #define PG8_STAGE(bufoff, gbase, voff) do { _Pragma("unroll") for (int _i = 0; _i < 2; ++_i) \
;         __builtin_amdgcn_global_load_lds((const unsigned*)((const char*)(gbase) + (voff)[_i]), (PG8_LAS unsigned*)(lds + (bufoff) + ldsw + _i * 8192), 16, 0, 0); } while (0)
; #define PG8_LDA(dst, b, h) do { _Pragma("unroll") for (int m = 0; m < 4; ++m) _Pragma("unroll") for (int k = 0; k < 2; ++k) dst[m][k] = *(const PG8_LAS bf16x8*)(lds + PG8_SA(b, h) + aoff + m * 2048 + k * 1024); } while (0)
; #define PG8_LDB(dst, b, h) do { _Pragma("unroll") for (int n = 0; n < 2; ++n) _Pragma("unroll") for (int k = 0; k < 2; ++k) dst[n][k] = *(const PG8_LAS bf16x8*)(lds + PG8_SB(b, h) + boff + n * 2048 + k * 1024); } while (0)
; #define PG8_MMA(ai, bj, At, Bt) do { __builtin_amdgcn_s_setprio(1); _Pragma("unroll") for (int m = 0; m < 4; ++m) _Pragma("unroll") for (int n = 0; n < 2; ++n) _Pragma("unroll") for (int k = 0; k < 2; ++k) \
;         acc[ai][bj][m][n] = __builtin_amdgcn_mfma_f32_16x16x32_bf16(Bt[n][k], At[m][k], acc[ai][bj][m][n], 0, 0, 0); __builtin_amdgcn_s_setprio(0); } while (0)
; #define PG8_BAR __builtin_amdgcn_s_barrier()
; template <class Epi, class Sched, bool ALIGN_EPI = false, bool SP2 = false>
; __device__ __forceinline__ void gemm_phase(PG8_LAS unsigned char* lds, const Gemm g, const Sched& S, const Epi& E, const int wid) {
;     ...
;             PG8_LDB(B0, 0, 0); PG8_LDB(B1, 0, 1); PG8_SCHED; PG8_LDA(At, 0, 0); PG8_STAGE(PG8_SA(1, 1), a1 + hstep, voffA);
;             PG8_WAIT_V(8); PG8_WAIT_L(0); PG8_BAR; PG8_MMA(0, 0, At, B0); PG8_MMA(0, 1, At, B1); PG8_BAR; PG8_SCHED;
;             PG8_LDA(At, 0, 1); PG8_STAGE(PG8_SB(0, 0), b2, voffB); PG8_STAGE(PG8_SB(0, 1), b2 + hstep, voffB); PG8_STAGE(PG8_SA(0, 0), a2, voffA);
;             PG8_WAIT_V(8); PG8_WAIT_L(0); PG8_BAR; PG8_MMA(1, 0, At, B0); PG8_MMA(1, 1, At, B1); PG8_BAR; PG8_SCHED;
;             PG8_LDB(B0, 1, 0); PG8_LDB(B1, 1, 1); PG8_SCHED; PG8_LDA(At, 1, 0); PG8_STAGE(PG8_SA(0, 1), a2 + hstep, voffA);
;             PG8_WAIT_V(8); PG8_WAIT_L(0); PG8_BAR; PG8_MMA(0, 0, At, B0); PG8_MMA(0, 1, At, B1); PG8_BAR; PG8_SCHED;
;             PG8_LDA(At, 1, 1); PG8_STAGE(PG8_SB(1, 0), b3, voffB); PG8_STAGE(PG8_SB(1, 1), b3 + hstep, voffB); PG8_STAGE(PG8_SA(1, 0), a3, voffA);
;             PG8_WAIT_V(8); PG8_WAIT_L(0); PG8_BAR; PG8_MMA(1, 0, At, B0); PG8_MMA(1, 1, At, B1); PG8_BAR; PG8_SCHED;
	v_mfma_f32_16x16x32_bf16 v[124:127], v[128:131], v[192:195], v[124:127]
	v_mfma_f32_16x16x32_bf16 v[120:123], v[136:139], v[192:195], v[120:123]
	v_mfma_f32_16x16x32_bf16 v[108:111], v[128:131], v[200:203], v[108:111]
	v_mfma_f32_16x16x32_bf16 v[104:107], v[136:139], v[200:203], v[104:107]
	v_mfma_f32_16x16x32_bf16 v[92:95], v[128:131], v[208:211], v[92:95]
	v_mfma_f32_16x16x32_bf16 v[88:91], v[136:139], v[208:211], v[88:91]
	v_mfma_f32_16x16x32_bf16 v[76:79], v[128:131], v[216:219], v[76:79]
	v_mfma_f32_16x16x32_bf16 v[72:75], v[136:139], v[216:219], v[72:75]
	v_mfma_f32_16x16x32_bf16 v[124:127], v[132:135], v[196:199], v[124:127]
	v_mfma_f32_16x16x32_bf16 v[120:123], v[140:143], v[196:199], v[120:123]
	v_mfma_f32_16x16x32_bf16 v[108:111], v[132:135], v[204:207], v[108:111]
	v_mfma_f32_16x16x32_bf16 v[104:107], v[140:143], v[204:207], v[104:107]
	v_mfma_f32_16x16x32_bf16 v[92:95], v[132:135], v[212:215], v[92:95]
	v_mfma_f32_16x16x32_bf16 v[88:91], v[140:143], v[212:215], v[88:91]
	v_mfma_f32_16x16x32_bf16 v[76:79], v[132:135], v[220:223], v[76:79]
	v_mfma_f32_16x16x32_bf16 v[72:75], v[140:143], v[220:223], v[72:75]
	v_mfma_f32_16x16x32_bf16 v[116:119], v[166:169], v[192:195], v[116:119]
	v_mfma_f32_16x16x32_bf16 v[112:115], v[184:187], v[192:195], v[112:115]
	v_mfma_f32_16x16x32_bf16 v[100:103], v[166:169], v[200:203], v[100:103]
	v_mfma_f32_16x16x32_bf16 v[96:99], v[184:187], v[200:203], v[96:99]
	v_mfma_f32_16x16x32_bf16 v[84:87], v[166:169], v[208:211], v[84:87]
	v_mfma_f32_16x16x32_bf16 v[80:83], v[184:187], v[208:211], v[80:83]
	v_mfma_f32_16x16x32_bf16 v[68:71], v[166:169], v[216:219], v[68:71]
	v_mfma_f32_16x16x32_bf16 v[64:67], v[184:187], v[216:219], v[64:67]
	v_mfma_f32_16x16x32_bf16 v[116:119], v[170:173], v[196:199], v[116:119]
	v_mfma_f32_16x16x32_bf16 v[112:115], v[188:191], v[196:199], v[112:115]
	v_mfma_f32_16x16x32_bf16 v[100:103], v[170:173], v[204:207], v[100:103]
	v_mfma_f32_16x16x32_bf16 v[96:99], v[188:191], v[204:207], v[96:99]
	v_mfma_f32_16x16x32_bf16 v[84:87], v[170:173], v[212:215], v[84:87]
	v_mfma_f32_16x16x32_bf16 v[80:83], v[188:191], v[212:215], v[80:83]
	v_mfma_f32_16x16x32_bf16 v[68:71], v[170:173], v[220:223], v[68:71]
	v_mfma_f32_16x16x32_bf16 v[64:67], v[188:191], v[220:223], v[64:67]
	s_barrier
	s_setprio 0
	s_add_i32 s59, 0, 0x18000
	s_add_i32 s60, 0, 0x1c000
	v_add_u32_e32 v140, s59, v179
	v_add_u32_e32 v188, s60, v179
	ds_read_b128 v[128:131], v140
	ds_read_b128 v[132:135], v140 offset:1024
	ds_read_b128 v[136:139], v140 offset:2048
	ds_read_b128 v[140:143], v140 offset:3072
	ds_read_b128 v[166:169], v188
	ds_read_b128 v[170:173], v188 offset:1024
	ds_read_b128 v[184:187], v188 offset:2048
	ds_read_b128 v[188:191], v188 offset:3072
	s_add_u32 s30, s30, 0x100000
	s_addc_u32 s31, s31, 0
	s_mov_b32 m0, s39
	v_lshl_add_u64 v[230:231], s[30:31], 0, v[144:145]
	ds_read_b128 v[192:195], v183 offset:32768
	ds_read_b128 v[196:199], v183 offset:33792
	ds_read_b128 v[200:203], v183 offset:34816
	ds_read_b128 v[204:207], v183 offset:35840
	ds_read_b128 v[208:211], v183 offset:36864
	ds_read_b128 v[212:215], v183 offset:37888
	ds_read_b128 v[216:219], v183 offset:38912
	ds_read_b128 v[220:223], v183 offset:39936
	global_load_lds_dwordx4 v[230:231], off
	v_lshl_add_u64 v[230:231], s[30:31], 0, v[148:149]
	s_mov_b32 m0, s40
	s_nop 0
	global_load_lds_dwordx4 v[230:231], off
	s_waitcnt vmcnt(8)
	s_waitcnt lgkmcnt(0)
	s_setprio 1
	s_barrier
	v_mfma_f32_16x16x32_bf16 v[60:63], v[128:131], v[192:195], v[60:63]
	v_mfma_f32_16x16x32_bf16 v[56:59], v[136:139], v[192:195], v[56:59]
	v_mfma_f32_16x16x32_bf16 v[44:47], v[128:131], v[200:203], v[44:47]
	v_mfma_f32_16x16x32_bf16 v[40:43], v[136:139], v[200:203], v[40:43]
	v_mfma_f32_16x16x32_bf16 v[28:31], v[128:131], v[208:211], v[28:31]
	v_mfma_f32_16x16x32_bf16 v[24:27], v[136:139], v[208:211], v[24:27]
	v_mfma_f32_16x16x32_bf16 v[12:15], v[128:131], v[216:219], v[12:15]
	v_mfma_f32_16x16x32_bf16 v[8:11], v[136:139], v[216:219], v[8:11]
	v_mfma_f32_16x16x32_bf16 v[60:63], v[132:135], v[196:199], v[60:63]
	v_mfma_f32_16x16x32_bf16 v[56:59], v[140:143], v[196:199], v[56:59]
	v_mfma_f32_16x16x32_bf16 v[44:47], v[132:135], v[204:207], v[44:47]
	v_mfma_f32_16x16x32_bf16 v[40:43], v[140:143], v[204:207], v[40:43]
	v_mfma_f32_16x16x32_bf16 v[28:31], v[132:135], v[212:215], v[28:31]
	v_mfma_f32_16x16x32_bf16 v[24:27], v[140:143], v[212:215], v[24:27]
	v_mfma_f32_16x16x32_bf16 v[12:15], v[132:135], v[220:223], v[12:15]
	v_mfma_f32_16x16x32_bf16 v[8:11], v[140:143], v[220:223], v[8:11]
	v_mfma_f32_16x16x32_bf16 v[52:55], v[166:169], v[192:195], v[52:55]
	v_mfma_f32_16x16x32_bf16 v[48:51], v[184:187], v[192:195], v[48:51]
	v_mfma_f32_16x16x32_bf16 v[36:39], v[166:169], v[200:203], v[36:39]
	v_mfma_f32_16x16x32_bf16 v[32:35], v[184:187], v[200:203], v[32:35]
	v_mfma_f32_16x16x32_bf16 v[20:23], v[166:169], v[208:211], v[20:23]
	v_mfma_f32_16x16x32_bf16 v[16:19], v[184:187], v[208:211], v[16:19]
	v_mfma_f32_16x16x32_bf16 v[4:7], v[166:169], v[216:219], v[4:7]
	v_mfma_f32_16x16x32_bf16 v[0:3], v[184:187], v[216:219], v[0:3]
	v_mfma_f32_16x16x32_bf16 v[52:55], v[170:173], v[196:199], v[52:55]
	v_mfma_f32_16x16x32_bf16 v[48:51], v[188:191], v[196:199], v[48:51]
	v_mfma_f32_16x16x32_bf16 v[36:39], v[170:173], v[204:207], v[36:39]
	v_mfma_f32_16x16x32_bf16 v[32:35], v[188:191], v[204:207], v[32:35]
	v_mfma_f32_16x16x32_bf16 v[20:23], v[170:173], v[212:215], v[20:23]
	v_mfma_f32_16x16x32_bf16 v[16:19], v[188:191], v[212:215], v[16:19]
	v_mfma_f32_16x16x32_bf16 v[4:7], v[170:173], v[220:223], v[4:7]
	v_mfma_f32_16x16x32_bf16 v[0:3], v[188:191], v[220:223], v[0:3]
	s_barrier
; #define PG8_STAGE(bufoff, gbase, voff) do { _Pragma("unroll") for (int _i = 0; _i < 2; ++_i) \
;         __builtin_amdgcn_global_load_lds((const unsigned*)((const char*)(gbase) + (voff)[_i]), (PG8_LAS unsigned*)(lds + (bufoff) + ldsw + _i * 8192), 16, 0, 0); } while (0)
; #define PG8_LDA(dst, b, h) do { _Pragma("unroll") for (int m = 0; m < 4; ++m) _Pragma("unroll") for (int k = 0; k < 2; ++k) dst[m][k] = *(const PG8_LAS bf16x8*)(lds + PG8_SA(b, h) + aoff + m * 2048 + k * 1024); } while (0)
; #define PG8_WAIT_V(n) asm volatile("s_waitcnt vmcnt(" #n ")" ::: "memory")
; #define PG8_WAIT_L(n) asm volatile("s_waitcnt lgkmcnt(" #n ")" ::: "memory")
; #define PG8_BAR __builtin_amdgcn_s_barrier()
; template <class Epi, class Sched, bool ALIGN_EPI = false, bool SP2 = false>
; __device__ __forceinline__ void gemm_phase(PG8_LAS unsigned char* lds, const Gemm g, const Sched& S, const Epi& E, const int wid) {
;     ...
;         for (int t = 0; t < nt; t += 2) {
;             const bool last = (t == nt - 2);
;             const char* a1 = cA + (size_t)(t + 1) * kstep;
;             const char* a2 = last ? nA : cA + (size_t)(t + 2) * kstep; const char* b2 = last ? nB : cB + (size_t)(t + 2) * kstep;
;             const char* a3 = a2 + kstep; const char* b3 = b2 + kstep;
;             if (last && has_next) S.a_ready(nxt);
;             if constexpr (SP2) {
;             PG8_LDB(B0, 0, 0); PG8_LDB(B1, 0, 1); PG8_SCHED; PG8_LDA(At, 0, 0); PG8_STAGE(PG8_SA(1, 1), a1 + hstep, voffA);
;             PG8_WAIT_V(8); PG8_WAIT_L(0); PG8_BAR; PG8_MMA(0, 0, At, B0); PG8_MMA(0, 1, At, B1); PG8_BAR; PG8_SCHED;
;             PG8_LDA(At, 0, 1); PG8_STAGE(PG8_SB(0, 0), b2, voffB); PG8_STAGE(PG8_SB(0, 1), b2 + hstep, voffB); PG8_STAGE(PG8_SA(0, 0), a2, voffA);
;             PG8_WAIT_V(8); PG8_WAIT_L(0); PG8_BAR; PG8_MMA(1, 0, At, B0); PG8_MMA(1, 1, At, B1); PG8_BAR; PG8_SCHED;
;             PG8_LDB(B0, 1, 0); PG8_LDB(B1, 1, 1); PG8_SCHED; PG8_LDA(At, 1, 0); PG8_STAGE(PG8_SA(0, 1), a2 + hstep, voffA);
;             PG8_WAIT_V(8); PG8_WAIT_L(0); PG8_BAR; PG8_MMA(0, 0, At, B0); PG8_MMA(0, 1, At, B1); PG8_BAR; PG8_SCHED;
;             PG8_LDA(At, 1, 1); PG8_STAGE(PG8_SB(1, 0), b3, voffB); PG8_STAGE(PG8_SB(1, 1), b3 + hstep, voffB); PG8_STAGE(PG8_SA(1, 0), a3, voffA);
;             PG8_WAIT_V(8); PG8_WAIT_L(0); PG8_BAR; PG8_MMA(1, 0, At, B0); PG8_MMA(1, 1, At, B1); PG8_BAR; PG8_SCHED;
	s_setprio 0
	s_add_i32 s30, s59, s36
	v_lshl_add_u64 v[174:175], v[174:175], 0, s[6:7]
	s_mov_b32 m0, s30
	ds_read_b128 v[192:195], v183 offset:49152
	ds_read_b128 v[196:199], v183 offset:50176
	ds_read_b128 v[200:203], v183 offset:51200
	ds_read_b128 v[204:207], v183 offset:52224
	ds_read_b128 v[208:211], v183 offset:53248
	ds_read_b128 v[212:215], v183 offset:54272
	ds_read_b128 v[216:219], v183 offset:55296
	ds_read_b128 v[220:223], v183 offset:56320
	global_load_lds_dwordx4 v[174:175], off
	s_add_i32 m0, s30, 0x2000
	s_add_u32 s28, s28, 0x100080
	v_lshl_add_u64 v[174:175], v[224:225], 0, s[6:7]
	s_addc_u32 s29, s29, 0
	s_add_i32 s30, s60, s36
	global_load_lds_dwordx4 v[174:175], off
	v_lshl_add_u64 v[174:175], s[28:29], 0, v[146:147]
	s_mov_b32 m0, s30
	s_nop 0
	global_load_lds_dwordx4 v[174:175], off
	v_lshl_add_u64 v[174:175], s[28:29], 0, v[150:151]
	s_add_i32 m0, s30, 0x2000
	s_nop 0
	global_load_lds_dwordx4 v[174:175], off
	v_lshl_add_u64 v[174:175], v[226:227], 0, s[6:7]
	s_mov_b32 m0, s42
	s_nop 0
	global_load_lds_dwordx4 v[174:175], off
	v_lshl_add_u64 v[174:175], v[228:229], 0, s[6:7]
	s_mov_b32 m0, s43
	s_nop 0
	global_load_lds_dwordx4 v[174:175], off
	s_waitcnt vmcnt(8)
	s_waitcnt lgkmcnt(0)
	s_setprio 1
	s_barrier
	v_mfma_f32_16x16x32_bf16 v[124:127], v[128:131], v[192:195], v[124:127]
	v_mfma_f32_16x16x32_bf16 v[120:123], v[136:139], v[192:195], v[120:123]
	v_mfma_f32_16x16x32_bf16 v[108:111], v[128:131], v[200:203], v[108:111]
	v_mfma_f32_16x16x32_bf16 v[104:107], v[136:139], v[200:203], v[104:107]
	v_mfma_f32_16x16x32_bf16 v[92:95], v[128:131], v[208:211], v[92:95]
	v_mfma_f32_16x16x32_bf16 v[88:91], v[136:139], v[208:211], v[88:91]
	v_mfma_f32_16x16x32_bf16 v[76:79], v[128:131], v[216:219], v[76:79]
	v_mfma_f32_16x16x32_bf16 v[72:75], v[136:139], v[216:219], v[72:75]
	v_mfma_f32_16x16x32_bf16 v[124:127], v[132:135], v[196:199], v[124:127]
	v_mfma_f32_16x16x32_bf16 v[120:123], v[140:143], v[196:199], v[120:123]
	v_mfma_f32_16x16x32_bf16 v[108:111], v[132:135], v[204:207], v[108:111]
	v_mfma_f32_16x16x32_bf16 v[104:107], v[140:143], v[204:207], v[104:107]
	v_mfma_f32_16x16x32_bf16 v[92:95], v[132:135], v[212:215], v[92:95]
	v_mfma_f32_16x16x32_bf16 v[88:91], v[140:143], v[212:215], v[88:91]
	v_mfma_f32_16x16x32_bf16 v[76:79], v[132:135], v[220:223], v[76:79]
	v_mfma_f32_16x16x32_bf16 v[72:75], v[140:143], v[220:223], v[72:75]
	v_mfma_f32_16x16x32_bf16 v[116:119], v[166:169], v[192:195], v[116:119]
	v_mfma_f32_16x16x32_bf16 v[112:115], v[184:187], v[192:195], v[112:115]
	v_mfma_f32_16x16x32_bf16 v[100:103], v[166:169], v[200:203], v[100:103]
	v_mfma_f32_16x16x32_bf16 v[96:99], v[184:187], v[200:203], v[96:99]
	v_mfma_f32_16x16x32_bf16 v[84:87], v[166:169], v[208:211], v[84:87]
	v_mfma_f32_16x16x32_bf16 v[80:83], v[184:187], v[208:211], v[80:83]
	v_mfma_f32_16x16x32_bf16 v[68:71], v[166:169], v[216:219], v[68:71]
	v_mfma_f32_16x16x32_bf16 v[64:67], v[184:187], v[216:219], v[64:67]
	v_mfma_f32_16x16x32_bf16 v[116:119], v[170:173], v[196:199], v[116:119]
	v_mfma_f32_16x16x32_bf16 v[112:115], v[188:191], v[196:199], v[112:115]
	v_mfma_f32_16x16x32_bf16 v[100:103], v[170:173], v[204:207], v[100:103]
	v_mfma_f32_16x16x32_bf16 v[96:99], v[188:191], v[204:207], v[96:99]
	v_mfma_f32_16x16x32_bf16 v[84:87], v[170:173], v[212:215], v[84:87]
	v_mfma_f32_16x16x32_bf16 v[80:83], v[188:191], v[212:215], v[80:83]
	v_mfma_f32_16x16x32_bf16 v[68:71], v[170:173], v[220:223], v[68:71]
	v_mfma_f32_16x16x32_bf16 v[64:67], v[188:191], v[220:223], v[64:67]
	s_barrier
	s_setprio 0
	s_add_u32 s26, s26, 0x100
	s_addc_u32 s27, s27, 0
	s_add_u32 s56, s56, 0x100
	s_addc_u32 s57, s57, 0
	s_cmp_ge_i32 s58, s55
	s_mov_b32 s28, s58
	s_cbranch_scc0 .LBB0_843
	s_and_b64 vcc, exec, s[8:9]
	s_cbranch_vccz .LBB0_846
	s_barrier

; #define PG8_STAGE(bufoff, gbase, voff) do { _Pragma("unroll") for (int _i = 0; _i < 2; ++_i) \
;         __builtin_amdgcn_global_load_lds((const unsigned*)((const char*)(gbase) + (voff)[_i]), (PG8_LAS unsigned*)(lds + (bufoff) + ldsw + _i * 8192), 16, 0, 0); } while (0)
; #define PG8_LDA(dst, b, h) do { _Pragma("unroll") for (int m = 0; m < 4; ++m) _Pragma("unroll") for (int k = 0; k < 2; ++k) dst[m][k] = *(const PG8_LAS bf16x8*)(lds + PG8_SA(b, h) + aoff + m * 2048 + k * 1024); } while (0)
; #define PG8_LDB(dst, b, h) do { _Pragma("unroll") for (int n = 0; n < 2; ++n) _Pragma("unroll") for (int k = 0; k < 2; ++k) dst[n][k] = *(const PG8_LAS bf16x8*)(lds + PG8_SB(b, h) + boff + n * 2048 + k * 1024); } while (0)
; #define PG8_MMA(ai, bj, At, Bt) do { __builtin_amdgcn_s_setprio(1); _Pragma("unroll") for (int m = 0; m < 4; ++m) _Pragma("unroll") for (int n = 0; n < 2; ++n) _Pragma("unroll") for (int k = 0; k < 2; ++k) \
;         acc[ai][bj][m][n] = __builtin_amdgcn_mfma_f32_16x16x32_bf16(Bt[n][k], At[m][k], acc[ai][bj][m][n], 0, 0, 0); __builtin_amdgcn_s_setprio(0); } while (0)
; #define PG8_BAR __builtin_amdgcn_s_barrier()
; template <class Epi, class Sched, bool ALIGN_EPI = false, bool SP2 = false>
; __device__ __forceinline__ void gemm_phase(PG8_LAS unsigned char* lds, const Gemm g, const Sched& S, const Epi& E, const int wid) {
;     ...
;             PG8_LDB(B0, 0, 0); PG8_LDB(B1, 0, 1); PG8_SCHED; PG8_LDA(At, 0, 0); PG8_STAGE(PG8_SA(1, 1), a1 + hstep, voffA);
;             PG8_WAIT_V(8); PG8_WAIT_L(0); PG8_BAR; PG8_MMA(0, 0, At, B0); PG8_MMA(0, 1, At, B1); PG8_BAR; PG8_SCHED;
;             PG8_LDA(At, 0, 1); PG8_STAGE(PG8_SB(0, 0), b2, voffB); PG8_STAGE(PG8_SB(0, 1), b2 + hstep, voffB); PG8_STAGE(PG8_SA(0, 0), a2, voffA);
;             PG8_WAIT_V(8); PG8_WAIT_L(0); PG8_BAR; PG8_MMA(1, 0, At, B0); PG8_MMA(1, 1, At, B1); PG8_BAR; PG8_SCHED;
;             PG8_LDB(B0, 1, 0); PG8_LDB(B1, 1, 1); PG8_SCHED; PG8_LDA(At, 1, 0); PG8_STAGE(PG8_SA(0, 1), a2 + hstep, voffA);
;             PG8_WAIT_V(8); PG8_WAIT_L(0); PG8_BAR; PG8_MMA(0, 0, At, B0); PG8_MMA(0, 1, At, B1); PG8_BAR; PG8_SCHED;
;             PG8_LDA(At, 1, 1); PG8_STAGE(PG8_SB(1, 0), b3, voffB); PG8_STAGE(PG8_SB(1, 1), b3 + hstep, voffB); PG8_STAGE(PG8_SA(1, 0), a3, voffA);
;             PG8_WAIT_V(8); PG8_WAIT_L(0); PG8_BAR; PG8_MMA(1, 0, At, B0); PG8_MMA(1, 1, At, B1); PG8_BAR; PG8_SCHED;
.LBB0_963:
	ds_read_b128 v[146:149], v154
	ds_read_b128 v[158:161], v154 offset:1024
	ds_read_b128 v[162:165], v154 offset:2048
	ds_read_b128 v[166:169], v154 offset:3072
	ds_read_b128 v[170:173], v155
	ds_read_b128 v[174:177], v155 offset:1024
	ds_read_b128 v[178:181], v155 offset:2048
	ds_read_b128 v[182:185], v155 offset:3072
	s_add_u32 s24, s22, 0xfff00080
	s_addc_u32 s25, s23, -1
	s_cmp_eq_u32 s52, 60
	s_cselect_b32 s27, s15, s25
	s_cselect_b32 s26, s48, s24
	s_cselect_b32 s25, s13, s51
	s_cselect_b32 s24, s49, s50
	v_lshl_add_u64 v[218:219], s[22:23], 0, v[138:139]
	s_add_i32 m0, s21, 0xc000
	ds_read_b128 v[186:189], v156
	ds_read_b128 v[190:193], v156 offset:1024
	ds_read_b128 v[194:197], v156 offset:2048
	ds_read_b128 v[198:201], v156 offset:3072
	ds_read_b128 v[202:205], v156 offset:4096
	ds_read_b128 v[206:209], v156 offset:5120
	ds_read_b128 v[210:213], v156 offset:6144
	ds_read_b128 v[214:217], v156 offset:7168
	global_load_lds_dwordx4 v[218:219], off
	v_lshl_add_u64 v[218:219], s[22:23], 0, v[140:141]
	s_add_i32 m0, s21, 0xe000
	s_nop 0
	global_load_lds_dwordx4 v[218:219], off
	s_waitcnt vmcnt(8)
	s_waitcnt lgkmcnt(0)
	s_setprio 1
	s_barrier
	v_mfma_f32_16x16x32_bf16 v[124:127], v[146:149], v[186:189], v[124:127]
	v_mfma_f32_16x16x32_bf16 v[120:123], v[162:165], v[186:189], v[120:123]
	v_mfma_f32_16x16x32_bf16 v[108:111], v[146:149], v[194:197], v[108:111]
	v_mfma_f32_16x16x32_bf16 v[104:107], v[162:165], v[194:197], v[104:107]
	v_mfma_f32_16x16x32_bf16 v[92:95], v[146:149], v[202:205], v[92:95]
	v_mfma_f32_16x16x32_bf16 v[88:91], v[162:165], v[202:205], v[88:91]
	v_mfma_f32_16x16x32_bf16 v[76:79], v[146:149], v[210:213], v[76:79]
	v_mfma_f32_16x16x32_bf16 v[72:75], v[162:165], v[210:213], v[72:75]
	v_mfma_f32_16x16x32_bf16 v[124:127], v[158:161], v[190:193], v[124:127]
	v_mfma_f32_16x16x32_bf16 v[120:123], v[166:169], v[190:193], v[120:123]
	v_mfma_f32_16x16x32_bf16 v[108:111], v[158:161], v[198:201], v[108:111]
	v_mfma_f32_16x16x32_bf16 v[104:107], v[166:169], v[198:201], v[104:107]
	v_mfma_f32_16x16x32_bf16 v[92:95], v[158:161], v[206:209], v[92:95]
	v_mfma_f32_16x16x32_bf16 v[88:91], v[166:169], v[206:209], v[88:91]
	v_mfma_f32_16x16x32_bf16 v[76:79], v[158:161], v[214:217], v[76:79]
	v_mfma_f32_16x16x32_bf16 v[72:75], v[166:169], v[214:217], v[72:75]
	v_mfma_f32_16x16x32_bf16 v[116:119], v[170:173], v[186:189], v[116:119]
	v_mfma_f32_16x16x32_bf16 v[112:115], v[178:181], v[186:189], v[112:115]
	v_mfma_f32_16x16x32_bf16 v[100:103], v[170:173], v[194:197], v[100:103]
	v_mfma_f32_16x16x32_bf16 v[96:99], v[178:181], v[194:197], v[96:99]
	v_mfma_f32_16x16x32_bf16 v[84:87], v[170:173], v[202:205], v[84:87]
	v_mfma_f32_16x16x32_bf16 v[80:83], v[178:181], v[202:205], v[80:83]
	v_mfma_f32_16x16x32_bf16 v[68:71], v[170:173], v[210:213], v[68:71]
	v_mfma_f32_16x16x32_bf16 v[64:67], v[178:181], v[210:213], v[64:67]
	v_mfma_f32_16x16x32_bf16 v[116:119], v[174:177], v[190:193], v[116:119]
	v_mfma_f32_16x16x32_bf16 v[112:115], v[182:185], v[190:193], v[112:115]
	v_mfma_f32_16x16x32_bf16 v[100:103], v[174:177], v[198:201], v[100:103]
	v_mfma_f32_16x16x32_bf16 v[96:99], v[182:185], v[198:201], v[96:99]
	v_mfma_f32_16x16x32_bf16 v[84:87], v[174:177], v[206:209], v[84:87]
	v_mfma_f32_16x16x32_bf16 v[80:83], v[182:185], v[206:209], v[80:83]
	v_mfma_f32_16x16x32_bf16 v[68:71], v[174:177], v[214:217], v[68:71]
	v_mfma_f32_16x16x32_bf16 v[64:67], v[182:185], v[214:217], v[64:67]
	s_barrier
	s_setprio 0
	s_add_i32 s53, s41, s29
	v_lshl_add_u64 v[218:219], s[24:25], 0, v[130:131]
	s_mov_b32 m0, s53
	ds_read_b128 v[186:189], v156 offset:16384
	ds_read_b128 v[190:193], v156 offset:17408
	ds_read_b128 v[194:197], v156 offset:18432
	ds_read_b128 v[198:201], v156 offset:19456
	ds_read_b128 v[202:205], v156 offset:20480
	ds_read_b128 v[206:209], v156 offset:21504
	ds_read_b128 v[210:213], v156 offset:22528
	ds_read_b128 v[214:217], v156 offset:23552
	global_load_lds_dwordx4 v[218:219], off
	s_add_i32 m0, s53, 0x2000
	s_add_u32 s54, s24, 0x100000
	v_lshl_add_u64 v[220:221], s[24:25], 0, v[134:135]
	s_addc_u32 s55, s25, 0
	s_add_i32 s53, s42, s29
	global_load_lds_dwordx4 v[220:221], off
	v_lshl_add_u64 v[222:223], s[54:55], 0, v[130:131]
	s_mov_b32 m0, s53
	v_lshl_add_u64 v[224:225], s[26:27], 0, v[132:133]
	global_load_lds_dwordx4 v[222:223], off
	v_lshl_add_u64 v[222:223], s[54:55], 0, v[134:135]
	s_add_i32 m0, s53, 0x2000
	s_nop 0
	global_load_lds_dwordx4 v[222:223], off
	v_lshl_add_u64 v[222:223], s[26:27], 0, v[128:129]
	s_mov_b32 m0, s21
	s_nop 0
	global_load_lds_dwordx4 v[222:223], off
	s_mov_b32 m0, s34
	s_nop 0
	global_load_lds_dwordx4 v[224:225], off
	s_waitcnt vmcnt(8)
	s_waitcnt lgkmcnt(0)
	s_setprio 1
	s_barrier
; #define PG8_STAGE(bufoff, gbase, voff) do { _Pragma("unroll") for (int _i = 0; _i < 2; ++_i) \
;         __builtin_amdgcn_global_load_lds((const unsigned*)((const char*)(gbase) + (voff)[_i]), (PG8_LAS unsigned*)(lds + (bufoff) + ldsw + _i * 8192), 16, 0, 0); } while (0)
; #define PG8_LDA(dst, b, h) do { _Pragma("unroll") for (int m = 0; m < 4; ++m) _Pragma("unroll") for (int k = 0; k < 2; ++k) dst[m][k] = *(const PG8_LAS bf16x8*)(lds + PG8_SA(b, h) + aoff + m * 2048 + k * 1024); } while (0)
; #define PG8_LDB(dst, b, h) do { _Pragma("unroll") for (int n = 0; n < 2; ++n) _Pragma("unroll") for (int k = 0; k < 2; ++k) dst[n][k] = *(const PG8_LAS bf16x8*)(lds + PG8_SB(b, h) + boff + n * 2048 + k * 1024); } while (0)
; #define PG8_MMA(ai, bj, At, Bt) do { __builtin_amdgcn_s_setprio(1); _Pragma("unroll") for (int m = 0; m < 4; ++m) _Pragma("unroll") for (int n = 0; n < 2; ++n) _Pragma("unroll") for (int k = 0; k < 2; ++k) \
;         acc[ai][bj][m][n] = __builtin_amdgcn_mfma_f32_16x16x32_bf16(Bt[n][k], At[m][k], acc[ai][bj][m][n], 0, 0, 0); __builtin_amdgcn_s_setprio(0); } while (0)
; #define PG8_BAR __builtin_amdgcn_s_barrier()
; template <class Epi, class Sched, bool ALIGN_EPI = false, bool SP2 = false>
; __device__ __forceinline__ void gemm_phase(PG8_LAS unsigned char* lds, const Gemm g, const Sched& S, const Epi& E, const int wid) {
;     ...
;             PG8_LDB(B0, 0, 0); PG8_LDB(B1, 0, 1); PG8_SCHED; PG8_LDA(At, 0, 0); PG8_STAGE(PG8_SA(1, 1), a1 + hstep, voffA);
;             PG8_WAIT_V(8); PG8_WAIT_L(0); PG8_BAR; PG8_MMA(0, 0, At, B0); PG8_MMA(0, 1, At, B1); PG8_BAR; PG8_SCHED;
;             PG8_LDA(At, 0, 1); PG8_STAGE(PG8_SB(0, 0), b2, voffB); PG8_STAGE(PG8_SB(0, 1), b2 + hstep, voffB); PG8_STAGE(PG8_SA(0, 0), a2, voffA);
;             PG8_WAIT_V(8); PG8_WAIT_L(0); PG8_BAR; PG8_MMA(1, 0, At, B0); PG8_MMA(1, 1, At, B1); PG8_BAR; PG8_SCHED;
;             PG8_LDB(B0, 1, 0); PG8_LDB(B1, 1, 1); PG8_SCHED; PG8_LDA(At, 1, 0); PG8_STAGE(PG8_SA(0, 1), a2 + hstep, voffA);
;             PG8_WAIT_V(8); PG8_WAIT_L(0); PG8_BAR; PG8_MMA(0, 0, At, B0); PG8_MMA(0, 1, At, B1); PG8_BAR; PG8_SCHED;
;             PG8_LDA(At, 1, 1); PG8_STAGE(PG8_SB(1, 0), b3, voffB); PG8_STAGE(PG8_SB(1, 1), b3 + hstep, voffB); PG8_STAGE(PG8_SA(1, 0), a3, voffA);
;             PG8_WAIT_V(8); PG8_WAIT_L(0); PG8_BAR; PG8_MMA(1, 0, At, B0); PG8_MMA(1, 1, At, B1); PG8_BAR; PG8_SCHED;
	v_mfma_f32_16x16x32_bf16 v[60:63], v[146:149], v[186:189], v[60:63]
	v_mfma_f32_16x16x32_bf16 v[56:59], v[162:165], v[186:189], v[56:59]
	v_mfma_f32_16x16x32_bf16 v[44:47], v[146:149], v[194:197], v[44:47]
	v_mfma_f32_16x16x32_bf16 v[40:43], v[162:165], v[194:197], v[40:43]
	v_mfma_f32_16x16x32_bf16 v[28:31], v[146:149], v[202:205], v[28:31]
	v_mfma_f32_16x16x32_bf16 v[24:27], v[162:165], v[202:205], v[24:27]
	v_mfma_f32_16x16x32_bf16 v[12:15], v[146:149], v[210:213], v[12:15]
	v_mfma_f32_16x16x32_bf16 v[8:11], v[162:165], v[210:213], v[8:11]
	v_mfma_f32_16x16x32_bf16 v[60:63], v[158:161], v[190:193], v[60:63]
	v_mfma_f32_16x16x32_bf16 v[56:59], v[166:169], v[190:193], v[56:59]
	v_mfma_f32_16x16x32_bf16 v[44:47], v[158:161], v[198:201], v[44:47]
	v_mfma_f32_16x16x32_bf16 v[40:43], v[166:169], v[198:201], v[40:43]
	v_mfma_f32_16x16x32_bf16 v[28:31], v[158:161], v[206:209], v[28:31]
	v_mfma_f32_16x16x32_bf16 v[24:27], v[166:169], v[206:209], v[24:27]
	v_mfma_f32_16x16x32_bf16 v[12:15], v[158:161], v[214:217], v[12:15]
	v_mfma_f32_16x16x32_bf16 v[8:11], v[166:169], v[214:217], v[8:11]
	v_mfma_f32_16x16x32_bf16 v[52:55], v[170:173], v[186:189], v[52:55]
	v_mfma_f32_16x16x32_bf16 v[48:51], v[178:181], v[186:189], v[48:51]
	v_mfma_f32_16x16x32_bf16 v[36:39], v[170:173], v[194:197], v[36:39]
	v_mfma_f32_16x16x32_bf16 v[32:35], v[178:181], v[194:197], v[32:35]
	v_mfma_f32_16x16x32_bf16 v[20:23], v[170:173], v[202:205], v[20:23]
	v_mfma_f32_16x16x32_bf16 v[16:19], v[178:181], v[202:205], v[16:19]
	v_mfma_f32_16x16x32_bf16 v[4:7], v[170:173], v[210:213], v[4:7]
	v_mfma_f32_16x16x32_bf16 v[0:3], v[178:181], v[210:213], v[0:3]
	v_mfma_f32_16x16x32_bf16 v[52:55], v[174:177], v[190:193], v[52:55]
	v_mfma_f32_16x16x32_bf16 v[48:51], v[182:185], v[190:193], v[48:51]
	v_mfma_f32_16x16x32_bf16 v[36:39], v[174:177], v[198:201], v[36:39]
	v_mfma_f32_16x16x32_bf16 v[32:35], v[182:185], v[198:201], v[32:35]
	v_mfma_f32_16x16x32_bf16 v[20:23], v[174:177], v[206:209], v[20:23]
	v_mfma_f32_16x16x32_bf16 v[16:19], v[182:185], v[206:209], v[16:19]
	v_mfma_f32_16x16x32_bf16 v[4:7], v[174:177], v[214:217], v[4:7]
	v_mfma_f32_16x16x32_bf16 v[0:3], v[182:185], v[214:217], v[0:3]
	s_barrier
	s_setprio 0
	s_add_i32 s53, 0, 0x18000
	v_add_u32_e32 v136, s53, v152
	s_add_i32 s54, 0, 0x1c000
	ds_read_b128 v[146:149], v136
	ds_read_b128 v[158:161], v136 offset:1024
	ds_read_b128 v[162:165], v136 offset:2048
	ds_read_b128 v[166:169], v136 offset:3072
	v_add_u32_e32 v136, s54, v152
	ds_read_b128 v[170:173], v136
	ds_read_b128 v[174:177], v136 offset:1024
	ds_read_b128 v[178:181], v136 offset:2048
	ds_read_b128 v[182:185], v136 offset:3072
	s_add_u32 s26, s26, 0x100000
	s_addc_u32 s27, s27, 0
	s_mov_b32 m0, s35
	v_lshl_add_u64 v[226:227], s[26:27], 0, v[128:129]
	ds_read_b128 v[186:189], v156 offset:32768
	ds_read_b128 v[190:193], v156 offset:33792
	ds_read_b128 v[194:197], v156 offset:34816
	ds_read_b128 v[198:201], v156 offset:35840
	ds_read_b128 v[202:205], v156 offset:36864
	ds_read_b128 v[206:209], v156 offset:37888
	ds_read_b128 v[210:213], v156 offset:38912
	ds_read_b128 v[214:217], v156 offset:39936
	global_load_lds_dwordx4 v[226:227], off
	v_lshl_add_u64 v[226:227], s[26:27], 0, v[132:133]
	s_mov_b32 m0, s36
	s_nop 0
	global_load_lds_dwordx4 v[226:227], off
	s_waitcnt vmcnt(8)
	s_waitcnt lgkmcnt(0)
	s_setprio 1
	s_barrier
	v_mfma_f32_16x16x32_bf16 v[124:127], v[146:149], v[186:189], v[124:127]
	v_mfma_f32_16x16x32_bf16 v[120:123], v[162:165], v[186:189], v[120:123]
	v_mfma_f32_16x16x32_bf16 v[108:111], v[146:149], v[194:197], v[108:111]
	v_mfma_f32_16x16x32_bf16 v[104:107], v[162:165], v[194:197], v[104:107]
	v_mfma_f32_16x16x32_bf16 v[92:95], v[146:149], v[202:205], v[92:95]
	v_mfma_f32_16x16x32_bf16 v[88:91], v[162:165], v[202:205], v[88:91]
	v_mfma_f32_16x16x32_bf16 v[76:79], v[146:149], v[210:213], v[76:79]
	v_mfma_f32_16x16x32_bf16 v[72:75], v[162:165], v[210:213], v[72:75]
	v_mfma_f32_16x16x32_bf16 v[124:127], v[158:161], v[190:193], v[124:127]
	v_mfma_f32_16x16x32_bf16 v[120:123], v[166:169], v[190:193], v[120:123]
	v_mfma_f32_16x16x32_bf16 v[108:111], v[158:161], v[198:201], v[108:111]
	v_mfma_f32_16x16x32_bf16 v[104:107], v[166:169], v[198:201], v[104:107]
	v_mfma_f32_16x16x32_bf16 v[92:95], v[158:161], v[206:209], v[92:95]
	v_mfma_f32_16x16x32_bf16 v[88:91], v[166:169], v[206:209], v[88:91]
	v_mfma_f32_16x16x32_bf16 v[76:79], v[158:161], v[214:217], v[76:79]
	v_mfma_f32_16x16x32_bf16 v[72:75], v[166:169], v[214:217], v[72:75]
	v_mfma_f32_16x16x32_bf16 v[116:119], v[170:173], v[186:189], v[116:119]
	v_mfma_f32_16x16x32_bf16 v[112:115], v[178:181], v[186:189], v[112:115]
	v_mfma_f32_16x16x32_bf16 v[100:103], v[170:173], v[194:197], v[100:103]
	v_mfma_f32_16x16x32_bf16 v[96:99], v[178:181], v[194:197], v[96:99]
	v_mfma_f32_16x16x32_bf16 v[84:87], v[170:173], v[202:205], v[84:87]
	v_mfma_f32_16x16x32_bf16 v[80:83], v[178:181], v[202:205], v[80:83]
	v_mfma_f32_16x16x32_bf16 v[68:71], v[170:173], v[210:213], v[68:71]
	v_mfma_f32_16x16x32_bf16 v[64:67], v[178:181], v[210:213], v[64:67]
	v_mfma_f32_16x16x32_bf16 v[116:119], v[174:177], v[190:193], v[116:119]
	v_mfma_f32_16x16x32_bf16 v[112:115], v[182:185], v[190:193], v[112:115]
	v_mfma_f32_16x16x32_bf16 v[100:103], v[174:177], v[198:201], v[100:103]
	v_mfma_f32_16x16x32_bf16 v[96:99], v[182:185], v[198:201], v[96:99]
	v_mfma_f32_16x16x32_bf16 v[84:87], v[174:177], v[206:209], v[84:87]
	v_mfma_f32_16x16x32_bf16 v[80:83], v[182:185], v[206:209], v[80:83]
	v_mfma_f32_16x16x32_bf16 v[68:71], v[174:177], v[214:217], v[68:71]
	v_mfma_f32_16x16x32_bf16 v[64:67], v[182:185], v[214:217], v[64:67]
	s_barrier
; #define PG8_STAGE(bufoff, gbase, voff) do { _Pragma("unroll") for (int _i = 0; _i < 2; ++_i) \
;         __builtin_amdgcn_global_load_lds((const unsigned*)((const char*)(gbase) + (voff)[_i]), (PG8_LAS unsigned*)(lds + (bufoff) + ldsw + _i * 8192), 16, 0, 0); } while (0)
; #define PG8_LDA(dst, b, h) do { _Pragma("unroll") for (int m = 0; m < 4; ++m) _Pragma("unroll") for (int k = 0; k < 2; ++k) dst[m][k] = *(const PG8_LAS bf16x8*)(lds + PG8_SA(b, h) + aoff + m * 2048 + k * 1024); } while (0)
; #define PG8_WAIT_V(n) asm volatile("s_waitcnt vmcnt(" #n ")" ::: "memory")
; #define PG8_WAIT_L(n) asm volatile("s_waitcnt lgkmcnt(" #n ")" ::: "memory")
; #define PG8_BAR __builtin_amdgcn_s_barrier()
; template <class Epi, class Sched, bool ALIGN_EPI = false, bool SP2 = false>
; __device__ __forceinline__ void gemm_phase(PG8_LAS unsigned char* lds, const Gemm g, const Sched& S, const Epi& E, const int wid) {
;     ...
;         for (int t = 0; t < nt; t += 2) {
;             const bool last = (t == nt - 2);
;             const char* a1 = cA + (size_t)(t + 1) * kstep;
;             const char* a2 = last ? nA : cA + (size_t)(t + 2) * kstep; const char* b2 = last ? nB : cB + (size_t)(t + 2) * kstep;
;             const char* a3 = a2 + kstep; const char* b3 = b2 + kstep;
;             if (last && has_next) S.a_ready(nxt);
;             if constexpr (SP2) {
;             PG8_LDB(B0, 0, 0); PG8_LDB(B1, 0, 1); PG8_SCHED; PG8_LDA(At, 0, 0); PG8_STAGE(PG8_SA(1, 1), a1 + hstep, voffA);
;             PG8_WAIT_V(8); PG8_WAIT_L(0); PG8_BAR; PG8_MMA(0, 0, At, B0); PG8_MMA(0, 1, At, B1); PG8_BAR; PG8_SCHED;
;             PG8_LDA(At, 0, 1); PG8_STAGE(PG8_SB(0, 0), b2, voffB); PG8_STAGE(PG8_SB(0, 1), b2 + hstep, voffB); PG8_STAGE(PG8_SA(0, 0), a2, voffA);
;             PG8_WAIT_V(8); PG8_WAIT_L(0); PG8_BAR; PG8_MMA(1, 0, At, B0); PG8_MMA(1, 1, At, B1); PG8_BAR; PG8_SCHED;
;             PG8_LDB(B0, 1, 0); PG8_LDB(B1, 1, 1); PG8_SCHED; PG8_LDA(At, 1, 0); PG8_STAGE(PG8_SA(0, 1), a2 + hstep, voffA);
;             PG8_WAIT_V(8); PG8_WAIT_L(0); PG8_BAR; PG8_MMA(0, 0, At, B0); PG8_MMA(0, 1, At, B1); PG8_BAR; PG8_SCHED;
;             PG8_LDA(At, 1, 1); PG8_STAGE(PG8_SB(1, 0), b3, voffB); PG8_STAGE(PG8_SB(1, 1), b3 + hstep, voffB); PG8_STAGE(PG8_SA(1, 0), a3, voffA);
;             PG8_WAIT_V(8); PG8_WAIT_L(0); PG8_BAR; PG8_MMA(1, 0, At, B0); PG8_MMA(1, 1, At, B1); PG8_BAR; PG8_SCHED;
	s_setprio 0
	s_add_i32 s26, s53, s29
	v_lshl_add_u64 v[218:219], v[218:219], 0, s[8:9]
	s_mov_b32 m0, s26
	ds_read_b128 v[186:189], v156 offset:49152
	ds_read_b128 v[190:193], v156 offset:50176
	ds_read_b128 v[194:197], v156 offset:51200
	ds_read_b128 v[198:201], v156 offset:52224
	ds_read_b128 v[202:205], v156 offset:53248
	ds_read_b128 v[206:209], v156 offset:54272
	ds_read_b128 v[210:213], v156 offset:55296
	ds_read_b128 v[214:217], v156 offset:56320
	global_load_lds_dwordx4 v[218:219], off
	s_add_i32 m0, s26, 0x2000
	s_add_u32 s24, s24, 0x100080
	v_lshl_add_u64 v[218:219], v[220:221], 0, s[8:9]
	s_addc_u32 s25, s25, 0
	s_add_i32 s26, s54, s29
	global_load_lds_dwordx4 v[218:219], off
	v_lshl_add_u64 v[218:219], s[24:25], 0, v[130:131]
	s_mov_b32 m0, s26
	s_nop 0
	global_load_lds_dwordx4 v[218:219], off
	v_lshl_add_u64 v[218:219], s[24:25], 0, v[134:135]
	s_add_i32 m0, s26, 0x2000
	s_nop 0
	global_load_lds_dwordx4 v[218:219], off
	v_lshl_add_u64 v[218:219], v[222:223], 0, s[8:9]
	s_mov_b32 m0, s38
	s_nop 0
	global_load_lds_dwordx4 v[218:219], off
	v_lshl_add_u64 v[218:219], v[224:225], 0, s[8:9]
	s_mov_b32 m0, s39
	s_nop 0
	global_load_lds_dwordx4 v[218:219], off
	s_waitcnt vmcnt(8)
	s_waitcnt lgkmcnt(0)
	s_setprio 1
	s_barrier
	v_mfma_f32_16x16x32_bf16 v[60:63], v[146:149], v[186:189], v[60:63]
	v_mfma_f32_16x16x32_bf16 v[56:59], v[162:165], v[186:189], v[56:59]
	v_mfma_f32_16x16x32_bf16 v[44:47], v[146:149], v[194:197], v[44:47]
	v_mfma_f32_16x16x32_bf16 v[40:43], v[162:165], v[194:197], v[40:43]
	v_mfma_f32_16x16x32_bf16 v[28:31], v[146:149], v[202:205], v[28:31]
	v_mfma_f32_16x16x32_bf16 v[24:27], v[162:165], v[202:205], v[24:27]
	v_mfma_f32_16x16x32_bf16 v[12:15], v[146:149], v[210:213], v[12:15]
	v_mfma_f32_16x16x32_bf16 v[8:11], v[162:165], v[210:213], v[8:11]
	v_mfma_f32_16x16x32_bf16 v[60:63], v[158:161], v[190:193], v[60:63]
	v_mfma_f32_16x16x32_bf16 v[56:59], v[166:169], v[190:193], v[56:59]
	v_mfma_f32_16x16x32_bf16 v[44:47], v[158:161], v[198:201], v[44:47]
	v_mfma_f32_16x16x32_bf16 v[40:43], v[166:169], v[198:201], v[40:43]
	v_mfma_f32_16x16x32_bf16 v[28:31], v[158:161], v[206:209], v[28:31]
	v_mfma_f32_16x16x32_bf16 v[24:27], v[166:169], v[206:209], v[24:27]
	v_mfma_f32_16x16x32_bf16 v[12:15], v[158:161], v[214:217], v[12:15]
	v_mfma_f32_16x16x32_bf16 v[8:11], v[166:169], v[214:217], v[8:11]
	v_mfma_f32_16x16x32_bf16 v[52:55], v[170:173], v[186:189], v[52:55]
	v_mfma_f32_16x16x32_bf16 v[48:51], v[178:181], v[186:189], v[48:51]
	v_mfma_f32_16x16x32_bf16 v[36:39], v[170:173], v[194:197], v[36:39]
	v_mfma_f32_16x16x32_bf16 v[32:35], v[178:181], v[194:197], v[32:35]
	v_mfma_f32_16x16x32_bf16 v[20:23], v[170:173], v[202:205], v[20:23]
	v_mfma_f32_16x16x32_bf16 v[16:19], v[178:181], v[202:205], v[16:19]
	v_mfma_f32_16x16x32_bf16 v[4:7], v[170:173], v[210:213], v[4:7]
	v_mfma_f32_16x16x32_bf16 v[0:3], v[178:181], v[210:213], v[0:3]
	v_mfma_f32_16x16x32_bf16 v[52:55], v[174:177], v[190:193], v[52:55]
	v_mfma_f32_16x16x32_bf16 v[48:51], v[182:185], v[190:193], v[48:51]
	v_mfma_f32_16x16x32_bf16 v[36:39], v[174:177], v[198:201], v[36:39]
	v_mfma_f32_16x16x32_bf16 v[32:35], v[182:185], v[198:201], v[32:35]
	v_mfma_f32_16x16x32_bf16 v[20:23], v[174:177], v[206:209], v[20:23]
	v_mfma_f32_16x16x32_bf16 v[16:19], v[182:185], v[206:209], v[16:19]
	v_mfma_f32_16x16x32_bf16 v[4:7], v[174:177], v[214:217], v[4:7]
	v_mfma_f32_16x16x32_bf16 v[0:3], v[182:185], v[214:217], v[0:3]
	s_barrier
	s_setprio 0
	s_add_i32 s52, s52, 2
	s_add_u32 s22, s22, 0x100
	s_addc_u32 s23, s23, 0
	s_add_u32 s50, s50, 0x100
	s_addc_u32 s51, s51, 0
	s_cmp_gt_u32 s52, 61
	s_cbranch_scc0 .LBB0_963
	s_and_b64 vcc, exec, s[10:11]
	s_cbranch_vccz .LBB0_966
	s_barrier

; #define PG8_STAGE(bufoff, gbase, voff) do { _Pragma("unroll") for (int _i = 0; _i < 2; ++_i) \
;         __builtin_amdgcn_global_load_lds((const unsigned*)((const char*)(gbase) + (voff)[_i]), (PG8_LAS unsigned*)(lds + (bufoff) + ldsw + _i * 8192), 16, 0, 0); } while (0)
; #define PG8_LDA(dst, b, h) do { _Pragma("unroll") for (int m = 0; m < 4; ++m) _Pragma("unroll") for (int k = 0; k < 2; ++k) dst[m][k] = *(const PG8_LAS bf16x8*)(lds + PG8_SA(b, h) + aoff + m * 2048 + k * 1024); } while (0)
; #define PG8_LDB(dst, b, h) do { _Pragma("unroll") for (int n = 0; n < 2; ++n) _Pragma("unroll") for (int k = 0; k < 2; ++k) dst[n][k] = *(const PG8_LAS bf16x8*)(lds + PG8_SB(b, h) + boff + n * 2048 + k * 1024); } while (0)
; #define PG8_MMA(ai, bj, At, Bt) do { __builtin_amdgcn_s_setprio(1); _Pragma("unroll") for (int m = 0; m < 4; ++m) _Pragma("unroll") for (int n = 0; n < 2; ++n) _Pragma("unroll") for (int k = 0; k < 2; ++k) \
;         acc[ai][bj][m][n] = __builtin_amdgcn_mfma_f32_16x16x32_bf16(Bt[n][k], At[m][k], acc[ai][bj][m][n], 0, 0, 0); __builtin_amdgcn_s_setprio(0); } while (0)
; #define PG8_BAR __builtin_amdgcn_s_barrier()
; template <class Epi, class Sched, bool ALIGN_EPI = false, bool SP2 = false>
; __device__ __forceinline__ void gemm_phase(PG8_LAS unsigned char* lds, const Gemm g, const Sched& S, const Epi& E, const int wid) {
;     ...
;             PG8_LDB(B0, 0, 0); PG8_LDB(B1, 0, 1); PG8_SCHED; PG8_LDA(At, 0, 0); PG8_STAGE(PG8_SA(1, 1), a1 + hstep, voffA);
;             PG8_WAIT_V(8); PG8_WAIT_L(0); PG8_BAR; PG8_MMA(0, 0, At, B0); PG8_MMA(0, 1, At, B1); PG8_BAR; PG8_SCHED;
;             PG8_LDA(At, 0, 1); PG8_STAGE(PG8_SB(0, 0), b2, voffB); PG8_STAGE(PG8_SB(0, 1), b2 + hstep, voffB); PG8_STAGE(PG8_SA(0, 0), a2, voffA);
;             PG8_WAIT_V(8); PG8_WAIT_L(0); PG8_BAR; PG8_MMA(1, 0, At, B0); PG8_MMA(1, 1, At, B1); PG8_BAR; PG8_SCHED;
;             PG8_LDB(B0, 1, 0); PG8_LDB(B1, 1, 1); PG8_SCHED; PG8_LDA(At, 1, 0); PG8_STAGE(PG8_SA(0, 1), a2 + hstep, voffA);
;             PG8_WAIT_V(8); PG8_WAIT_L(0); PG8_BAR; PG8_MMA(0, 0, At, B0); PG8_MMA(0, 1, At, B1); PG8_BAR; PG8_SCHED;
;             PG8_LDA(At, 1, 1); PG8_STAGE(PG8_SB(1, 0), b3, voffB); PG8_STAGE(PG8_SB(1, 1), b3 + hstep, voffB); PG8_STAGE(PG8_SA(1, 0), a3, voffA);
;             PG8_WAIT_V(8); PG8_WAIT_L(0); PG8_BAR; PG8_MMA(1, 0, At, B0); PG8_MMA(1, 1, At, B1); PG8_BAR; PG8_SCHED;
.LBB0_1138:
	ds_read_b128 v[128:131], v197
	ds_read_b128 v[132:135], v197 offset:1024
	ds_read_b128 v[136:139], v197 offset:2048
	ds_read_b128 v[140:143], v197 offset:3072
	ds_read_b128 v[144:147], v198
	ds_read_b128 v[148:151], v198 offset:1024
	ds_read_b128 v[174:177], v198 offset:2048
	ds_read_b128 v[178:181], v198 offset:3072
	s_add_i32 s56, s22, 2
	s_add_u32 s20, s18, 0x100
	s_addc_u32 s21, s19, 0
	s_cmp_eq_u32 s13, s22
	s_cselect_b32 s22, s16, s54
	s_cselect_b32 s25, s15, s21
	s_cselect_b32 s24, s14, s20
	s_cselect_b32 s23, s17, s55
	v_lshl_add_u64 v[190:191], s[18:19], 0, v[168:169]
	s_add_i32 m0, s29, 0xc000
	ds_read_b128 v[182:185], v199
	ds_read_b128 v[186:189], v199 offset:1024
	ds_read_b128 v[200:203], v199 offset:2048
	ds_read_b128 v[204:207], v199 offset:3072
	ds_read_b128 v[208:211], v199 offset:4096
	ds_read_b128 v[212:215], v199 offset:5120
	ds_read_b128 v[216:219], v199 offset:6144
	ds_read_b128 v[220:223], v199 offset:7168
	global_load_lds_dwordx4 v[190:191], off
	v_lshl_add_u64 v[190:191], s[18:19], 0, v[170:171]
	s_add_i32 m0, s29, 0xe000
	s_nop 0
	global_load_lds_dwordx4 v[190:191], off
	s_waitcnt vmcnt(8)
	s_waitcnt lgkmcnt(0)
	s_setprio 1
	s_barrier
	v_mfma_f32_16x16x32_bf16 v[60:63], v[128:131], v[182:185], v[60:63]
	v_mfma_f32_16x16x32_bf16 v[56:59], v[136:139], v[182:185], v[56:59]
	v_mfma_f32_16x16x32_bf16 v[44:47], v[128:131], v[200:203], v[44:47]
	v_mfma_f32_16x16x32_bf16 v[40:43], v[136:139], v[200:203], v[40:43]
	v_mfma_f32_16x16x32_bf16 v[28:31], v[128:131], v[208:211], v[28:31]
	v_mfma_f32_16x16x32_bf16 v[24:27], v[136:139], v[208:211], v[24:27]
	v_mfma_f32_16x16x32_bf16 v[12:15], v[128:131], v[216:219], v[12:15]
	v_mfma_f32_16x16x32_bf16 v[8:11], v[136:139], v[216:219], v[8:11]
	v_mfma_f32_16x16x32_bf16 v[60:63], v[132:135], v[186:189], v[60:63]
	v_mfma_f32_16x16x32_bf16 v[56:59], v[140:143], v[186:189], v[56:59]
	v_mfma_f32_16x16x32_bf16 v[44:47], v[132:135], v[204:207], v[44:47]
	v_mfma_f32_16x16x32_bf16 v[40:43], v[140:143], v[204:207], v[40:43]
	v_mfma_f32_16x16x32_bf16 v[28:31], v[132:135], v[212:215], v[28:31]
	v_mfma_f32_16x16x32_bf16 v[24:27], v[140:143], v[212:215], v[24:27]
	v_mfma_f32_16x16x32_bf16 v[12:15], v[132:135], v[220:223], v[12:15]
	v_mfma_f32_16x16x32_bf16 v[8:11], v[140:143], v[220:223], v[8:11]
	v_mfma_f32_16x16x32_bf16 v[52:55], v[144:147], v[182:185], v[52:55]
	v_mfma_f32_16x16x32_bf16 v[48:51], v[174:177], v[182:185], v[48:51]
	v_mfma_f32_16x16x32_bf16 v[36:39], v[144:147], v[200:203], v[36:39]
	v_mfma_f32_16x16x32_bf16 v[32:35], v[174:177], v[200:203], v[32:35]
	v_mfma_f32_16x16x32_bf16 v[20:23], v[144:147], v[208:211], v[20:23]
	v_mfma_f32_16x16x32_bf16 v[16:19], v[174:177], v[208:211], v[16:19]
	v_mfma_f32_16x16x32_bf16 v[4:7], v[144:147], v[216:219], v[4:7]
	v_mfma_f32_16x16x32_bf16 v[0:3], v[174:177], v[216:219], v[0:3]
	v_mfma_f32_16x16x32_bf16 v[52:55], v[148:151], v[186:189], v[52:55]
	v_mfma_f32_16x16x32_bf16 v[48:51], v[178:181], v[186:189], v[48:51]
	v_mfma_f32_16x16x32_bf16 v[36:39], v[148:151], v[204:207], v[36:39]
	v_mfma_f32_16x16x32_bf16 v[32:35], v[178:181], v[204:207], v[32:35]
	v_mfma_f32_16x16x32_bf16 v[20:23], v[148:151], v[212:215], v[20:23]
	v_mfma_f32_16x16x32_bf16 v[16:19], v[178:181], v[212:215], v[16:19]
	v_mfma_f32_16x16x32_bf16 v[4:7], v[148:151], v[220:223], v[4:7]
	v_mfma_f32_16x16x32_bf16 v[0:3], v[178:181], v[220:223], v[0:3]
	s_barrier
	s_setprio 0
	s_add_i32 s18, s40, s28
	v_lshl_add_u64 v[190:191], s[22:23], 0, v[154:155]
	s_mov_b32 m0, s18
	ds_read_b128 v[182:185], v199 offset:16384
	ds_read_b128 v[186:189], v199 offset:17408
	ds_read_b128 v[200:203], v199 offset:18432
	ds_read_b128 v[204:207], v199 offset:19456
	ds_read_b128 v[208:211], v199 offset:20480
	ds_read_b128 v[212:215], v199 offset:21504
	ds_read_b128 v[216:219], v199 offset:22528
	ds_read_b128 v[220:223], v199 offset:23552
	global_load_lds_dwordx4 v[190:191], off
	s_add_i32 m0, s18, 0x2000
	s_add_u32 s18, s22, 0x2b0000
	v_lshl_add_u64 v[224:225], s[22:23], 0, v[158:159]
	s_addc_u32 s19, s23, 0
	s_add_i32 s57, s41, s28
	global_load_lds_dwordx4 v[224:225], off
	v_lshl_add_u64 v[226:227], s[18:19], 0, v[154:155]
	s_mov_b32 m0, s57
	v_lshl_add_u64 v[228:229], s[24:25], 0, v[156:157]
	global_load_lds_dwordx4 v[226:227], off
	v_lshl_add_u64 v[226:227], s[18:19], 0, v[158:159]
	s_add_i32 m0, s57, 0x2000
	s_nop 0
	global_load_lds_dwordx4 v[226:227], off
	v_lshl_add_u64 v[226:227], s[24:25], 0, v[152:153]
	s_mov_b32 m0, s29
	s_nop 0
	global_load_lds_dwordx4 v[226:227], off
	s_mov_b32 m0, s30
	s_nop 0
	global_load_lds_dwordx4 v[228:229], off
	s_waitcnt vmcnt(8)
	s_waitcnt lgkmcnt(0)
	s_setprio 1
	s_barrier
; #define PG8_STAGE(bufoff, gbase, voff) do { _Pragma("unroll") for (int _i = 0; _i < 2; ++_i) \
;         __builtin_amdgcn_global_load_lds((const unsigned*)((const char*)(gbase) + (voff)[_i]), (PG8_LAS unsigned*)(lds + (bufoff) + ldsw + _i * 8192), 16, 0, 0); } while (0)
; #define PG8_LDA(dst, b, h) do { _Pragma("unroll") for (int m = 0; m < 4; ++m) _Pragma("unroll") for (int k = 0; k < 2; ++k) dst[m][k] = *(const PG8_LAS bf16x8*)(lds + PG8_SA(b, h) + aoff + m * 2048 + k * 1024); } while (0)
; #define PG8_LDB(dst, b, h) do { _Pragma("unroll") for (int n = 0; n < 2; ++n) _Pragma("unroll") for (int k = 0; k < 2; ++k) dst[n][k] = *(const PG8_LAS bf16x8*)(lds + PG8_SB(b, h) + boff + n * 2048 + k * 1024); } while (0)
; #define PG8_MMA(ai, bj, At, Bt) do { __builtin_amdgcn_s_setprio(1); _Pragma("unroll") for (int m = 0; m < 4; ++m) _Pragma("unroll") for (int n = 0; n < 2; ++n) _Pragma("unroll") for (int k = 0; k < 2; ++k) \
;         acc[ai][bj][m][n] = __builtin_amdgcn_mfma_f32_16x16x32_bf16(Bt[n][k], At[m][k], acc[ai][bj][m][n], 0, 0, 0); __builtin_amdgcn_s_setprio(0); } while (0)
; #define PG8_BAR __builtin_amdgcn_s_barrier()
; template <class Epi, class Sched, bool ALIGN_EPI = false, bool SP2 = false>
; __device__ __forceinline__ void gemm_phase(PG8_LAS unsigned char* lds, const Gemm g, const Sched& S, const Epi& E, const int wid) {
;     ...
;             PG8_LDB(B0, 0, 0); PG8_LDB(B1, 0, 1); PG8_SCHED; PG8_LDA(At, 0, 0); PG8_STAGE(PG8_SA(1, 1), a1 + hstep, voffA);
;             PG8_WAIT_V(8); PG8_WAIT_L(0); PG8_BAR; PG8_MMA(0, 0, At, B0); PG8_MMA(0, 1, At, B1); PG8_BAR; PG8_SCHED;
;             PG8_LDA(At, 0, 1); PG8_STAGE(PG8_SB(0, 0), b2, voffB); PG8_STAGE(PG8_SB(0, 1), b2 + hstep, voffB); PG8_STAGE(PG8_SA(0, 0), a2, voffA);
;             PG8_WAIT_V(8); PG8_WAIT_L(0); PG8_BAR; PG8_MMA(1, 0, At, B0); PG8_MMA(1, 1, At, B1); PG8_BAR; PG8_SCHED;
;             PG8_LDB(B0, 1, 0); PG8_LDB(B1, 1, 1); PG8_SCHED; PG8_LDA(At, 1, 0); PG8_STAGE(PG8_SA(0, 1), a2 + hstep, voffA);
;             PG8_WAIT_V(8); PG8_WAIT_L(0); PG8_BAR; PG8_MMA(0, 0, At, B0); PG8_MMA(0, 1, At, B1); PG8_BAR; PG8_SCHED;
;             PG8_LDA(At, 1, 1); PG8_STAGE(PG8_SB(1, 0), b3, voffB); PG8_STAGE(PG8_SB(1, 1), b3 + hstep, voffB); PG8_STAGE(PG8_SA(1, 0), a3, voffA);
;             PG8_WAIT_V(8); PG8_WAIT_L(0); PG8_BAR; PG8_MMA(1, 0, At, B0); PG8_MMA(1, 1, At, B1); PG8_BAR; PG8_SCHED;
	v_mfma_f32_16x16x32_bf16 v[124:127], v[128:131], v[182:185], v[124:127]
	v_mfma_f32_16x16x32_bf16 v[120:123], v[136:139], v[182:185], v[120:123]
	v_mfma_f32_16x16x32_bf16 v[108:111], v[128:131], v[200:203], v[108:111]
	v_mfma_f32_16x16x32_bf16 v[104:107], v[136:139], v[200:203], v[104:107]
	v_mfma_f32_16x16x32_bf16 v[92:95], v[128:131], v[208:211], v[92:95]
	v_mfma_f32_16x16x32_bf16 v[88:91], v[136:139], v[208:211], v[88:91]
	v_mfma_f32_16x16x32_bf16 v[76:79], v[128:131], v[216:219], v[76:79]
	v_mfma_f32_16x16x32_bf16 v[72:75], v[136:139], v[216:219], v[72:75]
	v_mfma_f32_16x16x32_bf16 v[124:127], v[132:135], v[186:189], v[124:127]
	v_mfma_f32_16x16x32_bf16 v[120:123], v[140:143], v[186:189], v[120:123]
	v_mfma_f32_16x16x32_bf16 v[108:111], v[132:135], v[204:207], v[108:111]
	v_mfma_f32_16x16x32_bf16 v[104:107], v[140:143], v[204:207], v[104:107]
	v_mfma_f32_16x16x32_bf16 v[92:95], v[132:135], v[212:215], v[92:95]
	v_mfma_f32_16x16x32_bf16 v[88:91], v[140:143], v[212:215], v[88:91]
	v_mfma_f32_16x16x32_bf16 v[76:79], v[132:135], v[220:223], v[76:79]
	v_mfma_f32_16x16x32_bf16 v[72:75], v[140:143], v[220:223], v[72:75]
	v_mfma_f32_16x16x32_bf16 v[116:119], v[144:147], v[182:185], v[116:119]
	v_mfma_f32_16x16x32_bf16 v[112:115], v[174:177], v[182:185], v[112:115]
	v_mfma_f32_16x16x32_bf16 v[100:103], v[144:147], v[200:203], v[100:103]
	v_mfma_f32_16x16x32_bf16 v[96:99], v[174:177], v[200:203], v[96:99]
	v_mfma_f32_16x16x32_bf16 v[84:87], v[144:147], v[208:211], v[84:87]
	v_mfma_f32_16x16x32_bf16 v[80:83], v[174:177], v[208:211], v[80:83]
	v_mfma_f32_16x16x32_bf16 v[68:71], v[144:147], v[216:219], v[68:71]
	v_mfma_f32_16x16x32_bf16 v[64:67], v[174:177], v[216:219], v[64:67]
	v_mfma_f32_16x16x32_bf16 v[116:119], v[148:151], v[186:189], v[116:119]
	v_mfma_f32_16x16x32_bf16 v[112:115], v[178:181], v[186:189], v[112:115]
	v_mfma_f32_16x16x32_bf16 v[100:103], v[148:151], v[204:207], v[100:103]
	v_mfma_f32_16x16x32_bf16 v[96:99], v[178:181], v[204:207], v[96:99]
	v_mfma_f32_16x16x32_bf16 v[84:87], v[148:151], v[212:215], v[84:87]
	v_mfma_f32_16x16x32_bf16 v[80:83], v[178:181], v[212:215], v[80:83]
	v_mfma_f32_16x16x32_bf16 v[68:71], v[148:151], v[220:223], v[68:71]
	v_mfma_f32_16x16x32_bf16 v[64:67], v[178:181], v[220:223], v[64:67]
	s_barrier
	s_setprio 0
	s_add_i32 s57, 0, 0x18000
	s_add_i32 s58, 0, 0x1c000
	v_add_u32_e32 v140, s57, v195
	v_add_u32_e32 v178, s58, v195
	ds_read_b128 v[128:131], v140
	ds_read_b128 v[132:135], v140 offset:1024
	ds_read_b128 v[136:139], v140 offset:2048
	ds_read_b128 v[140:143], v140 offset:3072
	ds_read_b128 v[144:147], v178
	ds_read_b128 v[148:151], v178 offset:1024
	ds_read_b128 v[174:177], v178 offset:2048
	ds_read_b128 v[178:181], v178 offset:3072
	s_add_u32 s18, s24, 0x2b0000
	s_addc_u32 s19, s25, 0
	s_mov_b32 m0, s31
	v_lshl_add_u64 v[230:231], s[18:19], 0, v[152:153]
	ds_read_b128 v[182:185], v199 offset:32768
	ds_read_b128 v[186:189], v199 offset:33792
	ds_read_b128 v[200:203], v199 offset:34816
	ds_read_b128 v[204:207], v199 offset:35840
	ds_read_b128 v[208:211], v199 offset:36864
	ds_read_b128 v[212:215], v199 offset:37888
	ds_read_b128 v[216:219], v199 offset:38912
	ds_read_b128 v[220:223], v199 offset:39936
	global_load_lds_dwordx4 v[230:231], off
	v_lshl_add_u64 v[230:231], s[18:19], 0, v[156:157]
	s_mov_b32 m0, s34
	s_nop 0
	global_load_lds_dwordx4 v[230:231], off
	s_waitcnt vmcnt(8)
	s_waitcnt lgkmcnt(0)
	s_setprio 1
	s_barrier
	v_mfma_f32_16x16x32_bf16 v[60:63], v[128:131], v[182:185], v[60:63]
	v_mfma_f32_16x16x32_bf16 v[56:59], v[136:139], v[182:185], v[56:59]
	v_mfma_f32_16x16x32_bf16 v[44:47], v[128:131], v[200:203], v[44:47]
	v_mfma_f32_16x16x32_bf16 v[40:43], v[136:139], v[200:203], v[40:43]
	v_mfma_f32_16x16x32_bf16 v[28:31], v[128:131], v[208:211], v[28:31]
	v_mfma_f32_16x16x32_bf16 v[24:27], v[136:139], v[208:211], v[24:27]
	v_mfma_f32_16x16x32_bf16 v[12:15], v[128:131], v[216:219], v[12:15]
	v_mfma_f32_16x16x32_bf16 v[8:11], v[136:139], v[216:219], v[8:11]
	v_mfma_f32_16x16x32_bf16 v[60:63], v[132:135], v[186:189], v[60:63]
	v_mfma_f32_16x16x32_bf16 v[56:59], v[140:143], v[186:189], v[56:59]
	v_mfma_f32_16x16x32_bf16 v[44:47], v[132:135], v[204:207], v[44:47]
	v_mfma_f32_16x16x32_bf16 v[40:43], v[140:143], v[204:207], v[40:43]
	v_mfma_f32_16x16x32_bf16 v[28:31], v[132:135], v[212:215], v[28:31]
	v_mfma_f32_16x16x32_bf16 v[24:27], v[140:143], v[212:215], v[24:27]
	v_mfma_f32_16x16x32_bf16 v[12:15], v[132:135], v[220:223], v[12:15]
	v_mfma_f32_16x16x32_bf16 v[8:11], v[140:143], v[220:223], v[8:11]
	v_mfma_f32_16x16x32_bf16 v[52:55], v[144:147], v[182:185], v[52:55]
	v_mfma_f32_16x16x32_bf16 v[48:51], v[174:177], v[182:185], v[48:51]
	v_mfma_f32_16x16x32_bf16 v[36:39], v[144:147], v[200:203], v[36:39]
	v_mfma_f32_16x16x32_bf16 v[32:35], v[174:177], v[200:203], v[32:35]
	v_mfma_f32_16x16x32_bf16 v[20:23], v[144:147], v[208:211], v[20:23]
	v_mfma_f32_16x16x32_bf16 v[16:19], v[174:177], v[208:211], v[16:19]
	v_mfma_f32_16x16x32_bf16 v[4:7], v[144:147], v[216:219], v[4:7]
	v_mfma_f32_16x16x32_bf16 v[0:3], v[174:177], v[216:219], v[0:3]
	v_mfma_f32_16x16x32_bf16 v[52:55], v[148:151], v[186:189], v[52:55]
	v_mfma_f32_16x16x32_bf16 v[48:51], v[178:181], v[186:189], v[48:51]
	v_mfma_f32_16x16x32_bf16 v[36:39], v[148:151], v[204:207], v[36:39]
	v_mfma_f32_16x16x32_bf16 v[32:35], v[178:181], v[204:207], v[32:35]
	v_mfma_f32_16x16x32_bf16 v[20:23], v[148:151], v[212:215], v[20:23]
	v_mfma_f32_16x16x32_bf16 v[16:19], v[178:181], v[212:215], v[16:19]
	v_mfma_f32_16x16x32_bf16 v[4:7], v[148:151], v[220:223], v[4:7]
	v_mfma_f32_16x16x32_bf16 v[0:3], v[178:181], v[220:223], v[0:3]
	s_barrier
; #define PG8_STAGE(bufoff, gbase, voff) do { _Pragma("unroll") for (int _i = 0; _i < 2; ++_i) \
;         __builtin_amdgcn_global_load_lds((const unsigned*)((const char*)(gbase) + (voff)[_i]), (PG8_LAS unsigned*)(lds + (bufoff) + ldsw + _i * 8192), 16, 0, 0); } while (0)
; #define PG8_LDA(dst, b, h) do { _Pragma("unroll") for (int m = 0; m < 4; ++m) _Pragma("unroll") for (int k = 0; k < 2; ++k) dst[m][k] = *(const PG8_LAS bf16x8*)(lds + PG8_SA(b, h) + aoff + m * 2048 + k * 1024); } while (0)
; #define PG8_WAIT_V(n) asm volatile("s_waitcnt vmcnt(" #n ")" ::: "memory")
; #define PG8_WAIT_L(n) asm volatile("s_waitcnt lgkmcnt(" #n ")" ::: "memory")
; #define PG8_BAR __builtin_amdgcn_s_barrier()
; template <class Epi, class Sched, bool ALIGN_EPI = false, bool SP2 = false>
; __device__ __forceinline__ void gemm_phase(PG8_LAS unsigned char* lds, const Gemm g, const Sched& S, const Epi& E, const int wid) {
;     ...
;         for (int t = 0; t < nt; t += 2) {
;             const bool last = (t == nt - 2);
;             const char* a1 = cA + (size_t)(t + 1) * kstep;
;             const char* a2 = last ? nA : cA + (size_t)(t + 2) * kstep; const char* b2 = last ? nB : cB + (size_t)(t + 2) * kstep;
;             const char* a3 = a2 + kstep; const char* b3 = b2 + kstep;
;             if (last && has_next) S.a_ready(nxt);
;             if constexpr (SP2) {
;             PG8_LDB(B0, 0, 0); PG8_LDB(B1, 0, 1); PG8_SCHED; PG8_LDA(At, 0, 0); PG8_STAGE(PG8_SA(1, 1), a1 + hstep, voffA);
;             PG8_WAIT_V(8); PG8_WAIT_L(0); PG8_BAR; PG8_MMA(0, 0, At, B0); PG8_MMA(0, 1, At, B1); PG8_BAR; PG8_SCHED;
;             PG8_LDA(At, 0, 1); PG8_STAGE(PG8_SB(0, 0), b2, voffB); PG8_STAGE(PG8_SB(0, 1), b2 + hstep, voffB); PG8_STAGE(PG8_SA(0, 0), a2, voffA);
;             PG8_WAIT_V(8); PG8_WAIT_L(0); PG8_BAR; PG8_MMA(1, 0, At, B0); PG8_MMA(1, 1, At, B1); PG8_BAR; PG8_SCHED;
;             PG8_LDB(B0, 1, 0); PG8_LDB(B1, 1, 1); PG8_SCHED; PG8_LDA(At, 1, 0); PG8_STAGE(PG8_SA(0, 1), a2 + hstep, voffA);
;             PG8_WAIT_V(8); PG8_WAIT_L(0); PG8_BAR; PG8_MMA(0, 0, At, B0); PG8_MMA(0, 1, At, B1); PG8_BAR; PG8_SCHED;
;             PG8_LDA(At, 1, 1); PG8_STAGE(PG8_SB(1, 0), b3, voffB); PG8_STAGE(PG8_SB(1, 1), b3 + hstep, voffB); PG8_STAGE(PG8_SA(1, 0), a3, voffA);
;             PG8_WAIT_V(8); PG8_WAIT_L(0); PG8_BAR; PG8_MMA(1, 0, At, B0); PG8_MMA(1, 1, At, B1); PG8_BAR; PG8_SCHED;
	s_setprio 0
	s_add_i32 s18, s57, s28
	v_lshl_add_u64 v[190:191], v[190:191], 0, s[8:9]
	s_mov_b32 m0, s18
	ds_read_b128 v[182:185], v199 offset:49152
	ds_read_b128 v[186:189], v199 offset:50176
	ds_read_b128 v[200:203], v199 offset:51200
	ds_read_b128 v[204:207], v199 offset:52224
	ds_read_b128 v[208:211], v199 offset:53248
	ds_read_b128 v[212:215], v199 offset:54272
	ds_read_b128 v[216:219], v199 offset:55296
	ds_read_b128 v[220:223], v199 offset:56320
	global_load_lds_dwordx4 v[190:191], off
	s_add_i32 m0, s18, 0x2000
	s_add_u32 s18, s22, 0x2b0080
	v_lshl_add_u64 v[190:191], v[224:225], 0, s[8:9]
	s_addc_u32 s19, s23, 0
	s_add_i32 s22, s58, s28
	global_load_lds_dwordx4 v[190:191], off
	v_lshl_add_u64 v[190:191], s[18:19], 0, v[154:155]
	s_mov_b32 m0, s22
	s_nop 0
	global_load_lds_dwordx4 v[190:191], off
	v_lshl_add_u64 v[190:191], s[18:19], 0, v[158:159]
	s_add_i32 m0, s22, 0x2000
	s_nop 0
	global_load_lds_dwordx4 v[190:191], off
	v_lshl_add_u64 v[190:191], v[226:227], 0, s[8:9]
	s_mov_b32 m0, s36
	s_nop 0
	global_load_lds_dwordx4 v[190:191], off
	v_lshl_add_u64 v[190:191], v[228:229], 0, s[8:9]
	s_mov_b32 m0, s37
	s_nop 0
	global_load_lds_dwordx4 v[190:191], off
	s_waitcnt vmcnt(8)
	s_waitcnt lgkmcnt(0)
	s_setprio 1
	s_barrier
	v_mfma_f32_16x16x32_bf16 v[124:127], v[128:131], v[182:185], v[124:127]
	v_mfma_f32_16x16x32_bf16 v[120:123], v[136:139], v[182:185], v[120:123]
	v_mfma_f32_16x16x32_bf16 v[108:111], v[128:131], v[200:203], v[108:111]
	v_mfma_f32_16x16x32_bf16 v[104:107], v[136:139], v[200:203], v[104:107]
	v_mfma_f32_16x16x32_bf16 v[92:95], v[128:131], v[208:211], v[92:95]
	v_mfma_f32_16x16x32_bf16 v[88:91], v[136:139], v[208:211], v[88:91]
	v_mfma_f32_16x16x32_bf16 v[76:79], v[128:131], v[216:219], v[76:79]
	v_mfma_f32_16x16x32_bf16 v[72:75], v[136:139], v[216:219], v[72:75]
	v_mfma_f32_16x16x32_bf16 v[124:127], v[132:135], v[186:189], v[124:127]
	v_mfma_f32_16x16x32_bf16 v[120:123], v[140:143], v[186:189], v[120:123]
	v_mfma_f32_16x16x32_bf16 v[108:111], v[132:135], v[204:207], v[108:111]
	v_mfma_f32_16x16x32_bf16 v[104:107], v[140:143], v[204:207], v[104:107]
	v_mfma_f32_16x16x32_bf16 v[92:95], v[132:135], v[212:215], v[92:95]
	v_mfma_f32_16x16x32_bf16 v[88:91], v[140:143], v[212:215], v[88:91]
	v_mfma_f32_16x16x32_bf16 v[76:79], v[132:135], v[220:223], v[76:79]
	v_mfma_f32_16x16x32_bf16 v[72:75], v[140:143], v[220:223], v[72:75]
	v_mfma_f32_16x16x32_bf16 v[116:119], v[144:147], v[182:185], v[116:119]
	v_mfma_f32_16x16x32_bf16 v[112:115], v[174:177], v[182:185], v[112:115]
	v_mfma_f32_16x16x32_bf16 v[100:103], v[144:147], v[200:203], v[100:103]
	v_mfma_f32_16x16x32_bf16 v[96:99], v[174:177], v[200:203], v[96:99]
	v_mfma_f32_16x16x32_bf16 v[84:87], v[144:147], v[208:211], v[84:87]
	v_mfma_f32_16x16x32_bf16 v[80:83], v[174:177], v[208:211], v[80:83]
	v_mfma_f32_16x16x32_bf16 v[68:71], v[144:147], v[216:219], v[68:71]
	v_mfma_f32_16x16x32_bf16 v[64:67], v[174:177], v[216:219], v[64:67]
	v_mfma_f32_16x16x32_bf16 v[116:119], v[148:151], v[186:189], v[116:119]
	v_mfma_f32_16x16x32_bf16 v[112:115], v[178:181], v[186:189], v[112:115]
	v_mfma_f32_16x16x32_bf16 v[100:103], v[148:151], v[204:207], v[100:103]
	v_mfma_f32_16x16x32_bf16 v[96:99], v[178:181], v[204:207], v[96:99]
	v_mfma_f32_16x16x32_bf16 v[84:87], v[148:151], v[212:215], v[84:87]
	v_mfma_f32_16x16x32_bf16 v[80:83], v[178:181], v[212:215], v[80:83]
	v_mfma_f32_16x16x32_bf16 v[68:71], v[148:151], v[220:223], v[68:71]
	v_mfma_f32_16x16x32_bf16 v[64:67], v[178:181], v[220:223], v[64:67]
	s_barrier
	s_setprio 0
	s_add_u32 s54, s54, 0x100
	s_addc_u32 s55, s55, 0
	s_cmp_ge_i32 s56, s53
	s_mov_b64 s[18:19], s[20:21]
	s_mov_b32 s22, s56
	s_cbranch_scc0 .LBB0_1138
	s_and_b64 vcc, exec, s[10:11]
	s_cbranch_vccz .LBB0_1141
	s_barrier

; #define PG8_STAGE(bufoff, gbase, voff) do { _Pragma("unroll") for (int _i = 0; _i < 2; ++_i) \
;         __builtin_amdgcn_global_load_lds((const unsigned*)((const char*)(gbase) + (voff)[_i]), (PG8_LAS unsigned*)(lds + (bufoff) + ldsw + _i * 8192), 16, 0, 0); } while (0)
; #define PG8_LDA(dst, b, h) do { _Pragma("unroll") for (int m = 0; m < 4; ++m) _Pragma("unroll") for (int k = 0; k < 2; ++k) dst[m][k] = *(const PG8_LAS bf16x8*)(lds + PG8_SA(b, h) + aoff + m * 2048 + k * 1024); } while (0)
; #define PG8_LDB(dst, b, h) do { _Pragma("unroll") for (int n = 0; n < 2; ++n) _Pragma("unroll") for (int k = 0; k < 2; ++k) dst[n][k] = *(const PG8_LAS bf16x8*)(lds + PG8_SB(b, h) + boff + n * 2048 + k * 1024); } while (0)
; #define PG8_MMA(ai, bj, At, Bt) do { __builtin_amdgcn_s_setprio(1); _Pragma("unroll") for (int m = 0; m < 4; ++m) _Pragma("unroll") for (int n = 0; n < 2; ++n) _Pragma("unroll") for (int k = 0; k < 2; ++k) \
;         acc[ai][bj][m][n] = __builtin_amdgcn_mfma_f32_16x16x32_bf16(Bt[n][k], At[m][k], acc[ai][bj][m][n], 0, 0, 0); __builtin_amdgcn_s_setprio(0); } while (0)
; #define PG8_BAR __builtin_amdgcn_s_barrier()
; template <class Epi, class Sched, bool ALIGN_EPI = false, bool SP2 = false>
; __device__ __forceinline__ void gemm_phase(PG8_LAS unsigned char* lds, const Gemm g, const Sched& S, const Epi& E, const int wid) {
;     ...
;             PG8_LDB(B0, 0, 0); PG8_LDB(B1, 0, 1); PG8_SCHED; PG8_LDA(At, 0, 0); PG8_STAGE(PG8_SA(1, 1), a1 + hstep, voffA);
;             PG8_WAIT_V(8); PG8_WAIT_L(0); PG8_BAR; PG8_MMA(0, 0, At, B0); PG8_MMA(0, 1, At, B1); PG8_BAR; PG8_SCHED;
;             PG8_LDA(At, 0, 1); PG8_STAGE(PG8_SB(0, 0), b2, voffB); PG8_STAGE(PG8_SB(0, 1), b2 + hstep, voffB); PG8_STAGE(PG8_SA(0, 0), a2, voffA);
;             PG8_WAIT_V(8); PG8_WAIT_L(0); PG8_BAR; PG8_MMA(1, 0, At, B0); PG8_MMA(1, 1, At, B1); PG8_BAR; PG8_SCHED;
;             PG8_LDB(B0, 1, 0); PG8_LDB(B1, 1, 1); PG8_SCHED; PG8_LDA(At, 1, 0); PG8_STAGE(PG8_SA(0, 1), a2 + hstep, voffA);
;             PG8_WAIT_V(8); PG8_WAIT_L(0); PG8_BAR; PG8_MMA(0, 0, At, B0); PG8_MMA(0, 1, At, B1); PG8_BAR; PG8_SCHED;
;             PG8_LDA(At, 1, 1); PG8_STAGE(PG8_SB(1, 0), b3, voffB); PG8_STAGE(PG8_SB(1, 1), b3 + hstep, voffB); PG8_STAGE(PG8_SA(1, 0), a3, voffA);
;             PG8_WAIT_V(8); PG8_WAIT_L(0); PG8_BAR; PG8_MMA(1, 0, At, B0); PG8_MMA(1, 1, At, B1); PG8_BAR; PG8_SCHED;
.LBB0_1250:
	ds_read_b128 v[128:131], v175
	ds_read_b128 v[150:153], v175 offset:1024
	ds_read_b128 v[154:157], v175 offset:2048
	ds_read_b128 v[158:161], v175 offset:3072
	ds_read_b128 v[180:183], v176
	ds_read_b128 v[184:187], v176 offset:1024
	ds_read_b128 v[188:191], v176 offset:2048
	ds_read_b128 v[192:195], v176 offset:3072
	s_add_u32 s22, s20, 0xfff00080
	s_addc_u32 s23, s21, -1
	s_cmp_eq_u32 s60, 60
	s_cselect_b32 s25, s13, s23
	s_cselect_b32 s24, s19, s22
	s_cselect_b32 s23, s11, s59
	s_cselect_b32 s22, s57, s58
	v_lshl_add_u64 v[228:229], s[20:21], 0, v[142:143]
	s_add_i32 m0, s31, 0xc000
	ds_read_b128 v[196:199], v177
	ds_read_b128 v[200:203], v177 offset:1024
	ds_read_b128 v[204:207], v177 offset:2048
	ds_read_b128 v[208:211], v177 offset:3072
	ds_read_b128 v[212:215], v177 offset:4096
	ds_read_b128 v[216:219], v177 offset:5120
	ds_read_b128 v[220:223], v177 offset:6144
	ds_read_b128 v[224:227], v177 offset:7168
	global_load_lds_dwordx4 v[228:229], off
	v_lshl_add_u64 v[228:229], s[20:21], 0, v[144:145]
	s_add_i32 m0, s31, 0xe000
	s_nop 0
	global_load_lds_dwordx4 v[228:229], off
	s_waitcnt vmcnt(8)
	s_waitcnt lgkmcnt(0)
	s_setprio 1
	s_barrier
	v_mfma_f32_16x16x32_bf16 v[124:127], v[128:131], v[196:199], v[124:127]
	v_mfma_f32_16x16x32_bf16 v[116:119], v[154:157], v[196:199], v[116:119]
	v_mfma_f32_16x16x32_bf16 v[108:111], v[128:131], v[204:207], v[108:111]
	v_mfma_f32_16x16x32_bf16 v[100:103], v[154:157], v[204:207], v[100:103]
	v_mfma_f32_16x16x32_bf16 v[92:95], v[128:131], v[212:215], v[92:95]
	v_mfma_f32_16x16x32_bf16 v[84:87], v[154:157], v[212:215], v[84:87]
	v_mfma_f32_16x16x32_bf16 v[76:79], v[128:131], v[220:223], v[76:79]
	v_mfma_f32_16x16x32_bf16 v[68:71], v[154:157], v[220:223], v[68:71]
	v_mfma_f32_16x16x32_bf16 v[124:127], v[150:153], v[200:203], v[124:127]
	v_mfma_f32_16x16x32_bf16 v[116:119], v[158:161], v[200:203], v[116:119]
	v_mfma_f32_16x16x32_bf16 v[108:111], v[150:153], v[208:211], v[108:111]
	v_mfma_f32_16x16x32_bf16 v[100:103], v[158:161], v[208:211], v[100:103]
	v_mfma_f32_16x16x32_bf16 v[92:95], v[150:153], v[216:219], v[92:95]
	v_mfma_f32_16x16x32_bf16 v[84:87], v[158:161], v[216:219], v[84:87]
	v_mfma_f32_16x16x32_bf16 v[76:79], v[150:153], v[224:227], v[76:79]
	v_mfma_f32_16x16x32_bf16 v[68:71], v[158:161], v[224:227], v[68:71]
	v_mfma_f32_16x16x32_bf16 v[120:123], v[180:183], v[196:199], v[120:123]
	v_mfma_f32_16x16x32_bf16 v[112:115], v[188:191], v[196:199], v[112:115]
	v_mfma_f32_16x16x32_bf16 v[104:107], v[180:183], v[204:207], v[104:107]
	v_mfma_f32_16x16x32_bf16 v[96:99], v[188:191], v[204:207], v[96:99]
	v_mfma_f32_16x16x32_bf16 v[88:91], v[180:183], v[212:215], v[88:91]
	v_mfma_f32_16x16x32_bf16 v[80:83], v[188:191], v[212:215], v[80:83]
	v_mfma_f32_16x16x32_bf16 v[72:75], v[180:183], v[220:223], v[72:75]
	v_mfma_f32_16x16x32_bf16 v[64:67], v[188:191], v[220:223], v[64:67]
	v_mfma_f32_16x16x32_bf16 v[120:123], v[184:187], v[200:203], v[120:123]
	v_mfma_f32_16x16x32_bf16 v[112:115], v[192:195], v[200:203], v[112:115]
	v_mfma_f32_16x16x32_bf16 v[104:107], v[184:187], v[208:211], v[104:107]
	v_mfma_f32_16x16x32_bf16 v[96:99], v[192:195], v[208:211], v[96:99]
	v_mfma_f32_16x16x32_bf16 v[88:91], v[184:187], v[216:219], v[88:91]
	v_mfma_f32_16x16x32_bf16 v[80:83], v[192:195], v[216:219], v[80:83]
	v_mfma_f32_16x16x32_bf16 v[72:75], v[184:187], v[224:227], v[72:75]
	v_mfma_f32_16x16x32_bf16 v[64:67], v[192:195], v[224:227], v[64:67]
	s_barrier
	s_setprio 0
	s_add_i32 s61, s42, s28
	v_lshl_add_u64 v[228:229], s[22:23], 0, v[136:137]
	s_mov_b32 m0, s61
	ds_read_b128 v[196:199], v177 offset:16384
	ds_read_b128 v[200:203], v177 offset:17408
	ds_read_b128 v[204:207], v177 offset:18432
	ds_read_b128 v[208:211], v177 offset:19456
	ds_read_b128 v[212:215], v177 offset:20480
	ds_read_b128 v[216:219], v177 offset:21504
	ds_read_b128 v[220:223], v177 offset:22528
	ds_read_b128 v[224:227], v177 offset:23552
	global_load_lds_dwordx4 v[228:229], off
	s_add_i32 m0, s61, 0x2000
	s_add_u32 s62, s22, 0x100000
	v_lshl_add_u64 v[230:231], s[22:23], 0, v[132:133]
	s_addc_u32 s63, s23, 0
	s_add_i32 s61, s43, s28
	global_load_lds_dwordx4 v[230:231], off
	v_lshl_add_u64 v[232:233], s[62:63], 0, v[136:137]
	s_mov_b32 m0, s61
	v_lshl_add_u64 v[234:235], s[24:25], 0, v[134:135]
	global_load_lds_dwordx4 v[232:233], off
	v_lshl_add_u64 v[232:233], s[62:63], 0, v[132:133]
	s_add_i32 m0, s61, 0x2000
	s_nop 0
	global_load_lds_dwordx4 v[232:233], off
	v_lshl_add_u64 v[232:233], s[24:25], 0, v[138:139]
	s_mov_b32 m0, s31
	s_nop 0
	global_load_lds_dwordx4 v[232:233], off
	s_mov_b32 m0, s34
	s_nop 0
	global_load_lds_dwordx4 v[234:235], off
	s_waitcnt vmcnt(8)
	s_waitcnt lgkmcnt(0)
	s_setprio 1
	s_barrier
; #define PG8_STAGE(bufoff, gbase, voff) do { _Pragma("unroll") for (int _i = 0; _i < 2; ++_i) \
;         __builtin_amdgcn_global_load_lds((const unsigned*)((const char*)(gbase) + (voff)[_i]), (PG8_LAS unsigned*)(lds + (bufoff) + ldsw + _i * 8192), 16, 0, 0); } while (0)
; #define PG8_LDA(dst, b, h) do { _Pragma("unroll") for (int m = 0; m < 4; ++m) _Pragma("unroll") for (int k = 0; k < 2; ++k) dst[m][k] = *(const PG8_LAS bf16x8*)(lds + PG8_SA(b, h) + aoff + m * 2048 + k * 1024); } while (0)
; #define PG8_LDB(dst, b, h) do { _Pragma("unroll") for (int n = 0; n < 2; ++n) _Pragma("unroll") for (int k = 0; k < 2; ++k) dst[n][k] = *(const PG8_LAS bf16x8*)(lds + PG8_SB(b, h) + boff + n * 2048 + k * 1024); } while (0)
; #define PG8_MMA(ai, bj, At, Bt) do { __builtin_amdgcn_s_setprio(1); _Pragma("unroll") for (int m = 0; m < 4; ++m) _Pragma("unroll") for (int n = 0; n < 2; ++n) _Pragma("unroll") for (int k = 0; k < 2; ++k) \
;         acc[ai][bj][m][n] = __builtin_amdgcn_mfma_f32_16x16x32_bf16(Bt[n][k], At[m][k], acc[ai][bj][m][n], 0, 0, 0); __builtin_amdgcn_s_setprio(0); } while (0)
; #define PG8_BAR __builtin_amdgcn_s_barrier()
; template <class Epi, class Sched, bool ALIGN_EPI = false, bool SP2 = false>
; __device__ __forceinline__ void gemm_phase(PG8_LAS unsigned char* lds, const Gemm g, const Sched& S, const Epi& E, const int wid) {
;     ...
;             PG8_LDB(B0, 0, 0); PG8_LDB(B1, 0, 1); PG8_SCHED; PG8_LDA(At, 0, 0); PG8_STAGE(PG8_SA(1, 1), a1 + hstep, voffA);
;             PG8_WAIT_V(8); PG8_WAIT_L(0); PG8_BAR; PG8_MMA(0, 0, At, B0); PG8_MMA(0, 1, At, B1); PG8_BAR; PG8_SCHED;
;             PG8_LDA(At, 0, 1); PG8_STAGE(PG8_SB(0, 0), b2, voffB); PG8_STAGE(PG8_SB(0, 1), b2 + hstep, voffB); PG8_STAGE(PG8_SA(0, 0), a2, voffA);
;             PG8_WAIT_V(8); PG8_WAIT_L(0); PG8_BAR; PG8_MMA(1, 0, At, B0); PG8_MMA(1, 1, At, B1); PG8_BAR; PG8_SCHED;
;             PG8_LDB(B0, 1, 0); PG8_LDB(B1, 1, 1); PG8_SCHED; PG8_LDA(At, 1, 0); PG8_STAGE(PG8_SA(0, 1), a2 + hstep, voffA);
;             PG8_WAIT_V(8); PG8_WAIT_L(0); PG8_BAR; PG8_MMA(0, 0, At, B0); PG8_MMA(0, 1, At, B1); PG8_BAR; PG8_SCHED;
;             PG8_LDA(At, 1, 1); PG8_STAGE(PG8_SB(1, 0), b3, voffB); PG8_STAGE(PG8_SB(1, 1), b3 + hstep, voffB); PG8_STAGE(PG8_SA(1, 0), a3, voffA);
;             PG8_WAIT_V(8); PG8_WAIT_L(0); PG8_BAR; PG8_MMA(1, 0, At, B0); PG8_MMA(1, 1, At, B1); PG8_BAR; PG8_SCHED;
	v_mfma_f32_16x16x32_bf16 v[60:63], v[128:131], v[196:199], v[60:63]
	v_mfma_f32_16x16x32_bf16 v[52:55], v[154:157], v[196:199], v[52:55]
	v_mfma_f32_16x16x32_bf16 v[44:47], v[128:131], v[204:207], v[44:47]
	v_mfma_f32_16x16x32_bf16 v[36:39], v[154:157], v[204:207], v[36:39]
	v_mfma_f32_16x16x32_bf16 v[28:31], v[128:131], v[212:215], v[28:31]
	v_mfma_f32_16x16x32_bf16 v[20:23], v[154:157], v[212:215], v[20:23]
	v_mfma_f32_16x16x32_bf16 v[12:15], v[128:131], v[220:223], v[12:15]
	v_mfma_f32_16x16x32_bf16 v[4:7], v[154:157], v[220:223], v[4:7]
	v_mfma_f32_16x16x32_bf16 v[60:63], v[150:153], v[200:203], v[60:63]
	v_mfma_f32_16x16x32_bf16 v[52:55], v[158:161], v[200:203], v[52:55]
	v_mfma_f32_16x16x32_bf16 v[44:47], v[150:153], v[208:211], v[44:47]
	v_mfma_f32_16x16x32_bf16 v[36:39], v[158:161], v[208:211], v[36:39]
	v_mfma_f32_16x16x32_bf16 v[28:31], v[150:153], v[216:219], v[28:31]
	v_mfma_f32_16x16x32_bf16 v[20:23], v[158:161], v[216:219], v[20:23]
	v_mfma_f32_16x16x32_bf16 v[12:15], v[150:153], v[224:227], v[12:15]
	v_mfma_f32_16x16x32_bf16 v[4:7], v[158:161], v[224:227], v[4:7]
	v_mfma_f32_16x16x32_bf16 v[56:59], v[180:183], v[196:199], v[56:59]
	v_mfma_f32_16x16x32_bf16 v[48:51], v[188:191], v[196:199], v[48:51]
	v_mfma_f32_16x16x32_bf16 v[40:43], v[180:183], v[204:207], v[40:43]
	v_mfma_f32_16x16x32_bf16 v[32:35], v[188:191], v[204:207], v[32:35]
	v_mfma_f32_16x16x32_bf16 v[24:27], v[180:183], v[212:215], v[24:27]
	v_mfma_f32_16x16x32_bf16 v[16:19], v[188:191], v[212:215], v[16:19]
	v_mfma_f32_16x16x32_bf16 v[8:11], v[180:183], v[220:223], v[8:11]
	v_mfma_f32_16x16x32_bf16 v[0:3], v[188:191], v[220:223], v[0:3]
	v_mfma_f32_16x16x32_bf16 v[56:59], v[184:187], v[200:203], v[56:59]
	v_mfma_f32_16x16x32_bf16 v[48:51], v[192:195], v[200:203], v[48:51]
	v_mfma_f32_16x16x32_bf16 v[40:43], v[184:187], v[208:211], v[40:43]
	v_mfma_f32_16x16x32_bf16 v[32:35], v[192:195], v[208:211], v[32:35]
	v_mfma_f32_16x16x32_bf16 v[24:27], v[184:187], v[216:219], v[24:27]
	v_mfma_f32_16x16x32_bf16 v[16:19], v[192:195], v[216:219], v[16:19]
	v_mfma_f32_16x16x32_bf16 v[8:11], v[184:187], v[224:227], v[8:11]
	v_mfma_f32_16x16x32_bf16 v[0:3], v[192:195], v[224:227], v[0:3]
	s_barrier
	s_setprio 0
	s_add_i32 s61, 0, 0x18000
	v_add_u32_e32 v140, s61, v165
	s_add_i32 s62, 0, 0x1c000
	ds_read_b128 v[128:131], v140
	ds_read_b128 v[150:153], v140 offset:1024
	ds_read_b128 v[154:157], v140 offset:2048
	ds_read_b128 v[158:161], v140 offset:3072
	v_add_u32_e32 v140, s62, v165
	ds_read_b128 v[180:183], v140
	ds_read_b128 v[184:187], v140 offset:1024
	ds_read_b128 v[188:191], v140 offset:2048
	ds_read_b128 v[192:195], v140 offset:3072
	s_add_u32 s24, s24, 0x100000
	s_addc_u32 s25, s25, 0
	s_mov_b32 m0, s35
	v_lshl_add_u64 v[236:237], s[24:25], 0, v[138:139]
	ds_read_b128 v[196:199], v177 offset:32768
	ds_read_b128 v[200:203], v177 offset:33792
	ds_read_b128 v[204:207], v177 offset:34816
	ds_read_b128 v[208:211], v177 offset:35840
	ds_read_b128 v[212:215], v177 offset:36864
	ds_read_b128 v[216:219], v177 offset:37888
	ds_read_b128 v[220:223], v177 offset:38912
	ds_read_b128 v[224:227], v177 offset:39936
	global_load_lds_dwordx4 v[236:237], off
	v_lshl_add_u64 v[236:237], s[24:25], 0, v[134:135]
	s_mov_b32 m0, s36
	s_nop 0
	global_load_lds_dwordx4 v[236:237], off
	s_waitcnt vmcnt(8)
	s_waitcnt lgkmcnt(0)
	s_setprio 1
	s_barrier
	v_mfma_f32_16x16x32_bf16 v[124:127], v[128:131], v[196:199], v[124:127]
	v_mfma_f32_16x16x32_bf16 v[116:119], v[154:157], v[196:199], v[116:119]
	v_mfma_f32_16x16x32_bf16 v[108:111], v[128:131], v[204:207], v[108:111]
	v_mfma_f32_16x16x32_bf16 v[100:103], v[154:157], v[204:207], v[100:103]
	v_mfma_f32_16x16x32_bf16 v[92:95], v[128:131], v[212:215], v[92:95]
	v_mfma_f32_16x16x32_bf16 v[84:87], v[154:157], v[212:215], v[84:87]
	v_mfma_f32_16x16x32_bf16 v[76:79], v[128:131], v[220:223], v[76:79]
	v_mfma_f32_16x16x32_bf16 v[68:71], v[154:157], v[220:223], v[68:71]
	v_mfma_f32_16x16x32_bf16 v[124:127], v[150:153], v[200:203], v[124:127]
	v_mfma_f32_16x16x32_bf16 v[116:119], v[158:161], v[200:203], v[116:119]
	v_mfma_f32_16x16x32_bf16 v[108:111], v[150:153], v[208:211], v[108:111]
	v_mfma_f32_16x16x32_bf16 v[100:103], v[158:161], v[208:211], v[100:103]
	v_mfma_f32_16x16x32_bf16 v[92:95], v[150:153], v[216:219], v[92:95]
	v_mfma_f32_16x16x32_bf16 v[84:87], v[158:161], v[216:219], v[84:87]
	v_mfma_f32_16x16x32_bf16 v[76:79], v[150:153], v[224:227], v[76:79]
	v_mfma_f32_16x16x32_bf16 v[68:71], v[158:161], v[224:227], v[68:71]
	v_mfma_f32_16x16x32_bf16 v[120:123], v[180:183], v[196:199], v[120:123]
	v_mfma_f32_16x16x32_bf16 v[112:115], v[188:191], v[196:199], v[112:115]
	v_mfma_f32_16x16x32_bf16 v[104:107], v[180:183], v[204:207], v[104:107]
	v_mfma_f32_16x16x32_bf16 v[96:99], v[188:191], v[204:207], v[96:99]
	v_mfma_f32_16x16x32_bf16 v[88:91], v[180:183], v[212:215], v[88:91]
	v_mfma_f32_16x16x32_bf16 v[80:83], v[188:191], v[212:215], v[80:83]
	v_mfma_f32_16x16x32_bf16 v[72:75], v[180:183], v[220:223], v[72:75]
	v_mfma_f32_16x16x32_bf16 v[64:67], v[188:191], v[220:223], v[64:67]
	v_mfma_f32_16x16x32_bf16 v[120:123], v[184:187], v[200:203], v[120:123]
	v_mfma_f32_16x16x32_bf16 v[112:115], v[192:195], v[200:203], v[112:115]
	v_mfma_f32_16x16x32_bf16 v[104:107], v[184:187], v[208:211], v[104:107]
	v_mfma_f32_16x16x32_bf16 v[96:99], v[192:195], v[208:211], v[96:99]
	v_mfma_f32_16x16x32_bf16 v[88:91], v[184:187], v[216:219], v[88:91]
	v_mfma_f32_16x16x32_bf16 v[80:83], v[192:195], v[216:219], v[80:83]
	v_mfma_f32_16x16x32_bf16 v[72:75], v[184:187], v[224:227], v[72:75]
	v_mfma_f32_16x16x32_bf16 v[64:67], v[192:195], v[224:227], v[64:67]
	s_barrier
; #define PG8_STAGE(bufoff, gbase, voff) do { _Pragma("unroll") for (int _i = 0; _i < 2; ++_i) \
;         __builtin_amdgcn_global_load_lds((const unsigned*)((const char*)(gbase) + (voff)[_i]), (PG8_LAS unsigned*)(lds + (bufoff) + ldsw + _i * 8192), 16, 0, 0); } while (0)
; #define PG8_LDA(dst, b, h) do { _Pragma("unroll") for (int m = 0; m < 4; ++m) _Pragma("unroll") for (int k = 0; k < 2; ++k) dst[m][k] = *(const PG8_LAS bf16x8*)(lds + PG8_SA(b, h) + aoff + m * 2048 + k * 1024); } while (0)
; #define PG8_WAIT_V(n) asm volatile("s_waitcnt vmcnt(" #n ")" ::: "memory")
; #define PG8_WAIT_L(n) asm volatile("s_waitcnt lgkmcnt(" #n ")" ::: "memory")
; #define PG8_BAR __builtin_amdgcn_s_barrier()
; template <class Epi, class Sched, bool ALIGN_EPI = false, bool SP2 = false>
; __device__ __forceinline__ void gemm_phase(PG8_LAS unsigned char* lds, const Gemm g, const Sched& S, const Epi& E, const int wid) {
;     ...
;         for (int t = 0; t < nt; t += 2) {
;             const bool last = (t == nt - 2);
;             const char* a1 = cA + (size_t)(t + 1) * kstep;
;             const char* a2 = last ? nA : cA + (size_t)(t + 2) * kstep; const char* b2 = last ? nB : cB + (size_t)(t + 2) * kstep;
;             const char* a3 = a2 + kstep; const char* b3 = b2 + kstep;
;             if (last && has_next) S.a_ready(nxt);
;             if constexpr (SP2) {
;             PG8_LDB(B0, 0, 0); PG8_LDB(B1, 0, 1); PG8_SCHED; PG8_LDA(At, 0, 0); PG8_STAGE(PG8_SA(1, 1), a1 + hstep, voffA);
;             PG8_WAIT_V(8); PG8_WAIT_L(0); PG8_BAR; PG8_MMA(0, 0, At, B0); PG8_MMA(0, 1, At, B1); PG8_BAR; PG8_SCHED;
;             PG8_LDA(At, 0, 1); PG8_STAGE(PG8_SB(0, 0), b2, voffB); PG8_STAGE(PG8_SB(0, 1), b2 + hstep, voffB); PG8_STAGE(PG8_SA(0, 0), a2, voffA);
;             PG8_WAIT_V(8); PG8_WAIT_L(0); PG8_BAR; PG8_MMA(1, 0, At, B0); PG8_MMA(1, 1, At, B1); PG8_BAR; PG8_SCHED;
;             PG8_LDB(B0, 1, 0); PG8_LDB(B1, 1, 1); PG8_SCHED; PG8_LDA(At, 1, 0); PG8_STAGE(PG8_SA(0, 1), a2 + hstep, voffA);
;             PG8_WAIT_V(8); PG8_WAIT_L(0); PG8_BAR; PG8_MMA(0, 0, At, B0); PG8_MMA(0, 1, At, B1); PG8_BAR; PG8_SCHED;
;             PG8_LDA(At, 1, 1); PG8_STAGE(PG8_SB(1, 0), b3, voffB); PG8_STAGE(PG8_SB(1, 1), b3 + hstep, voffB); PG8_STAGE(PG8_SA(1, 0), a3, voffA);
;             PG8_WAIT_V(8); PG8_WAIT_L(0); PG8_BAR; PG8_MMA(1, 0, At, B0); PG8_MMA(1, 1, At, B1); PG8_BAR; PG8_SCHED;
	s_setprio 0
	s_add_i32 s24, s61, s28
	v_lshl_add_u64 v[228:229], v[228:229], 0, s[6:7]
	s_mov_b32 m0, s24
	ds_read_b128 v[196:199], v177 offset:49152
	ds_read_b128 v[200:203], v177 offset:50176
	ds_read_b128 v[204:207], v177 offset:51200
	ds_read_b128 v[208:211], v177 offset:52224
	ds_read_b128 v[212:215], v177 offset:53248
	ds_read_b128 v[216:219], v177 offset:54272
	ds_read_b128 v[220:223], v177 offset:55296
	ds_read_b128 v[224:227], v177 offset:56320
	global_load_lds_dwordx4 v[228:229], off
	s_add_i32 m0, s24, 0x2000
	s_add_u32 s22, s22, 0x100080
	v_lshl_add_u64 v[228:229], v[230:231], 0, s[6:7]
	s_addc_u32 s23, s23, 0
	s_add_i32 s24, s62, s28
	global_load_lds_dwordx4 v[228:229], off
	v_lshl_add_u64 v[228:229], s[22:23], 0, v[136:137]
	s_mov_b32 m0, s24
	s_nop 0
	global_load_lds_dwordx4 v[228:229], off
	v_lshl_add_u64 v[228:229], s[22:23], 0, v[132:133]
	s_add_i32 m0, s24, 0x2000
	s_nop 0
	global_load_lds_dwordx4 v[228:229], off
	v_lshl_add_u64 v[228:229], v[232:233], 0, s[6:7]
	s_mov_b32 m0, s38
	s_nop 0
	global_load_lds_dwordx4 v[228:229], off
	v_lshl_add_u64 v[228:229], v[234:235], 0, s[6:7]
	s_mov_b32 m0, s39
	s_nop 0
	global_load_lds_dwordx4 v[228:229], off
	s_waitcnt vmcnt(8)
	s_waitcnt lgkmcnt(0)
	s_setprio 1
	s_barrier
	v_mfma_f32_16x16x32_bf16 v[60:63], v[128:131], v[196:199], v[60:63]
	v_mfma_f32_16x16x32_bf16 v[52:55], v[154:157], v[196:199], v[52:55]
	v_mfma_f32_16x16x32_bf16 v[44:47], v[128:131], v[204:207], v[44:47]
	v_mfma_f32_16x16x32_bf16 v[36:39], v[154:157], v[204:207], v[36:39]
	v_mfma_f32_16x16x32_bf16 v[28:31], v[128:131], v[212:215], v[28:31]
	v_mfma_f32_16x16x32_bf16 v[20:23], v[154:157], v[212:215], v[20:23]
	v_mfma_f32_16x16x32_bf16 v[12:15], v[128:131], v[220:223], v[12:15]
	v_mfma_f32_16x16x32_bf16 v[4:7], v[154:157], v[220:223], v[4:7]
	v_mfma_f32_16x16x32_bf16 v[60:63], v[150:153], v[200:203], v[60:63]
	v_mfma_f32_16x16x32_bf16 v[52:55], v[158:161], v[200:203], v[52:55]
	v_mfma_f32_16x16x32_bf16 v[44:47], v[150:153], v[208:211], v[44:47]
	v_mfma_f32_16x16x32_bf16 v[36:39], v[158:161], v[208:211], v[36:39]
	v_mfma_f32_16x16x32_bf16 v[28:31], v[150:153], v[216:219], v[28:31]
	v_mfma_f32_16x16x32_bf16 v[20:23], v[158:161], v[216:219], v[20:23]
	v_mfma_f32_16x16x32_bf16 v[12:15], v[150:153], v[224:227], v[12:15]
	v_mfma_f32_16x16x32_bf16 v[4:7], v[158:161], v[224:227], v[4:7]
	v_mfma_f32_16x16x32_bf16 v[56:59], v[180:183], v[196:199], v[56:59]
	v_mfma_f32_16x16x32_bf16 v[48:51], v[188:191], v[196:199], v[48:51]
	v_mfma_f32_16x16x32_bf16 v[40:43], v[180:183], v[204:207], v[40:43]
	v_mfma_f32_16x16x32_bf16 v[32:35], v[188:191], v[204:207], v[32:35]
	v_mfma_f32_16x16x32_bf16 v[24:27], v[180:183], v[212:215], v[24:27]
	v_mfma_f32_16x16x32_bf16 v[16:19], v[188:191], v[212:215], v[16:19]
	v_mfma_f32_16x16x32_bf16 v[8:11], v[180:183], v[220:223], v[8:11]
	v_mfma_f32_16x16x32_bf16 v[0:3], v[188:191], v[220:223], v[0:3]
	v_mfma_f32_16x16x32_bf16 v[56:59], v[184:187], v[200:203], v[56:59]
	v_mfma_f32_16x16x32_bf16 v[48:51], v[192:195], v[200:203], v[48:51]
	v_mfma_f32_16x16x32_bf16 v[40:43], v[184:187], v[208:211], v[40:43]
	v_mfma_f32_16x16x32_bf16 v[32:35], v[192:195], v[208:211], v[32:35]
	v_mfma_f32_16x16x32_bf16 v[24:27], v[184:187], v[216:219], v[24:27]
	v_mfma_f32_16x16x32_bf16 v[16:19], v[192:195], v[216:219], v[16:19]
	v_mfma_f32_16x16x32_bf16 v[8:11], v[184:187], v[224:227], v[8:11]
	v_mfma_f32_16x16x32_bf16 v[0:3], v[192:195], v[224:227], v[0:3]
	s_barrier
	s_setprio 0
	s_add_i32 s60, s60, 2
	s_add_u32 s20, s20, 0x100
	s_addc_u32 s21, s21, 0
	s_add_u32 s58, s58, 0x100
	s_addc_u32 s59, s59, 0
	s_cmp_gt_u32 s60, 61
	s_cbranch_scc0 .LBB0_1250
	s_and_b64 vcc, exec, s[8:9]
	s_cbranch_vccz .LBB0_1253
	s_barrier

; #define PG8_STAGE(bufoff, gbase, voff) do { _Pragma("unroll") for (int _i = 0; _i < 2; ++_i) \
;         __builtin_amdgcn_global_load_lds((const unsigned*)((const char*)(gbase) + (voff)[_i]), (PG8_LAS unsigned*)(lds + (bufoff) + ldsw + _i * 8192), 16, 0, 0); } while (0)
; #define PG8_LDA(dst, b, h) do { _Pragma("unroll") for (int m = 0; m < 4; ++m) _Pragma("unroll") for (int k = 0; k < 2; ++k) dst[m][k] = *(const PG8_LAS bf16x8*)(lds + PG8_SA(b, h) + aoff + m * 2048 + k * 1024); } while (0)
; #define PG8_LDB(dst, b, h) do { _Pragma("unroll") for (int n = 0; n < 2; ++n) _Pragma("unroll") for (int k = 0; k < 2; ++k) dst[n][k] = *(const PG8_LAS bf16x8*)(lds + PG8_SB(b, h) + boff + n * 2048 + k * 1024); } while (0)
; #define PG8_MMA(ai, bj, At, Bt) do { __builtin_amdgcn_s_setprio(1); _Pragma("unroll") for (int m = 0; m < 4; ++m) _Pragma("unroll") for (int n = 0; n < 2; ++n) _Pragma("unroll") for (int k = 0; k < 2; ++k) \
;         acc[ai][bj][m][n] = __builtin_amdgcn_mfma_f32_16x16x32_bf16(Bt[n][k], At[m][k], acc[ai][bj][m][n], 0, 0, 0); __builtin_amdgcn_s_setprio(0); } while (0)
; #define PG8_BAR __builtin_amdgcn_s_barrier()
; template <class Epi, class Sched, bool ALIGN_EPI = false, bool SP2 = false>
; __device__ __forceinline__ void gemm_phase(PG8_LAS unsigned char* lds, const Gemm g, const Sched& S, const Epi& E, const int wid) {
;     ...
;             PG8_LDB(B0, 0, 0); PG8_LDB(B1, 0, 1); PG8_SCHED; PG8_LDA(At, 0, 0); PG8_STAGE(PG8_SA(1, 1), a1 + hstep, voffA);
;             PG8_WAIT_V(8); PG8_WAIT_L(0); PG8_BAR; PG8_MMA(0, 0, At, B0); PG8_MMA(0, 1, At, B1); PG8_BAR; PG8_SCHED;
;             PG8_LDA(At, 0, 1); PG8_STAGE(PG8_SB(0, 0), b2, voffB); PG8_STAGE(PG8_SB(0, 1), b2 + hstep, voffB); PG8_STAGE(PG8_SA(0, 0), a2, voffA);
;             PG8_WAIT_V(8); PG8_WAIT_L(0); PG8_BAR; PG8_MMA(1, 0, At, B0); PG8_MMA(1, 1, At, B1); PG8_BAR; PG8_SCHED;
;             PG8_LDB(B0, 1, 0); PG8_LDB(B1, 1, 1); PG8_SCHED; PG8_LDA(At, 1, 0); PG8_STAGE(PG8_SA(0, 1), a2 + hstep, voffA);
;             PG8_WAIT_V(8); PG8_WAIT_L(0); PG8_BAR; PG8_MMA(0, 0, At, B0); PG8_MMA(0, 1, At, B1); PG8_BAR; PG8_SCHED;
;             PG8_LDA(At, 1, 1); PG8_STAGE(PG8_SB(1, 0), b3, voffB); PG8_STAGE(PG8_SB(1, 1), b3 + hstep, voffB); PG8_STAGE(PG8_SA(1, 0), a3, voffA);
;             PG8_WAIT_V(8); PG8_WAIT_L(0); PG8_BAR; PG8_MMA(1, 0, At, B0); PG8_MMA(1, 1, At, B1); PG8_BAR; PG8_SCHED;
.LBB0_1671:
	ds_read_b128 v[128:131], v197
	ds_read_b128 v[132:135], v197 offset:1024
	ds_read_b128 v[136:139], v197 offset:2048
	ds_read_b128 v[140:143], v197 offset:3072
	ds_read_b128 v[144:147], v198
	ds_read_b128 v[148:151], v198 offset:1024
	ds_read_b128 v[176:179], v198 offset:2048
	ds_read_b128 v[180:183], v198 offset:3072
	s_add_u32 s26, s24, 0xffe00080
	s_addc_u32 s27, s25, -1
	s_cmpk_eq_i32 s50, 0x7c
	s_cselect_b32 s29, s15, s27
	s_cselect_b32 s28, s21, s26
	s_cselect_b32 s27, s13, s49
	s_cselect_b32 s26, s23, s48
	v_lshl_add_u64 v[192:193], s[24:25], 0, v[168:169]
	s_add_i32 m0, s35, 0xc000
	ds_read_b128 v[184:187], v199
	ds_read_b128 v[188:191], v199 offset:1024
	ds_read_b128 v[200:203], v199 offset:2048
	ds_read_b128 v[204:207], v199 offset:3072
	ds_read_b128 v[208:211], v199 offset:4096
	ds_read_b128 v[212:215], v199 offset:5120
	ds_read_b128 v[216:219], v199 offset:6144
	ds_read_b128 v[220:223], v199 offset:7168
	global_load_lds_dwordx4 v[192:193], off
	v_lshl_add_u64 v[192:193], s[24:25], 0, v[170:171]
	s_add_i32 m0, s35, 0xe000
	s_nop 0
	global_load_lds_dwordx4 v[192:193], off
	s_waitcnt vmcnt(8)
	s_waitcnt lgkmcnt(0)
	s_setprio 1
	s_barrier
	v_mfma_f32_16x16x32_bf16 v[60:63], v[128:131], v[184:187], v[60:63]
	v_mfma_f32_16x16x32_bf16 v[56:59], v[136:139], v[184:187], v[56:59]
	v_mfma_f32_16x16x32_bf16 v[44:47], v[128:131], v[200:203], v[44:47]
	v_mfma_f32_16x16x32_bf16 v[40:43], v[136:139], v[200:203], v[40:43]
	v_mfma_f32_16x16x32_bf16 v[28:31], v[128:131], v[208:211], v[28:31]
	v_mfma_f32_16x16x32_bf16 v[24:27], v[136:139], v[208:211], v[24:27]
	v_mfma_f32_16x16x32_bf16 v[12:15], v[128:131], v[216:219], v[12:15]
	v_mfma_f32_16x16x32_bf16 v[8:11], v[136:139], v[216:219], v[8:11]
	v_mfma_f32_16x16x32_bf16 v[60:63], v[132:135], v[188:191], v[60:63]
	v_mfma_f32_16x16x32_bf16 v[56:59], v[140:143], v[188:191], v[56:59]
	v_mfma_f32_16x16x32_bf16 v[44:47], v[132:135], v[204:207], v[44:47]
	v_mfma_f32_16x16x32_bf16 v[40:43], v[140:143], v[204:207], v[40:43]
	v_mfma_f32_16x16x32_bf16 v[28:31], v[132:135], v[212:215], v[28:31]
	v_mfma_f32_16x16x32_bf16 v[24:27], v[140:143], v[212:215], v[24:27]
	v_mfma_f32_16x16x32_bf16 v[12:15], v[132:135], v[220:223], v[12:15]
	v_mfma_f32_16x16x32_bf16 v[8:11], v[140:143], v[220:223], v[8:11]
	v_mfma_f32_16x16x32_bf16 v[52:55], v[144:147], v[184:187], v[52:55]
	v_mfma_f32_16x16x32_bf16 v[48:51], v[176:179], v[184:187], v[48:51]
	v_mfma_f32_16x16x32_bf16 v[36:39], v[144:147], v[200:203], v[36:39]
	v_mfma_f32_16x16x32_bf16 v[32:35], v[176:179], v[200:203], v[32:35]
	v_mfma_f32_16x16x32_bf16 v[20:23], v[144:147], v[208:211], v[20:23]
	v_mfma_f32_16x16x32_bf16 v[16:19], v[176:179], v[208:211], v[16:19]
	v_mfma_f32_16x16x32_bf16 v[4:7], v[144:147], v[216:219], v[4:7]
	v_mfma_f32_16x16x32_bf16 v[0:3], v[176:179], v[216:219], v[0:3]
	v_mfma_f32_16x16x32_bf16 v[52:55], v[148:151], v[188:191], v[52:55]
	v_mfma_f32_16x16x32_bf16 v[48:51], v[180:183], v[188:191], v[48:51]
	v_mfma_f32_16x16x32_bf16 v[36:39], v[148:151], v[204:207], v[36:39]
	v_mfma_f32_16x16x32_bf16 v[32:35], v[180:183], v[204:207], v[32:35]
	v_mfma_f32_16x16x32_bf16 v[20:23], v[148:151], v[212:215], v[20:23]
	v_mfma_f32_16x16x32_bf16 v[16:19], v[180:183], v[212:215], v[16:19]
	v_mfma_f32_16x16x32_bf16 v[4:7], v[148:151], v[220:223], v[4:7]
	v_mfma_f32_16x16x32_bf16 v[0:3], v[180:183], v[220:223], v[0:3]
	s_barrier
	s_setprio 0
	s_add_i32 s51, s44, s34
	v_lshl_add_u64 v[192:193], s[26:27], 0, v[154:155]
	s_mov_b32 m0, s51
	ds_read_b128 v[184:187], v199 offset:16384
	ds_read_b128 v[188:191], v199 offset:17408
	ds_read_b128 v[200:203], v199 offset:18432
	ds_read_b128 v[204:207], v199 offset:19456
	ds_read_b128 v[208:211], v199 offset:20480
	ds_read_b128 v[212:215], v199 offset:21504
	ds_read_b128 v[216:219], v199 offset:22528
	ds_read_b128 v[220:223], v199 offset:23552
	global_load_lds_dwordx4 v[192:193], off
	s_add_i32 m0, s51, 0x2000
	s_add_u32 s52, s26, 0x200000
	v_lshl_add_u64 v[224:225], s[26:27], 0, v[158:159]
	s_addc_u32 s53, s27, 0
	s_add_i32 s51, s45, s34
	global_load_lds_dwordx4 v[224:225], off
	v_lshl_add_u64 v[226:227], s[52:53], 0, v[154:155]
	s_mov_b32 m0, s51
	v_lshl_add_u64 v[228:229], s[28:29], 0, v[156:157]
	global_load_lds_dwordx4 v[226:227], off
	v_lshl_add_u64 v[226:227], s[52:53], 0, v[158:159]
	s_add_i32 m0, s51, 0x2000
	s_nop 0
	global_load_lds_dwordx4 v[226:227], off
	v_lshl_add_u64 v[226:227], s[28:29], 0, v[152:153]
	s_mov_b32 m0, s35
	s_nop 0
	global_load_lds_dwordx4 v[226:227], off
	s_mov_b32 m0, s36
	s_nop 0
	global_load_lds_dwordx4 v[228:229], off
	s_waitcnt vmcnt(8)
	s_waitcnt lgkmcnt(0)
	s_setprio 1
	s_barrier
; #define PG8_STAGE(bufoff, gbase, voff) do { _Pragma("unroll") for (int _i = 0; _i < 2; ++_i) \
;         __builtin_amdgcn_global_load_lds((const unsigned*)((const char*)(gbase) + (voff)[_i]), (PG8_LAS unsigned*)(lds + (bufoff) + ldsw + _i * 8192), 16, 0, 0); } while (0)
; #define PG8_LDA(dst, b, h) do { _Pragma("unroll") for (int m = 0; m < 4; ++m) _Pragma("unroll") for (int k = 0; k < 2; ++k) dst[m][k] = *(const PG8_LAS bf16x8*)(lds + PG8_SA(b, h) + aoff + m * 2048 + k * 1024); } while (0)
; #define PG8_LDB(dst, b, h) do { _Pragma("unroll") for (int n = 0; n < 2; ++n) _Pragma("unroll") for (int k = 0; k < 2; ++k) dst[n][k] = *(const PG8_LAS bf16x8*)(lds + PG8_SB(b, h) + boff + n * 2048 + k * 1024); } while (0)
; #define PG8_MMA(ai, bj, At, Bt) do { __builtin_amdgcn_s_setprio(1); _Pragma("unroll") for (int m = 0; m < 4; ++m) _Pragma("unroll") for (int n = 0; n < 2; ++n) _Pragma("unroll") for (int k = 0; k < 2; ++k) \
;         acc[ai][bj][m][n] = __builtin_amdgcn_mfma_f32_16x16x32_bf16(Bt[n][k], At[m][k], acc[ai][bj][m][n], 0, 0, 0); __builtin_amdgcn_s_setprio(0); } while (0)
; #define PG8_BAR __builtin_amdgcn_s_barrier()
; template <class Epi, class Sched, bool ALIGN_EPI = false, bool SP2 = false>
; __device__ __forceinline__ void gemm_phase(PG8_LAS unsigned char* lds, const Gemm g, const Sched& S, const Epi& E, const int wid) {
;     ...
;             PG8_LDB(B0, 0, 0); PG8_LDB(B1, 0, 1); PG8_SCHED; PG8_LDA(At, 0, 0); PG8_STAGE(PG8_SA(1, 1), a1 + hstep, voffA);
;             PG8_WAIT_V(8); PG8_WAIT_L(0); PG8_BAR; PG8_MMA(0, 0, At, B0); PG8_MMA(0, 1, At, B1); PG8_BAR; PG8_SCHED;
;             PG8_LDA(At, 0, 1); PG8_STAGE(PG8_SB(0, 0), b2, voffB); PG8_STAGE(PG8_SB(0, 1), b2 + hstep, voffB); PG8_STAGE(PG8_SA(0, 0), a2, voffA);
;             PG8_WAIT_V(8); PG8_WAIT_L(0); PG8_BAR; PG8_MMA(1, 0, At, B0); PG8_MMA(1, 1, At, B1); PG8_BAR; PG8_SCHED;
;             PG8_LDB(B0, 1, 0); PG8_LDB(B1, 1, 1); PG8_SCHED; PG8_LDA(At, 1, 0); PG8_STAGE(PG8_SA(0, 1), a2 + hstep, voffA);
;             PG8_WAIT_V(8); PG8_WAIT_L(0); PG8_BAR; PG8_MMA(0, 0, At, B0); PG8_MMA(0, 1, At, B1); PG8_BAR; PG8_SCHED;
;             PG8_LDA(At, 1, 1); PG8_STAGE(PG8_SB(1, 0), b3, voffB); PG8_STAGE(PG8_SB(1, 1), b3 + hstep, voffB); PG8_STAGE(PG8_SA(1, 0), a3, voffA);
;             PG8_WAIT_V(8); PG8_WAIT_L(0); PG8_BAR; PG8_MMA(1, 0, At, B0); PG8_MMA(1, 1, At, B1); PG8_BAR; PG8_SCHED;
	v_mfma_f32_16x16x32_bf16 v[124:127], v[128:131], v[184:187], v[124:127]
	v_mfma_f32_16x16x32_bf16 v[120:123], v[136:139], v[184:187], v[120:123]
	v_mfma_f32_16x16x32_bf16 v[108:111], v[128:131], v[200:203], v[108:111]
	v_mfma_f32_16x16x32_bf16 v[104:107], v[136:139], v[200:203], v[104:107]
	v_mfma_f32_16x16x32_bf16 v[92:95], v[128:131], v[208:211], v[92:95]
	v_mfma_f32_16x16x32_bf16 v[88:91], v[136:139], v[208:211], v[88:91]
	v_mfma_f32_16x16x32_bf16 v[76:79], v[128:131], v[216:219], v[76:79]
	v_mfma_f32_16x16x32_bf16 v[72:75], v[136:139], v[216:219], v[72:75]
	v_mfma_f32_16x16x32_bf16 v[124:127], v[132:135], v[188:191], v[124:127]
	v_mfma_f32_16x16x32_bf16 v[120:123], v[140:143], v[188:191], v[120:123]
	v_mfma_f32_16x16x32_bf16 v[108:111], v[132:135], v[204:207], v[108:111]
	v_mfma_f32_16x16x32_bf16 v[104:107], v[140:143], v[204:207], v[104:107]
	v_mfma_f32_16x16x32_bf16 v[92:95], v[132:135], v[212:215], v[92:95]
	v_mfma_f32_16x16x32_bf16 v[88:91], v[140:143], v[212:215], v[88:91]
	v_mfma_f32_16x16x32_bf16 v[76:79], v[132:135], v[220:223], v[76:79]
	v_mfma_f32_16x16x32_bf16 v[72:75], v[140:143], v[220:223], v[72:75]
	v_mfma_f32_16x16x32_bf16 v[116:119], v[144:147], v[184:187], v[116:119]
	v_mfma_f32_16x16x32_bf16 v[112:115], v[176:179], v[184:187], v[112:115]
	v_mfma_f32_16x16x32_bf16 v[100:103], v[144:147], v[200:203], v[100:103]
	v_mfma_f32_16x16x32_bf16 v[96:99], v[176:179], v[200:203], v[96:99]
	v_mfma_f32_16x16x32_bf16 v[84:87], v[144:147], v[208:211], v[84:87]
	v_mfma_f32_16x16x32_bf16 v[80:83], v[176:179], v[208:211], v[80:83]
	v_mfma_f32_16x16x32_bf16 v[68:71], v[144:147], v[216:219], v[68:71]
	v_mfma_f32_16x16x32_bf16 v[64:67], v[176:179], v[216:219], v[64:67]
	v_mfma_f32_16x16x32_bf16 v[116:119], v[148:151], v[188:191], v[116:119]
	v_mfma_f32_16x16x32_bf16 v[112:115], v[180:183], v[188:191], v[112:115]
	v_mfma_f32_16x16x32_bf16 v[100:103], v[148:151], v[204:207], v[100:103]
	v_mfma_f32_16x16x32_bf16 v[96:99], v[180:183], v[204:207], v[96:99]
	v_mfma_f32_16x16x32_bf16 v[84:87], v[148:151], v[212:215], v[84:87]
	v_mfma_f32_16x16x32_bf16 v[80:83], v[180:183], v[212:215], v[80:83]
	v_mfma_f32_16x16x32_bf16 v[68:71], v[148:151], v[220:223], v[68:71]
	v_mfma_f32_16x16x32_bf16 v[64:67], v[180:183], v[220:223], v[64:67]
	s_barrier
	s_setprio 0
	s_add_i32 s51, 0, 0x18000
	s_add_i32 s52, 0, 0x1c000
	v_add_u32_e32 v140, s51, v195
	v_add_u32_e32 v180, s52, v195
	ds_read_b128 v[128:131], v140
	ds_read_b128 v[132:135], v140 offset:1024
	ds_read_b128 v[136:139], v140 offset:2048
	ds_read_b128 v[140:143], v140 offset:3072
	ds_read_b128 v[144:147], v180
	ds_read_b128 v[148:151], v180 offset:1024
	ds_read_b128 v[176:179], v180 offset:2048
	ds_read_b128 v[180:183], v180 offset:3072
	s_add_u32 s28, s28, 0x200000
	s_addc_u32 s29, s29, 0
	s_mov_b32 m0, s37
	v_lshl_add_u64 v[230:231], s[28:29], 0, v[152:153]
	ds_read_b128 v[184:187], v199 offset:32768
	ds_read_b128 v[188:191], v199 offset:33792
	ds_read_b128 v[200:203], v199 offset:34816
	ds_read_b128 v[204:207], v199 offset:35840
	ds_read_b128 v[208:211], v199 offset:36864
	ds_read_b128 v[212:215], v199 offset:37888
	ds_read_b128 v[216:219], v199 offset:38912
	ds_read_b128 v[220:223], v199 offset:39936
	global_load_lds_dwordx4 v[230:231], off
	v_lshl_add_u64 v[230:231], s[28:29], 0, v[156:157]
	s_mov_b32 m0, s38
	s_nop 0
	global_load_lds_dwordx4 v[230:231], off
	s_waitcnt vmcnt(8)
	s_waitcnt lgkmcnt(0)
	s_setprio 1
	s_barrier
	v_mfma_f32_16x16x32_bf16 v[60:63], v[128:131], v[184:187], v[60:63]
	v_mfma_f32_16x16x32_bf16 v[56:59], v[136:139], v[184:187], v[56:59]
	v_mfma_f32_16x16x32_bf16 v[44:47], v[128:131], v[200:203], v[44:47]
	v_mfma_f32_16x16x32_bf16 v[40:43], v[136:139], v[200:203], v[40:43]
	v_mfma_f32_16x16x32_bf16 v[28:31], v[128:131], v[208:211], v[28:31]
	v_mfma_f32_16x16x32_bf16 v[24:27], v[136:139], v[208:211], v[24:27]
	v_mfma_f32_16x16x32_bf16 v[12:15], v[128:131], v[216:219], v[12:15]
	v_mfma_f32_16x16x32_bf16 v[8:11], v[136:139], v[216:219], v[8:11]
	v_mfma_f32_16x16x32_bf16 v[60:63], v[132:135], v[188:191], v[60:63]
	v_mfma_f32_16x16x32_bf16 v[56:59], v[140:143], v[188:191], v[56:59]
	v_mfma_f32_16x16x32_bf16 v[44:47], v[132:135], v[204:207], v[44:47]
	v_mfma_f32_16x16x32_bf16 v[40:43], v[140:143], v[204:207], v[40:43]
	v_mfma_f32_16x16x32_bf16 v[28:31], v[132:135], v[212:215], v[28:31]
	v_mfma_f32_16x16x32_bf16 v[24:27], v[140:143], v[212:215], v[24:27]
	v_mfma_f32_16x16x32_bf16 v[12:15], v[132:135], v[220:223], v[12:15]
	v_mfma_f32_16x16x32_bf16 v[8:11], v[140:143], v[220:223], v[8:11]
	v_mfma_f32_16x16x32_bf16 v[52:55], v[144:147], v[184:187], v[52:55]
	v_mfma_f32_16x16x32_bf16 v[48:51], v[176:179], v[184:187], v[48:51]
	v_mfma_f32_16x16x32_bf16 v[36:39], v[144:147], v[200:203], v[36:39]
	v_mfma_f32_16x16x32_bf16 v[32:35], v[176:179], v[200:203], v[32:35]
	v_mfma_f32_16x16x32_bf16 v[20:23], v[144:147], v[208:211], v[20:23]
	v_mfma_f32_16x16x32_bf16 v[16:19], v[176:179], v[208:211], v[16:19]
	v_mfma_f32_16x16x32_bf16 v[4:7], v[144:147], v[216:219], v[4:7]
	v_mfma_f32_16x16x32_bf16 v[0:3], v[176:179], v[216:219], v[0:3]
	v_mfma_f32_16x16x32_bf16 v[52:55], v[148:151], v[188:191], v[52:55]
	v_mfma_f32_16x16x32_bf16 v[48:51], v[180:183], v[188:191], v[48:51]
	v_mfma_f32_16x16x32_bf16 v[36:39], v[148:151], v[204:207], v[36:39]
	v_mfma_f32_16x16x32_bf16 v[32:35], v[180:183], v[204:207], v[32:35]
	v_mfma_f32_16x16x32_bf16 v[20:23], v[148:151], v[212:215], v[20:23]
	v_mfma_f32_16x16x32_bf16 v[16:19], v[180:183], v[212:215], v[16:19]
	v_mfma_f32_16x16x32_bf16 v[4:7], v[148:151], v[220:223], v[4:7]
	v_mfma_f32_16x16x32_bf16 v[0:3], v[180:183], v[220:223], v[0:3]
	s_barrier
; #define PG8_STAGE(bufoff, gbase, voff) do { _Pragma("unroll") for (int _i = 0; _i < 2; ++_i) \
;         __builtin_amdgcn_global_load_lds((const unsigned*)((const char*)(gbase) + (voff)[_i]), (PG8_LAS unsigned*)(lds + (bufoff) + ldsw + _i * 8192), 16, 0, 0); } while (0)
; #define PG8_LDA(dst, b, h) do { _Pragma("unroll") for (int m = 0; m < 4; ++m) _Pragma("unroll") for (int k = 0; k < 2; ++k) dst[m][k] = *(const PG8_LAS bf16x8*)(lds + PG8_SA(b, h) + aoff + m * 2048 + k * 1024); } while (0)
; #define PG8_WAIT_V(n) asm volatile("s_waitcnt vmcnt(" #n ")" ::: "memory")
; #define PG8_WAIT_L(n) asm volatile("s_waitcnt lgkmcnt(" #n ")" ::: "memory")
; #define PG8_BAR __builtin_amdgcn_s_barrier()
; template <class Epi, class Sched, bool ALIGN_EPI = false, bool SP2 = false>
; __device__ __forceinline__ void gemm_phase(PG8_LAS unsigned char* lds, const Gemm g, const Sched& S, const Epi& E, const int wid) {
;     ...
;         for (int t = 0; t < nt; t += 2) {
;             const bool last = (t == nt - 2);
;             const char* a1 = cA + (size_t)(t + 1) * kstep;
;             const char* a2 = last ? nA : cA + (size_t)(t + 2) * kstep; const char* b2 = last ? nB : cB + (size_t)(t + 2) * kstep;
;             const char* a3 = a2 + kstep; const char* b3 = b2 + kstep;
;             if (last && has_next) S.a_ready(nxt);
;             if constexpr (SP2) {
;             PG8_LDB(B0, 0, 0); PG8_LDB(B1, 0, 1); PG8_SCHED; PG8_LDA(At, 0, 0); PG8_STAGE(PG8_SA(1, 1), a1 + hstep, voffA);
;             PG8_WAIT_V(8); PG8_WAIT_L(0); PG8_BAR; PG8_MMA(0, 0, At, B0); PG8_MMA(0, 1, At, B1); PG8_BAR; PG8_SCHED;
;             PG8_LDA(At, 0, 1); PG8_STAGE(PG8_SB(0, 0), b2, voffB); PG8_STAGE(PG8_SB(0, 1), b2 + hstep, voffB); PG8_STAGE(PG8_SA(0, 0), a2, voffA);
;             PG8_WAIT_V(8); PG8_WAIT_L(0); PG8_BAR; PG8_MMA(1, 0, At, B0); PG8_MMA(1, 1, At, B1); PG8_BAR; PG8_SCHED;
;             PG8_LDB(B0, 1, 0); PG8_LDB(B1, 1, 1); PG8_SCHED; PG8_LDA(At, 1, 0); PG8_STAGE(PG8_SA(0, 1), a2 + hstep, voffA);
;             PG8_WAIT_V(8); PG8_WAIT_L(0); PG8_BAR; PG8_MMA(0, 0, At, B0); PG8_MMA(0, 1, At, B1); PG8_BAR; PG8_SCHED;
;             PG8_LDA(At, 1, 1); PG8_STAGE(PG8_SB(1, 0), b3, voffB); PG8_STAGE(PG8_SB(1, 1), b3 + hstep, voffB); PG8_STAGE(PG8_SA(1, 0), a3, voffA);
;             PG8_WAIT_V(8); PG8_WAIT_L(0); PG8_BAR; PG8_MMA(1, 0, At, B0); PG8_MMA(1, 1, At, B1); PG8_BAR; PG8_SCHED;
	s_setprio 0
	s_add_i32 s28, s51, s34
	v_lshl_add_u64 v[192:193], v[192:193], 0, s[8:9]
	s_mov_b32 m0, s28
	ds_read_b128 v[184:187], v199 offset:49152
	ds_read_b128 v[188:191], v199 offset:50176
	ds_read_b128 v[200:203], v199 offset:51200
	ds_read_b128 v[204:207], v199 offset:52224
	ds_read_b128 v[208:211], v199 offset:53248
	ds_read_b128 v[212:215], v199 offset:54272
	ds_read_b128 v[216:219], v199 offset:55296
	ds_read_b128 v[220:223], v199 offset:56320
	global_load_lds_dwordx4 v[192:193], off
	s_add_i32 m0, s28, 0x2000
	s_add_u32 s26, s26, 0x200080
	v_lshl_add_u64 v[192:193], v[224:225], 0, s[8:9]
	s_addc_u32 s27, s27, 0
	s_add_i32 s28, s52, s34
	global_load_lds_dwordx4 v[192:193], off
	v_lshl_add_u64 v[192:193], s[26:27], 0, v[154:155]
	s_mov_b32 m0, s28
	s_nop 0
	global_load_lds_dwordx4 v[192:193], off
	v_lshl_add_u64 v[192:193], s[26:27], 0, v[158:159]
	s_add_i32 m0, s28, 0x2000
	s_nop 0
	global_load_lds_dwordx4 v[192:193], off
	v_lshl_add_u64 v[192:193], v[226:227], 0, s[8:9]
	s_mov_b32 m0, s40
	s_nop 0
	global_load_lds_dwordx4 v[192:193], off
	v_lshl_add_u64 v[192:193], v[228:229], 0, s[8:9]
	s_mov_b32 m0, s41
	s_nop 0
	global_load_lds_dwordx4 v[192:193], off
	s_waitcnt vmcnt(8)
	s_waitcnt lgkmcnt(0)
	s_setprio 1
	s_barrier
	v_mfma_f32_16x16x32_bf16 v[124:127], v[128:131], v[184:187], v[124:127]
	v_mfma_f32_16x16x32_bf16 v[120:123], v[136:139], v[184:187], v[120:123]
	v_mfma_f32_16x16x32_bf16 v[108:111], v[128:131], v[200:203], v[108:111]
	v_mfma_f32_16x16x32_bf16 v[104:107], v[136:139], v[200:203], v[104:107]
	v_mfma_f32_16x16x32_bf16 v[92:95], v[128:131], v[208:211], v[92:95]
	v_mfma_f32_16x16x32_bf16 v[88:91], v[136:139], v[208:211], v[88:91]
	v_mfma_f32_16x16x32_bf16 v[76:79], v[128:131], v[216:219], v[76:79]
	v_mfma_f32_16x16x32_bf16 v[72:75], v[136:139], v[216:219], v[72:75]
	v_mfma_f32_16x16x32_bf16 v[124:127], v[132:135], v[188:191], v[124:127]
	v_mfma_f32_16x16x32_bf16 v[120:123], v[140:143], v[188:191], v[120:123]
	v_mfma_f32_16x16x32_bf16 v[108:111], v[132:135], v[204:207], v[108:111]
	v_mfma_f32_16x16x32_bf16 v[104:107], v[140:143], v[204:207], v[104:107]
	v_mfma_f32_16x16x32_bf16 v[92:95], v[132:135], v[212:215], v[92:95]
	v_mfma_f32_16x16x32_bf16 v[88:91], v[140:143], v[212:215], v[88:91]
	v_mfma_f32_16x16x32_bf16 v[76:79], v[132:135], v[220:223], v[76:79]
	v_mfma_f32_16x16x32_bf16 v[72:75], v[140:143], v[220:223], v[72:75]
	v_mfma_f32_16x16x32_bf16 v[116:119], v[144:147], v[184:187], v[116:119]
	v_mfma_f32_16x16x32_bf16 v[112:115], v[176:179], v[184:187], v[112:115]
	v_mfma_f32_16x16x32_bf16 v[100:103], v[144:147], v[200:203], v[100:103]
	v_mfma_f32_16x16x32_bf16 v[96:99], v[176:179], v[200:203], v[96:99]
	v_mfma_f32_16x16x32_bf16 v[84:87], v[144:147], v[208:211], v[84:87]
	v_mfma_f32_16x16x32_bf16 v[80:83], v[176:179], v[208:211], v[80:83]
	v_mfma_f32_16x16x32_bf16 v[68:71], v[144:147], v[216:219], v[68:71]
	v_mfma_f32_16x16x32_bf16 v[64:67], v[176:179], v[216:219], v[64:67]
	v_mfma_f32_16x16x32_bf16 v[116:119], v[148:151], v[188:191], v[116:119]
	v_mfma_f32_16x16x32_bf16 v[112:115], v[180:183], v[188:191], v[112:115]
	v_mfma_f32_16x16x32_bf16 v[100:103], v[148:151], v[204:207], v[100:103]
	v_mfma_f32_16x16x32_bf16 v[96:99], v[180:183], v[204:207], v[96:99]
	v_mfma_f32_16x16x32_bf16 v[84:87], v[148:151], v[212:215], v[84:87]
	v_mfma_f32_16x16x32_bf16 v[80:83], v[180:183], v[212:215], v[80:83]
	v_mfma_f32_16x16x32_bf16 v[68:71], v[148:151], v[220:223], v[68:71]
	v_mfma_f32_16x16x32_bf16 v[64:67], v[180:183], v[220:223], v[64:67]
	s_barrier
	s_setprio 0
	s_add_i32 s50, s50, 2
	s_add_u32 s24, s24, 0x100
	s_addc_u32 s25, s25, 0
	s_add_u32 s48, s48, 0x100
	s_addc_u32 s49, s49, 0
	s_cmpk_gt_u32 s50, 0x7d
	s_cbranch_scc0 .LBB0_1671
	s_and_b64 vcc, exec, s[10:11]
	s_cbranch_vccnz .LBB0_1675
	v_lshl_add_u32 v176, s22, 8, v196
	s_cmp_eq_u32 s20, 64
	s_mov_b64 s[22:23], -1
	s_cbranch_scc0 .LBB0_1676

; #define PG8_STAGE(bufoff, gbase, voff) do { _Pragma("unroll") for (int _i = 0; _i < 2; ++_i) \
;         __builtin_amdgcn_global_load_lds((const unsigned*)((const char*)(gbase) + (voff)[_i]), (PG8_LAS unsigned*)(lds + (bufoff) + ldsw + _i * 8192), 16, 0, 0); } while (0)
; #define PG8_LDA(dst, b, h) do { _Pragma("unroll") for (int m = 0; m < 4; ++m) _Pragma("unroll") for (int k = 0; k < 2; ++k) dst[m][k] = *(const PG8_LAS bf16x8*)(lds + PG8_SA(b, h) + aoff + m * 2048 + k * 1024); } while (0)
; #define PG8_LDB(dst, b, h) do { _Pragma("unroll") for (int n = 0; n < 2; ++n) _Pragma("unroll") for (int k = 0; k < 2; ++k) dst[n][k] = *(const PG8_LAS bf16x8*)(lds + PG8_SB(b, h) + boff + n * 2048 + k * 1024); } while (0)
; #define PG8_MMA(ai, bj, At, Bt) do { __builtin_amdgcn_s_setprio(1); _Pragma("unroll") for (int m = 0; m < 4; ++m) _Pragma("unroll") for (int n = 0; n < 2; ++n) _Pragma("unroll") for (int k = 0; k < 2; ++k) \
;         acc[ai][bj][m][n] = __builtin_amdgcn_mfma_f32_16x16x32_bf16(Bt[n][k], At[m][k], acc[ai][bj][m][n], 0, 0, 0); __builtin_amdgcn_s_setprio(0); } while (0)
; #define PG8_BAR __builtin_amdgcn_s_barrier()
; template <class Epi, class Sched, bool ALIGN_EPI = false, bool SP2 = false>
; __device__ __forceinline__ void gemm_phase(PG8_LAS unsigned char* lds, const Gemm g, const Sched& S, const Epi& E, const int wid) {
;     ...
;             PG8_LDB(B0, 0, 0); PG8_LDB(B1, 0, 1); PG8_SCHED; PG8_LDA(At, 0, 0); PG8_STAGE(PG8_SA(1, 1), a1 + hstep, voffA);
;             PG8_WAIT_V(8); PG8_WAIT_L(0); PG8_BAR; PG8_MMA(0, 0, At, B0); PG8_MMA(0, 1, At, B1); PG8_BAR; PG8_SCHED;
;             PG8_LDA(At, 0, 1); PG8_STAGE(PG8_SB(0, 0), b2, voffB); PG8_STAGE(PG8_SB(0, 1), b2 + hstep, voffB); PG8_STAGE(PG8_SA(0, 0), a2, voffA);
;             PG8_WAIT_V(8); PG8_WAIT_L(0); PG8_BAR; PG8_MMA(1, 0, At, B0); PG8_MMA(1, 1, At, B1); PG8_BAR; PG8_SCHED;
;             PG8_LDB(B0, 1, 0); PG8_LDB(B1, 1, 1); PG8_SCHED; PG8_LDA(At, 1, 0); PG8_STAGE(PG8_SA(0, 1), a2 + hstep, voffA);
;             PG8_WAIT_V(8); PG8_WAIT_L(0); PG8_BAR; PG8_MMA(0, 0, At, B0); PG8_MMA(0, 1, At, B1); PG8_BAR; PG8_SCHED;
;             PG8_LDA(At, 1, 1); PG8_STAGE(PG8_SB(1, 0), b3, voffB); PG8_STAGE(PG8_SB(1, 1), b3 + hstep, voffB); PG8_STAGE(PG8_SA(1, 0), a3, voffA);
;             PG8_WAIT_V(8); PG8_WAIT_L(0); PG8_BAR; PG8_MMA(1, 0, At, B0); PG8_MMA(1, 1, At, B1); PG8_BAR; PG8_SCHED;
.LBB0_1764:
	ds_read_b128 v[146:149], v154
	ds_read_b128 v[158:161], v154 offset:1024
	ds_read_b128 v[162:165], v154 offset:2048
	ds_read_b128 v[166:169], v154 offset:3072
	ds_read_b128 v[170:173], v155
	ds_read_b128 v[174:177], v155 offset:1024
	ds_read_b128 v[178:181], v155 offset:2048
	ds_read_b128 v[182:185], v155 offset:3072
	s_add_u32 s24, s22, 0xfff00080
	s_addc_u32 s25, s23, -1
	s_cmp_eq_u32 s51, 60
	s_cselect_b32 s27, s15, s25
	s_cselect_b32 s26, s47, s24
	s_cselect_b32 s25, s13, s50
	s_cselect_b32 s24, s48, s49
	v_lshl_add_u64 v[218:219], s[22:23], 0, v[138:139]
	s_add_i32 m0, s21, 0xc000
	ds_read_b128 v[186:189], v156
	ds_read_b128 v[190:193], v156 offset:1024
	ds_read_b128 v[194:197], v156 offset:2048
	ds_read_b128 v[198:201], v156 offset:3072
	ds_read_b128 v[202:205], v156 offset:4096
	ds_read_b128 v[206:209], v156 offset:5120
	ds_read_b128 v[210:213], v156 offset:6144
	ds_read_b128 v[214:217], v156 offset:7168
	global_load_lds_dwordx4 v[218:219], off
	v_lshl_add_u64 v[218:219], s[22:23], 0, v[140:141]
	s_add_i32 m0, s21, 0xe000
	s_nop 0
	global_load_lds_dwordx4 v[218:219], off
	s_waitcnt vmcnt(8)
	s_waitcnt lgkmcnt(0)
	s_setprio 1
	s_barrier
	v_mfma_f32_16x16x32_bf16 v[124:127], v[146:149], v[186:189], v[124:127]
	v_mfma_f32_16x16x32_bf16 v[120:123], v[162:165], v[186:189], v[120:123]
	v_mfma_f32_16x16x32_bf16 v[108:111], v[146:149], v[194:197], v[108:111]
	v_mfma_f32_16x16x32_bf16 v[104:107], v[162:165], v[194:197], v[104:107]
	v_mfma_f32_16x16x32_bf16 v[92:95], v[146:149], v[202:205], v[92:95]
	v_mfma_f32_16x16x32_bf16 v[88:91], v[162:165], v[202:205], v[88:91]
	v_mfma_f32_16x16x32_bf16 v[76:79], v[146:149], v[210:213], v[76:79]
	v_mfma_f32_16x16x32_bf16 v[72:75], v[162:165], v[210:213], v[72:75]
	v_mfma_f32_16x16x32_bf16 v[124:127], v[158:161], v[190:193], v[124:127]
	v_mfma_f32_16x16x32_bf16 v[120:123], v[166:169], v[190:193], v[120:123]
	v_mfma_f32_16x16x32_bf16 v[108:111], v[158:161], v[198:201], v[108:111]
	v_mfma_f32_16x16x32_bf16 v[104:107], v[166:169], v[198:201], v[104:107]
	v_mfma_f32_16x16x32_bf16 v[92:95], v[158:161], v[206:209], v[92:95]
	v_mfma_f32_16x16x32_bf16 v[88:91], v[166:169], v[206:209], v[88:91]
	v_mfma_f32_16x16x32_bf16 v[76:79], v[158:161], v[214:217], v[76:79]
	v_mfma_f32_16x16x32_bf16 v[72:75], v[166:169], v[214:217], v[72:75]
	v_mfma_f32_16x16x32_bf16 v[116:119], v[170:173], v[186:189], v[116:119]
	v_mfma_f32_16x16x32_bf16 v[112:115], v[178:181], v[186:189], v[112:115]
	v_mfma_f32_16x16x32_bf16 v[100:103], v[170:173], v[194:197], v[100:103]
	v_mfma_f32_16x16x32_bf16 v[96:99], v[178:181], v[194:197], v[96:99]
	v_mfma_f32_16x16x32_bf16 v[84:87], v[170:173], v[202:205], v[84:87]
	v_mfma_f32_16x16x32_bf16 v[80:83], v[178:181], v[202:205], v[80:83]
	v_mfma_f32_16x16x32_bf16 v[68:71], v[170:173], v[210:213], v[68:71]
	v_mfma_f32_16x16x32_bf16 v[64:67], v[178:181], v[210:213], v[64:67]
	v_mfma_f32_16x16x32_bf16 v[116:119], v[174:177], v[190:193], v[116:119]
	v_mfma_f32_16x16x32_bf16 v[112:115], v[182:185], v[190:193], v[112:115]
	v_mfma_f32_16x16x32_bf16 v[100:103], v[174:177], v[198:201], v[100:103]
	v_mfma_f32_16x16x32_bf16 v[96:99], v[182:185], v[198:201], v[96:99]
	v_mfma_f32_16x16x32_bf16 v[84:87], v[174:177], v[206:209], v[84:87]
	v_mfma_f32_16x16x32_bf16 v[80:83], v[182:185], v[206:209], v[80:83]
	v_mfma_f32_16x16x32_bf16 v[68:71], v[174:177], v[214:217], v[68:71]
	v_mfma_f32_16x16x32_bf16 v[64:67], v[182:185], v[214:217], v[64:67]
	s_barrier
	s_setprio 0
	s_add_i32 s52, s42, s28
	v_lshl_add_u64 v[218:219], s[24:25], 0, v[132:133]
	s_mov_b32 m0, s52
	ds_read_b128 v[186:189], v156 offset:16384
	ds_read_b128 v[190:193], v156 offset:17408
	ds_read_b128 v[194:197], v156 offset:18432
	ds_read_b128 v[198:201], v156 offset:19456
	ds_read_b128 v[202:205], v156 offset:20480
	ds_read_b128 v[206:209], v156 offset:21504
	ds_read_b128 v[210:213], v156 offset:22528
	ds_read_b128 v[214:217], v156 offset:23552
	global_load_lds_dwordx4 v[218:219], off
	s_add_i32 m0, s52, 0x2000
	s_add_u32 s52, s24, 0x100000
	v_lshl_add_u64 v[220:221], s[24:25], 0, v[128:129]
	s_addc_u32 s53, s25, 0
	s_add_i32 s54, s43, s28
	global_load_lds_dwordx4 v[220:221], off
	v_lshl_add_u64 v[222:223], s[52:53], 0, v[132:133]
	s_mov_b32 m0, s54
	v_lshl_add_u64 v[224:225], s[26:27], 0, v[130:131]
	global_load_lds_dwordx4 v[222:223], off
	v_lshl_add_u64 v[222:223], s[52:53], 0, v[128:129]
	s_add_i32 m0, s54, 0x2000
	s_nop 0
	global_load_lds_dwordx4 v[222:223], off
	v_lshl_add_u64 v[222:223], s[26:27], 0, v[134:135]
	s_mov_b32 m0, s21
	s_nop 0
	global_load_lds_dwordx4 v[222:223], off
	s_mov_b32 m0, s31
	s_nop 0
	global_load_lds_dwordx4 v[224:225], off
	s_waitcnt vmcnt(8)
	s_waitcnt lgkmcnt(0)
	s_setprio 1
	s_barrier
; #define PG8_STAGE(bufoff, gbase, voff) do { _Pragma("unroll") for (int _i = 0; _i < 2; ++_i) \
;         __builtin_amdgcn_global_load_lds((const unsigned*)((const char*)(gbase) + (voff)[_i]), (PG8_LAS unsigned*)(lds + (bufoff) + ldsw + _i * 8192), 16, 0, 0); } while (0)
; #define PG8_LDA(dst, b, h) do { _Pragma("unroll") for (int m = 0; m < 4; ++m) _Pragma("unroll") for (int k = 0; k < 2; ++k) dst[m][k] = *(const PG8_LAS bf16x8*)(lds + PG8_SA(b, h) + aoff + m * 2048 + k * 1024); } while (0)
; #define PG8_LDB(dst, b, h) do { _Pragma("unroll") for (int n = 0; n < 2; ++n) _Pragma("unroll") for (int k = 0; k < 2; ++k) dst[n][k] = *(const PG8_LAS bf16x8*)(lds + PG8_SB(b, h) + boff + n * 2048 + k * 1024); } while (0)
; #define PG8_MMA(ai, bj, At, Bt) do { __builtin_amdgcn_s_setprio(1); _Pragma("unroll") for (int m = 0; m < 4; ++m) _Pragma("unroll") for (int n = 0; n < 2; ++n) _Pragma("unroll") for (int k = 0; k < 2; ++k) \
;         acc[ai][bj][m][n] = __builtin_amdgcn_mfma_f32_16x16x32_bf16(Bt[n][k], At[m][k], acc[ai][bj][m][n], 0, 0, 0); __builtin_amdgcn_s_setprio(0); } while (0)
; #define PG8_BAR __builtin_amdgcn_s_barrier()
; template <class Epi, class Sched, bool ALIGN_EPI = false, bool SP2 = false>
; __device__ __forceinline__ void gemm_phase(PG8_LAS unsigned char* lds, const Gemm g, const Sched& S, const Epi& E, const int wid) {
;     ...
;             PG8_LDB(B0, 0, 0); PG8_LDB(B1, 0, 1); PG8_SCHED; PG8_LDA(At, 0, 0); PG8_STAGE(PG8_SA(1, 1), a1 + hstep, voffA);
;             PG8_WAIT_V(8); PG8_WAIT_L(0); PG8_BAR; PG8_MMA(0, 0, At, B0); PG8_MMA(0, 1, At, B1); PG8_BAR; PG8_SCHED;
;             PG8_LDA(At, 0, 1); PG8_STAGE(PG8_SB(0, 0), b2, voffB); PG8_STAGE(PG8_SB(0, 1), b2 + hstep, voffB); PG8_STAGE(PG8_SA(0, 0), a2, voffA);
;             PG8_WAIT_V(8); PG8_WAIT_L(0); PG8_BAR; PG8_MMA(1, 0, At, B0); PG8_MMA(1, 1, At, B1); PG8_BAR; PG8_SCHED;
;             PG8_LDB(B0, 1, 0); PG8_LDB(B1, 1, 1); PG8_SCHED; PG8_LDA(At, 1, 0); PG8_STAGE(PG8_SA(0, 1), a2 + hstep, voffA);
;             PG8_WAIT_V(8); PG8_WAIT_L(0); PG8_BAR; PG8_MMA(0, 0, At, B0); PG8_MMA(0, 1, At, B1); PG8_BAR; PG8_SCHED;
;             PG8_LDA(At, 1, 1); PG8_STAGE(PG8_SB(1, 0), b3, voffB); PG8_STAGE(PG8_SB(1, 1), b3 + hstep, voffB); PG8_STAGE(PG8_SA(1, 0), a3, voffA);
;             PG8_WAIT_V(8); PG8_WAIT_L(0); PG8_BAR; PG8_MMA(1, 0, At, B0); PG8_MMA(1, 1, At, B1); PG8_BAR; PG8_SCHED;
	v_mfma_f32_16x16x32_bf16 v[60:63], v[146:149], v[186:189], v[60:63]
	v_mfma_f32_16x16x32_bf16 v[56:59], v[162:165], v[186:189], v[56:59]
	v_mfma_f32_16x16x32_bf16 v[44:47], v[146:149], v[194:197], v[44:47]
	v_mfma_f32_16x16x32_bf16 v[40:43], v[162:165], v[194:197], v[40:43]
	v_mfma_f32_16x16x32_bf16 v[28:31], v[146:149], v[202:205], v[28:31]
	v_mfma_f32_16x16x32_bf16 v[24:27], v[162:165], v[202:205], v[24:27]
	v_mfma_f32_16x16x32_bf16 v[12:15], v[146:149], v[210:213], v[12:15]
	v_mfma_f32_16x16x32_bf16 v[8:11], v[162:165], v[210:213], v[8:11]
	v_mfma_f32_16x16x32_bf16 v[60:63], v[158:161], v[190:193], v[60:63]
	v_mfma_f32_16x16x32_bf16 v[56:59], v[166:169], v[190:193], v[56:59]
	v_mfma_f32_16x16x32_bf16 v[44:47], v[158:161], v[198:201], v[44:47]
	v_mfma_f32_16x16x32_bf16 v[40:43], v[166:169], v[198:201], v[40:43]
	v_mfma_f32_16x16x32_bf16 v[28:31], v[158:161], v[206:209], v[28:31]
	v_mfma_f32_16x16x32_bf16 v[24:27], v[166:169], v[206:209], v[24:27]
	v_mfma_f32_16x16x32_bf16 v[12:15], v[158:161], v[214:217], v[12:15]
	v_mfma_f32_16x16x32_bf16 v[8:11], v[166:169], v[214:217], v[8:11]
	v_mfma_f32_16x16x32_bf16 v[52:55], v[170:173], v[186:189], v[52:55]
	v_mfma_f32_16x16x32_bf16 v[48:51], v[178:181], v[186:189], v[48:51]
	v_mfma_f32_16x16x32_bf16 v[36:39], v[170:173], v[194:197], v[36:39]
	v_mfma_f32_16x16x32_bf16 v[32:35], v[178:181], v[194:197], v[32:35]
	v_mfma_f32_16x16x32_bf16 v[20:23], v[170:173], v[202:205], v[20:23]
	v_mfma_f32_16x16x32_bf16 v[16:19], v[178:181], v[202:205], v[16:19]
	v_mfma_f32_16x16x32_bf16 v[4:7], v[170:173], v[210:213], v[4:7]
	v_mfma_f32_16x16x32_bf16 v[0:3], v[178:181], v[210:213], v[0:3]
	v_mfma_f32_16x16x32_bf16 v[52:55], v[174:177], v[190:193], v[52:55]
	v_mfma_f32_16x16x32_bf16 v[48:51], v[182:185], v[190:193], v[48:51]
	v_mfma_f32_16x16x32_bf16 v[36:39], v[174:177], v[198:201], v[36:39]
	v_mfma_f32_16x16x32_bf16 v[32:35], v[182:185], v[198:201], v[32:35]
	v_mfma_f32_16x16x32_bf16 v[20:23], v[174:177], v[206:209], v[20:23]
	v_mfma_f32_16x16x32_bf16 v[16:19], v[182:185], v[206:209], v[16:19]
	v_mfma_f32_16x16x32_bf16 v[4:7], v[174:177], v[214:217], v[4:7]
	v_mfma_f32_16x16x32_bf16 v[0:3], v[182:185], v[214:217], v[0:3]
	s_barrier
	s_setprio 0
	s_add_i32 s52, 0, 0x18000
	v_add_u32_e32 v136, s52, v152
	s_add_i32 s53, 0, 0x1c000
	ds_read_b128 v[146:149], v136
	ds_read_b128 v[158:161], v136 offset:1024
	ds_read_b128 v[162:165], v136 offset:2048
	ds_read_b128 v[166:169], v136 offset:3072
	v_add_u32_e32 v136, s53, v152
	ds_read_b128 v[170:173], v136
	ds_read_b128 v[174:177], v136 offset:1024
	ds_read_b128 v[178:181], v136 offset:2048
	ds_read_b128 v[182:185], v136 offset:3072
	s_add_u32 s26, s26, 0x100000
	s_addc_u32 s27, s27, 0
	s_mov_b32 m0, s34
	v_lshl_add_u64 v[226:227], s[26:27], 0, v[134:135]
	ds_read_b128 v[186:189], v156 offset:32768
	ds_read_b128 v[190:193], v156 offset:33792
	ds_read_b128 v[194:197], v156 offset:34816
	ds_read_b128 v[198:201], v156 offset:35840
	ds_read_b128 v[202:205], v156 offset:36864
	ds_read_b128 v[206:209], v156 offset:37888
	ds_read_b128 v[210:213], v156 offset:38912
	ds_read_b128 v[214:217], v156 offset:39936
	global_load_lds_dwordx4 v[226:227], off
	v_lshl_add_u64 v[226:227], s[26:27], 0, v[130:131]
	s_mov_b32 m0, s35
	s_nop 0
	global_load_lds_dwordx4 v[226:227], off
	s_waitcnt vmcnt(8)
	s_waitcnt lgkmcnt(0)
	s_setprio 1
	s_barrier
	v_mfma_f32_16x16x32_bf16 v[124:127], v[146:149], v[186:189], v[124:127]
	v_mfma_f32_16x16x32_bf16 v[120:123], v[162:165], v[186:189], v[120:123]
	v_mfma_f32_16x16x32_bf16 v[108:111], v[146:149], v[194:197], v[108:111]
	v_mfma_f32_16x16x32_bf16 v[104:107], v[162:165], v[194:197], v[104:107]
	v_mfma_f32_16x16x32_bf16 v[92:95], v[146:149], v[202:205], v[92:95]
	v_mfma_f32_16x16x32_bf16 v[88:91], v[162:165], v[202:205], v[88:91]
	v_mfma_f32_16x16x32_bf16 v[76:79], v[146:149], v[210:213], v[76:79]
	v_mfma_f32_16x16x32_bf16 v[72:75], v[162:165], v[210:213], v[72:75]
	v_mfma_f32_16x16x32_bf16 v[124:127], v[158:161], v[190:193], v[124:127]
	v_mfma_f32_16x16x32_bf16 v[120:123], v[166:169], v[190:193], v[120:123]
	v_mfma_f32_16x16x32_bf16 v[108:111], v[158:161], v[198:201], v[108:111]
	v_mfma_f32_16x16x32_bf16 v[104:107], v[166:169], v[198:201], v[104:107]
	v_mfma_f32_16x16x32_bf16 v[92:95], v[158:161], v[206:209], v[92:95]
	v_mfma_f32_16x16x32_bf16 v[88:91], v[166:169], v[206:209], v[88:91]
	v_mfma_f32_16x16x32_bf16 v[76:79], v[158:161], v[214:217], v[76:79]
	v_mfma_f32_16x16x32_bf16 v[72:75], v[166:169], v[214:217], v[72:75]
	v_mfma_f32_16x16x32_bf16 v[116:119], v[170:173], v[186:189], v[116:119]
	v_mfma_f32_16x16x32_bf16 v[112:115], v[178:181], v[186:189], v[112:115]
	v_mfma_f32_16x16x32_bf16 v[100:103], v[170:173], v[194:197], v[100:103]
	v_mfma_f32_16x16x32_bf16 v[96:99], v[178:181], v[194:197], v[96:99]
	v_mfma_f32_16x16x32_bf16 v[84:87], v[170:173], v[202:205], v[84:87]
	v_mfma_f32_16x16x32_bf16 v[80:83], v[178:181], v[202:205], v[80:83]
	v_mfma_f32_16x16x32_bf16 v[68:71], v[170:173], v[210:213], v[68:71]
	v_mfma_f32_16x16x32_bf16 v[64:67], v[178:181], v[210:213], v[64:67]
	v_mfma_f32_16x16x32_bf16 v[116:119], v[174:177], v[190:193], v[116:119]
	v_mfma_f32_16x16x32_bf16 v[112:115], v[182:185], v[190:193], v[112:115]
	v_mfma_f32_16x16x32_bf16 v[100:103], v[174:177], v[198:201], v[100:103]
	v_mfma_f32_16x16x32_bf16 v[96:99], v[182:185], v[198:201], v[96:99]
	v_mfma_f32_16x16x32_bf16 v[84:87], v[174:177], v[206:209], v[84:87]
	v_mfma_f32_16x16x32_bf16 v[80:83], v[182:185], v[206:209], v[80:83]
	v_mfma_f32_16x16x32_bf16 v[68:71], v[174:177], v[214:217], v[68:71]
	v_mfma_f32_16x16x32_bf16 v[64:67], v[182:185], v[214:217], v[64:67]
	s_barrier
; #define PG8_STAGE(bufoff, gbase, voff) do { _Pragma("unroll") for (int _i = 0; _i < 2; ++_i) \
;         __builtin_amdgcn_global_load_lds((const unsigned*)((const char*)(gbase) + (voff)[_i]), (PG8_LAS unsigned*)(lds + (bufoff) + ldsw + _i * 8192), 16, 0, 0); } while (0)
; #define PG8_LDA(dst, b, h) do { _Pragma("unroll") for (int m = 0; m < 4; ++m) _Pragma("unroll") for (int k = 0; k < 2; ++k) dst[m][k] = *(const PG8_LAS bf16x8*)(lds + PG8_SA(b, h) + aoff + m * 2048 + k * 1024); } while (0)
; #define PG8_WAIT_V(n) asm volatile("s_waitcnt vmcnt(" #n ")" ::: "memory")
; #define PG8_WAIT_L(n) asm volatile("s_waitcnt lgkmcnt(" #n ")" ::: "memory")
; #define PG8_BAR __builtin_amdgcn_s_barrier()
; template <class Epi, class Sched, bool ALIGN_EPI = false, bool SP2 = false>
; __device__ __forceinline__ void gemm_phase(PG8_LAS unsigned char* lds, const Gemm g, const Sched& S, const Epi& E, const int wid) {
;     ...
;         for (int t = 0; t < nt; t += 2) {
;             const bool last = (t == nt - 2);
;             const char* a1 = cA + (size_t)(t + 1) * kstep;
;             const char* a2 = last ? nA : cA + (size_t)(t + 2) * kstep; const char* b2 = last ? nB : cB + (size_t)(t + 2) * kstep;
;             const char* a3 = a2 + kstep; const char* b3 = b2 + kstep;
;             if (last && has_next) S.a_ready(nxt);
;             if constexpr (SP2) {
;             PG8_LDB(B0, 0, 0); PG8_LDB(B1, 0, 1); PG8_SCHED; PG8_LDA(At, 0, 0); PG8_STAGE(PG8_SA(1, 1), a1 + hstep, voffA);
;             PG8_WAIT_V(8); PG8_WAIT_L(0); PG8_BAR; PG8_MMA(0, 0, At, B0); PG8_MMA(0, 1, At, B1); PG8_BAR; PG8_SCHED;
;             PG8_LDA(At, 0, 1); PG8_STAGE(PG8_SB(0, 0), b2, voffB); PG8_STAGE(PG8_SB(0, 1), b2 + hstep, voffB); PG8_STAGE(PG8_SA(0, 0), a2, voffA);
;             PG8_WAIT_V(8); PG8_WAIT_L(0); PG8_BAR; PG8_MMA(1, 0, At, B0); PG8_MMA(1, 1, At, B1); PG8_BAR; PG8_SCHED;
;             PG8_LDB(B0, 1, 0); PG8_LDB(B1, 1, 1); PG8_SCHED; PG8_LDA(At, 1, 0); PG8_STAGE(PG8_SA(0, 1), a2 + hstep, voffA);
;             PG8_WAIT_V(8); PG8_WAIT_L(0); PG8_BAR; PG8_MMA(0, 0, At, B0); PG8_MMA(0, 1, At, B1); PG8_BAR; PG8_SCHED;
;             PG8_LDA(At, 1, 1); PG8_STAGE(PG8_SB(1, 0), b3, voffB); PG8_STAGE(PG8_SB(1, 1), b3 + hstep, voffB); PG8_STAGE(PG8_SA(1, 0), a3, voffA);
;             PG8_WAIT_V(8); PG8_WAIT_L(0); PG8_BAR; PG8_MMA(1, 0, At, B0); PG8_MMA(1, 1, At, B1); PG8_BAR; PG8_SCHED;
	s_setprio 0
	s_add_i32 s26, s52, s28
	v_lshl_add_u64 v[218:219], v[218:219], 0, s[8:9]
	s_mov_b32 m0, s26
	ds_read_b128 v[186:189], v156 offset:49152
	ds_read_b128 v[190:193], v156 offset:50176
	ds_read_b128 v[194:197], v156 offset:51200
	ds_read_b128 v[198:201], v156 offset:52224
	ds_read_b128 v[202:205], v156 offset:53248
	ds_read_b128 v[206:209], v156 offset:54272
	ds_read_b128 v[210:213], v156 offset:55296
	ds_read_b128 v[214:217], v156 offset:56320
	global_load_lds_dwordx4 v[218:219], off
	s_add_i32 m0, s26, 0x2000
	s_add_u32 s24, s24, 0x100080
	v_lshl_add_u64 v[218:219], v[220:221], 0, s[8:9]
	s_addc_u32 s25, s25, 0
	s_add_i32 s26, s53, s28
	global_load_lds_dwordx4 v[218:219], off
	v_lshl_add_u64 v[218:219], s[24:25], 0, v[132:133]
	s_mov_b32 m0, s26
	s_nop 0
	global_load_lds_dwordx4 v[218:219], off
	v_lshl_add_u64 v[218:219], s[24:25], 0, v[128:129]
	s_add_i32 m0, s26, 0x2000
	s_nop 0
	global_load_lds_dwordx4 v[218:219], off
	v_lshl_add_u64 v[218:219], v[222:223], 0, s[8:9]
	s_mov_b32 m0, s37
	s_nop 0
	global_load_lds_dwordx4 v[218:219], off
	v_lshl_add_u64 v[218:219], v[224:225], 0, s[8:9]
	s_mov_b32 m0, s40
	s_nop 0
	global_load_lds_dwordx4 v[218:219], off
	s_waitcnt vmcnt(8)
	s_waitcnt lgkmcnt(0)
	s_setprio 1
	s_barrier
	v_mfma_f32_16x16x32_bf16 v[60:63], v[146:149], v[186:189], v[60:63]
	v_mfma_f32_16x16x32_bf16 v[56:59], v[162:165], v[186:189], v[56:59]
	v_mfma_f32_16x16x32_bf16 v[44:47], v[146:149], v[194:197], v[44:47]
	v_mfma_f32_16x16x32_bf16 v[40:43], v[162:165], v[194:197], v[40:43]
	v_mfma_f32_16x16x32_bf16 v[28:31], v[146:149], v[202:205], v[28:31]
	v_mfma_f32_16x16x32_bf16 v[24:27], v[162:165], v[202:205], v[24:27]
	v_mfma_f32_16x16x32_bf16 v[12:15], v[146:149], v[210:213], v[12:15]
	v_mfma_f32_16x16x32_bf16 v[8:11], v[162:165], v[210:213], v[8:11]
	v_mfma_f32_16x16x32_bf16 v[60:63], v[158:161], v[190:193], v[60:63]
	v_mfma_f32_16x16x32_bf16 v[56:59], v[166:169], v[190:193], v[56:59]
	v_mfma_f32_16x16x32_bf16 v[44:47], v[158:161], v[198:201], v[44:47]
	v_mfma_f32_16x16x32_bf16 v[40:43], v[166:169], v[198:201], v[40:43]
	v_mfma_f32_16x16x32_bf16 v[28:31], v[158:161], v[206:209], v[28:31]
	v_mfma_f32_16x16x32_bf16 v[24:27], v[166:169], v[206:209], v[24:27]
	v_mfma_f32_16x16x32_bf16 v[12:15], v[158:161], v[214:217], v[12:15]
	v_mfma_f32_16x16x32_bf16 v[8:11], v[166:169], v[214:217], v[8:11]
	v_mfma_f32_16x16x32_bf16 v[52:55], v[170:173], v[186:189], v[52:55]
	v_mfma_f32_16x16x32_bf16 v[48:51], v[178:181], v[186:189], v[48:51]
	v_mfma_f32_16x16x32_bf16 v[36:39], v[170:173], v[194:197], v[36:39]
	v_mfma_f32_16x16x32_bf16 v[32:35], v[178:181], v[194:197], v[32:35]
	v_mfma_f32_16x16x32_bf16 v[20:23], v[170:173], v[202:205], v[20:23]
	v_mfma_f32_16x16x32_bf16 v[16:19], v[178:181], v[202:205], v[16:19]
	v_mfma_f32_16x16x32_bf16 v[4:7], v[170:173], v[210:213], v[4:7]
	v_mfma_f32_16x16x32_bf16 v[0:3], v[178:181], v[210:213], v[0:3]
	v_mfma_f32_16x16x32_bf16 v[52:55], v[174:177], v[190:193], v[52:55]
	v_mfma_f32_16x16x32_bf16 v[48:51], v[182:185], v[190:193], v[48:51]
	v_mfma_f32_16x16x32_bf16 v[36:39], v[174:177], v[198:201], v[36:39]
	v_mfma_f32_16x16x32_bf16 v[32:35], v[182:185], v[198:201], v[32:35]
	v_mfma_f32_16x16x32_bf16 v[20:23], v[174:177], v[206:209], v[20:23]
	v_mfma_f32_16x16x32_bf16 v[16:19], v[182:185], v[206:209], v[16:19]
	v_mfma_f32_16x16x32_bf16 v[4:7], v[174:177], v[214:217], v[4:7]
	v_mfma_f32_16x16x32_bf16 v[0:3], v[182:185], v[214:217], v[0:3]
	s_barrier
	s_setprio 0
	s_add_i32 s51, s51, 2
	s_add_u32 s22, s22, 0x100
	s_addc_u32 s23, s23, 0
	s_add_u32 s49, s49, 0x100
	s_addc_u32 s50, s50, 0
	s_cmp_gt_u32 s51, 61
	s_cbranch_scc0 .LBB0_1764
	s_and_b64 vcc, exec, s[10:11]
	s_cbranch_vccz .LBB0_1767
	s_barrier

; #define PG8_STAGE(bufoff, gbase, voff) do { _Pragma("unroll") for (int _i = 0; _i < 2; ++_i) \
;         __builtin_amdgcn_global_load_lds((const unsigned*)((const char*)(gbase) + (voff)[_i]), (PG8_LAS unsigned*)(lds + (bufoff) + ldsw + _i * 8192), 16, 0, 0); } while (0)
; #define PG8_LDA(dst, b, h) do { _Pragma("unroll") for (int m = 0; m < 4; ++m) _Pragma("unroll") for (int k = 0; k < 2; ++k) dst[m][k] = *(const PG8_LAS bf16x8*)(lds + PG8_SA(b, h) + aoff + m * 2048 + k * 1024); } while (0)
; #define PG8_LDB(dst, b, h) do { _Pragma("unroll") for (int n = 0; n < 2; ++n) _Pragma("unroll") for (int k = 0; k < 2; ++k) dst[n][k] = *(const PG8_LAS bf16x8*)(lds + PG8_SB(b, h) + boff + n * 2048 + k * 1024); } while (0)
; #define PG8_MMA(ai, bj, At, Bt) do { __builtin_amdgcn_s_setprio(1); _Pragma("unroll") for (int m = 0; m < 4; ++m) _Pragma("unroll") for (int n = 0; n < 2; ++n) _Pragma("unroll") for (int k = 0; k < 2; ++k) \
;         acc[ai][bj][m][n] = __builtin_amdgcn_mfma_f32_16x16x32_bf16(Bt[n][k], At[m][k], acc[ai][bj][m][n], 0, 0, 0); __builtin_amdgcn_s_setprio(0); } while (0)
; #define PG8_BAR __builtin_amdgcn_s_barrier()
; template <class Epi, class Sched, bool ALIGN_EPI = false, bool SP2 = false>
; __device__ __forceinline__ void gemm_phase(PG8_LAS unsigned char* lds, const Gemm g, const Sched& S, const Epi& E, const int wid) {
;     ...
;             PG8_LDB(B0, 0, 0); PG8_LDB(B1, 0, 1); PG8_SCHED; PG8_LDA(At, 0, 0); PG8_STAGE(PG8_SA(1, 1), a1 + hstep, voffA);
;             PG8_WAIT_V(8); PG8_WAIT_L(0); PG8_BAR; PG8_MMA(0, 0, At, B0); PG8_MMA(0, 1, At, B1); PG8_BAR; PG8_SCHED;
;             PG8_LDA(At, 0, 1); PG8_STAGE(PG8_SB(0, 0), b2, voffB); PG8_STAGE(PG8_SB(0, 1), b2 + hstep, voffB); PG8_STAGE(PG8_SA(0, 0), a2, voffA);
;             PG8_WAIT_V(8); PG8_WAIT_L(0); PG8_BAR; PG8_MMA(1, 0, At, B0); PG8_MMA(1, 1, At, B1); PG8_BAR; PG8_SCHED;
;             PG8_LDB(B0, 1, 0); PG8_LDB(B1, 1, 1); PG8_SCHED; PG8_LDA(At, 1, 0); PG8_STAGE(PG8_SA(0, 1), a2 + hstep, voffA);
;             PG8_WAIT_V(8); PG8_WAIT_L(0); PG8_BAR; PG8_MMA(0, 0, At, B0); PG8_MMA(0, 1, At, B1); PG8_BAR; PG8_SCHED;
;             PG8_LDA(At, 1, 1); PG8_STAGE(PG8_SB(1, 0), b3, voffB); PG8_STAGE(PG8_SB(1, 1), b3 + hstep, voffB); PG8_STAGE(PG8_SA(1, 0), a3, voffA);
;             PG8_WAIT_V(8); PG8_WAIT_L(0); PG8_BAR; PG8_MMA(1, 0, At, B0); PG8_MMA(1, 1, At, B1); PG8_BAR; PG8_SCHED;
.LBB0_2055:
	ds_read_b128 v[144:147], v155
	ds_read_b128 v[148:151], v155 offset:1024
	ds_read_b128 v[158:161], v155 offset:2048
	ds_read_b128 v[162:165], v155 offset:3072
	ds_read_b128 v[166:169], v156
	ds_read_b128 v[170:173], v156 offset:1024
	ds_read_b128 v[174:177], v156 offset:2048
	ds_read_b128 v[178:181], v156 offset:3072
	s_add_u32 s14, s12, 0x100
	s_addc_u32 s15, s13, 0
	s_cmpk_eq_i32 s42, 0xa8
	s_cselect_b32 s19, s3, s15
	s_cselect_b32 s18, s2, s14
	s_cselect_b32 s17, s11, s41
	s_cselect_b32 s16, s10, s40
	v_lshl_add_u64 v[214:215], s[12:13], 0, v[136:137]
	s_add_i32 m0, s24, 0xc000
	ds_read_b128 v[182:185], v157
	ds_read_b128 v[186:189], v157 offset:1024
	ds_read_b128 v[190:193], v157 offset:2048
	ds_read_b128 v[194:197], v157 offset:3072
	ds_read_b128 v[198:201], v157 offset:4096
	ds_read_b128 v[202:205], v157 offset:5120
	ds_read_b128 v[206:209], v157 offset:6144
	ds_read_b128 v[210:213], v157 offset:7168
	global_load_lds_dwordx4 v[214:215], off
	v_lshl_add_u64 v[214:215], s[12:13], 0, v[138:139]
	s_add_i32 m0, s24, 0xe000
	s_nop 0
	global_load_lds_dwordx4 v[214:215], off
	s_waitcnt vmcnt(8)
	s_waitcnt lgkmcnt(0)
	s_setprio 1
	s_barrier
	v_mfma_f32_16x16x32_bf16 v[124:127], v[144:147], v[182:185], v[124:127]
	v_mfma_f32_16x16x32_bf16 v[120:123], v[158:161], v[182:185], v[120:123]
	v_mfma_f32_16x16x32_bf16 v[108:111], v[144:147], v[190:193], v[108:111]
	v_mfma_f32_16x16x32_bf16 v[104:107], v[158:161], v[190:193], v[104:107]
	v_mfma_f32_16x16x32_bf16 v[96:99], v[144:147], v[198:201], v[96:99]
	v_mfma_f32_16x16x32_bf16 v[88:91], v[158:161], v[198:201], v[88:91]
	v_mfma_f32_16x16x32_bf16 v[80:83], v[144:147], v[206:209], v[80:83]
	v_mfma_f32_16x16x32_bf16 v[72:75], v[158:161], v[206:209], v[72:75]
	v_mfma_f32_16x16x32_bf16 v[124:127], v[148:151], v[186:189], v[124:127]
	v_mfma_f32_16x16x32_bf16 v[120:123], v[162:165], v[186:189], v[120:123]
	v_mfma_f32_16x16x32_bf16 v[108:111], v[148:151], v[194:197], v[108:111]
	v_mfma_f32_16x16x32_bf16 v[104:107], v[162:165], v[194:197], v[104:107]
	v_mfma_f32_16x16x32_bf16 v[96:99], v[148:151], v[202:205], v[96:99]
	v_mfma_f32_16x16x32_bf16 v[88:91], v[162:165], v[202:205], v[88:91]
	v_mfma_f32_16x16x32_bf16 v[80:83], v[148:151], v[210:213], v[80:83]
	v_mfma_f32_16x16x32_bf16 v[72:75], v[162:165], v[210:213], v[72:75]
	v_mfma_f32_16x16x32_bf16 v[116:119], v[166:169], v[182:185], v[116:119]
	v_mfma_f32_16x16x32_bf16 v[112:115], v[174:177], v[182:185], v[112:115]
	v_mfma_f32_16x16x32_bf16 v[100:103], v[166:169], v[190:193], v[100:103]
	v_mfma_f32_16x16x32_bf16 v[92:95], v[174:177], v[190:193], v[92:95]
	v_mfma_f32_16x16x32_bf16 v[84:87], v[166:169], v[198:201], v[84:87]
	v_mfma_f32_16x16x32_bf16 v[76:79], v[174:177], v[198:201], v[76:79]
	v_mfma_f32_16x16x32_bf16 v[68:71], v[166:169], v[206:209], v[68:71]
	v_mfma_f32_16x16x32_bf16 v[64:67], v[174:177], v[206:209], v[64:67]
	v_mfma_f32_16x16x32_bf16 v[116:119], v[170:173], v[186:189], v[116:119]
	v_mfma_f32_16x16x32_bf16 v[112:115], v[178:181], v[186:189], v[112:115]
	v_mfma_f32_16x16x32_bf16 v[100:103], v[170:173], v[194:197], v[100:103]
	v_mfma_f32_16x16x32_bf16 v[92:95], v[178:181], v[194:197], v[92:95]
	v_mfma_f32_16x16x32_bf16 v[84:87], v[170:173], v[202:205], v[84:87]
	v_mfma_f32_16x16x32_bf16 v[76:79], v[178:181], v[202:205], v[76:79]
	v_mfma_f32_16x16x32_bf16 v[68:71], v[170:173], v[210:213], v[68:71]
	v_mfma_f32_16x16x32_bf16 v[64:67], v[178:181], v[210:213], v[64:67]
	s_barrier
	s_setprio 0
	s_add_i32 s12, s34, s23
	v_lshl_add_u64 v[214:215], s[16:17], 0, v[130:131]
	s_mov_b32 m0, s12
	ds_read_b128 v[182:185], v157 offset:16384
	ds_read_b128 v[186:189], v157 offset:17408
	ds_read_b128 v[190:193], v157 offset:18432
	ds_read_b128 v[194:197], v157 offset:19456
	ds_read_b128 v[198:201], v157 offset:20480
	ds_read_b128 v[202:205], v157 offset:21504
	ds_read_b128 v[206:209], v157 offset:22528
	ds_read_b128 v[210:213], v157 offset:23552
	global_load_lds_dwordx4 v[214:215], off
	s_add_i32 m0, s12, 0x2000
	s_add_u32 s12, s16, 0x2b0000
	v_lshl_add_u64 v[216:217], s[16:17], 0, v[134:135]
	s_addc_u32 s13, s17, 0
	s_add_i32 s43, s35, s23
	global_load_lds_dwordx4 v[216:217], off
	v_lshl_add_u64 v[218:219], s[12:13], 0, v[130:131]
	s_mov_b32 m0, s43
	v_lshl_add_u64 v[220:221], s[18:19], 0, v[132:133]
	global_load_lds_dwordx4 v[218:219], off
	v_lshl_add_u64 v[218:219], s[12:13], 0, v[134:135]
	s_add_i32 m0, s43, 0x2000
	s_nop 0
	global_load_lds_dwordx4 v[218:219], off
	v_lshl_add_u64 v[218:219], s[18:19], 0, v[128:129]
	s_mov_b32 m0, s24
	s_nop 0
	global_load_lds_dwordx4 v[218:219], off
	s_mov_b32 m0, s25
	s_nop 0
	global_load_lds_dwordx4 v[220:221], off
	s_waitcnt vmcnt(8)
	s_waitcnt lgkmcnt(0)
	s_setprio 1
	s_barrier
; #define PG8_STAGE(bufoff, gbase, voff) do { _Pragma("unroll") for (int _i = 0; _i < 2; ++_i) \
;         __builtin_amdgcn_global_load_lds((const unsigned*)((const char*)(gbase) + (voff)[_i]), (PG8_LAS unsigned*)(lds + (bufoff) + ldsw + _i * 8192), 16, 0, 0); } while (0)
; #define PG8_LDA(dst, b, h) do { _Pragma("unroll") for (int m = 0; m < 4; ++m) _Pragma("unroll") for (int k = 0; k < 2; ++k) dst[m][k] = *(const PG8_LAS bf16x8*)(lds + PG8_SA(b, h) + aoff + m * 2048 + k * 1024); } while (0)
; #define PG8_LDB(dst, b, h) do { _Pragma("unroll") for (int n = 0; n < 2; ++n) _Pragma("unroll") for (int k = 0; k < 2; ++k) dst[n][k] = *(const PG8_LAS bf16x8*)(lds + PG8_SB(b, h) + boff + n * 2048 + k * 1024); } while (0)
; #define PG8_MMA(ai, bj, At, Bt) do { __builtin_amdgcn_s_setprio(1); _Pragma("unroll") for (int m = 0; m < 4; ++m) _Pragma("unroll") for (int n = 0; n < 2; ++n) _Pragma("unroll") for (int k = 0; k < 2; ++k) \
;         acc[ai][bj][m][n] = __builtin_amdgcn_mfma_f32_16x16x32_bf16(Bt[n][k], At[m][k], acc[ai][bj][m][n], 0, 0, 0); __builtin_amdgcn_s_setprio(0); } while (0)
; #define PG8_BAR __builtin_amdgcn_s_barrier()
; template <class Epi, class Sched, bool ALIGN_EPI = false, bool SP2 = false>
; __device__ __forceinline__ void gemm_phase(PG8_LAS unsigned char* lds, const Gemm g, const Sched& S, const Epi& E, const int wid) {
;     ...
;             PG8_LDB(B0, 0, 0); PG8_LDB(B1, 0, 1); PG8_SCHED; PG8_LDA(At, 0, 0); PG8_STAGE(PG8_SA(1, 1), a1 + hstep, voffA);
;             PG8_WAIT_V(8); PG8_WAIT_L(0); PG8_BAR; PG8_MMA(0, 0, At, B0); PG8_MMA(0, 1, At, B1); PG8_BAR; PG8_SCHED;
;             PG8_LDA(At, 0, 1); PG8_STAGE(PG8_SB(0, 0), b2, voffB); PG8_STAGE(PG8_SB(0, 1), b2 + hstep, voffB); PG8_STAGE(PG8_SA(0, 0), a2, voffA);
;             PG8_WAIT_V(8); PG8_WAIT_L(0); PG8_BAR; PG8_MMA(1, 0, At, B0); PG8_MMA(1, 1, At, B1); PG8_BAR; PG8_SCHED;
;             PG8_LDB(B0, 1, 0); PG8_LDB(B1, 1, 1); PG8_SCHED; PG8_LDA(At, 1, 0); PG8_STAGE(PG8_SA(0, 1), a2 + hstep, voffA);
;             PG8_WAIT_V(8); PG8_WAIT_L(0); PG8_BAR; PG8_MMA(0, 0, At, B0); PG8_MMA(0, 1, At, B1); PG8_BAR; PG8_SCHED;
;             PG8_LDA(At, 1, 1); PG8_STAGE(PG8_SB(1, 0), b3, voffB); PG8_STAGE(PG8_SB(1, 1), b3 + hstep, voffB); PG8_STAGE(PG8_SA(1, 0), a3, voffA);
;             PG8_WAIT_V(8); PG8_WAIT_L(0); PG8_BAR; PG8_MMA(1, 0, At, B0); PG8_MMA(1, 1, At, B1); PG8_BAR; PG8_SCHED;
	v_mfma_f32_16x16x32_bf16 v[60:63], v[144:147], v[182:185], v[60:63]
	v_mfma_f32_16x16x32_bf16 v[56:59], v[158:161], v[182:185], v[56:59]
	v_mfma_f32_16x16x32_bf16 v[48:51], v[144:147], v[190:193], v[48:51]
	v_mfma_f32_16x16x32_bf16 v[40:43], v[158:161], v[190:193], v[40:43]
	v_mfma_f32_16x16x32_bf16 v[32:35], v[144:147], v[198:201], v[32:35]
	v_mfma_f32_16x16x32_bf16 v[24:27], v[158:161], v[198:201], v[24:27]
	v_mfma_f32_16x16x32_bf16 v[16:19], v[144:147], v[206:209], v[16:19]
	v_mfma_f32_16x16x32_bf16 v[8:11], v[158:161], v[206:209], v[8:11]
	v_mfma_f32_16x16x32_bf16 v[60:63], v[148:151], v[186:189], v[60:63]
	v_mfma_f32_16x16x32_bf16 v[56:59], v[162:165], v[186:189], v[56:59]
	v_mfma_f32_16x16x32_bf16 v[48:51], v[148:151], v[194:197], v[48:51]
	v_mfma_f32_16x16x32_bf16 v[40:43], v[162:165], v[194:197], v[40:43]
	v_mfma_f32_16x16x32_bf16 v[32:35], v[148:151], v[202:205], v[32:35]
	v_mfma_f32_16x16x32_bf16 v[24:27], v[162:165], v[202:205], v[24:27]
	v_mfma_f32_16x16x32_bf16 v[16:19], v[148:151], v[210:213], v[16:19]
	v_mfma_f32_16x16x32_bf16 v[8:11], v[162:165], v[210:213], v[8:11]
	v_mfma_f32_16x16x32_bf16 v[52:55], v[166:169], v[182:185], v[52:55]
	v_mfma_f32_16x16x32_bf16 v[44:47], v[174:177], v[182:185], v[44:47]
	v_mfma_f32_16x16x32_bf16 v[36:39], v[166:169], v[190:193], v[36:39]
	v_mfma_f32_16x16x32_bf16 v[28:31], v[174:177], v[190:193], v[28:31]
	v_mfma_f32_16x16x32_bf16 v[20:23], v[166:169], v[198:201], v[20:23]
	v_mfma_f32_16x16x32_bf16 v[12:15], v[174:177], v[198:201], v[12:15]
	v_mfma_f32_16x16x32_bf16 v[4:7], v[166:169], v[206:209], v[4:7]
	v_mfma_f32_16x16x32_bf16 v[0:3], v[174:177], v[206:209], v[0:3]
	v_mfma_f32_16x16x32_bf16 v[52:55], v[170:173], v[186:189], v[52:55]
	v_mfma_f32_16x16x32_bf16 v[44:47], v[178:181], v[186:189], v[44:47]
	v_mfma_f32_16x16x32_bf16 v[36:39], v[170:173], v[194:197], v[36:39]
	v_mfma_f32_16x16x32_bf16 v[28:31], v[178:181], v[194:197], v[28:31]
	v_mfma_f32_16x16x32_bf16 v[20:23], v[170:173], v[202:205], v[20:23]
	v_mfma_f32_16x16x32_bf16 v[12:15], v[178:181], v[202:205], v[12:15]
	v_mfma_f32_16x16x32_bf16 v[4:7], v[170:173], v[210:213], v[4:7]
	v_mfma_f32_16x16x32_bf16 v[0:3], v[178:181], v[210:213], v[0:3]
	s_barrier
	s_setprio 0
	s_add_i32 s43, 0, 0x18000
	s_add_i32 s44, 0, 0x1c000
	v_add_u32_e32 v162, s43, v153
	v_add_u32_e32 v178, s44, v153
	ds_read_b128 v[144:147], v162
	ds_read_b128 v[148:151], v162 offset:1024
	ds_read_b128 v[158:161], v162 offset:2048
	ds_read_b128 v[162:165], v162 offset:3072
	ds_read_b128 v[166:169], v178
	ds_read_b128 v[170:173], v178 offset:1024
	ds_read_b128 v[174:177], v178 offset:2048
	ds_read_b128 v[178:181], v178 offset:3072
	s_add_u32 s12, s18, 0x2b0000
	s_addc_u32 s13, s19, 0
	s_mov_b32 m0, s26
	v_lshl_add_u64 v[222:223], s[12:13], 0, v[128:129]
	ds_read_b128 v[182:185], v157 offset:32768
	ds_read_b128 v[186:189], v157 offset:33792
	ds_read_b128 v[190:193], v157 offset:34816
	ds_read_b128 v[194:197], v157 offset:35840
	ds_read_b128 v[198:201], v157 offset:36864
	ds_read_b128 v[202:205], v157 offset:37888
	ds_read_b128 v[206:209], v157 offset:38912
	ds_read_b128 v[210:213], v157 offset:39936
	global_load_lds_dwordx4 v[222:223], off
	v_lshl_add_u64 v[222:223], s[12:13], 0, v[132:133]
	s_mov_b32 m0, s27
	s_nop 0
	global_load_lds_dwordx4 v[222:223], off
	s_waitcnt vmcnt(8)
	s_waitcnt lgkmcnt(0)
	s_setprio 1
	s_barrier
	v_mfma_f32_16x16x32_bf16 v[124:127], v[144:147], v[182:185], v[124:127]
	v_mfma_f32_16x16x32_bf16 v[120:123], v[158:161], v[182:185], v[120:123]
	v_mfma_f32_16x16x32_bf16 v[108:111], v[144:147], v[190:193], v[108:111]
	v_mfma_f32_16x16x32_bf16 v[104:107], v[158:161], v[190:193], v[104:107]
	v_mfma_f32_16x16x32_bf16 v[96:99], v[144:147], v[198:201], v[96:99]
	v_mfma_f32_16x16x32_bf16 v[88:91], v[158:161], v[198:201], v[88:91]
	v_mfma_f32_16x16x32_bf16 v[80:83], v[144:147], v[206:209], v[80:83]
	v_mfma_f32_16x16x32_bf16 v[72:75], v[158:161], v[206:209], v[72:75]
	v_mfma_f32_16x16x32_bf16 v[124:127], v[148:151], v[186:189], v[124:127]
	v_mfma_f32_16x16x32_bf16 v[120:123], v[162:165], v[186:189], v[120:123]
	v_mfma_f32_16x16x32_bf16 v[108:111], v[148:151], v[194:197], v[108:111]
	v_mfma_f32_16x16x32_bf16 v[104:107], v[162:165], v[194:197], v[104:107]
	v_mfma_f32_16x16x32_bf16 v[96:99], v[148:151], v[202:205], v[96:99]
	v_mfma_f32_16x16x32_bf16 v[88:91], v[162:165], v[202:205], v[88:91]
	v_mfma_f32_16x16x32_bf16 v[80:83], v[148:151], v[210:213], v[80:83]
	v_mfma_f32_16x16x32_bf16 v[72:75], v[162:165], v[210:213], v[72:75]
	v_mfma_f32_16x16x32_bf16 v[116:119], v[166:169], v[182:185], v[116:119]
	v_mfma_f32_16x16x32_bf16 v[112:115], v[174:177], v[182:185], v[112:115]
	v_mfma_f32_16x16x32_bf16 v[100:103], v[166:169], v[190:193], v[100:103]
	v_mfma_f32_16x16x32_bf16 v[92:95], v[174:177], v[190:193], v[92:95]
	v_mfma_f32_16x16x32_bf16 v[84:87], v[166:169], v[198:201], v[84:87]
	v_mfma_f32_16x16x32_bf16 v[76:79], v[174:177], v[198:201], v[76:79]
	v_mfma_f32_16x16x32_bf16 v[68:71], v[166:169], v[206:209], v[68:71]
	v_mfma_f32_16x16x32_bf16 v[64:67], v[174:177], v[206:209], v[64:67]
	v_mfma_f32_16x16x32_bf16 v[116:119], v[170:173], v[186:189], v[116:119]
	v_mfma_f32_16x16x32_bf16 v[112:115], v[178:181], v[186:189], v[112:115]
	v_mfma_f32_16x16x32_bf16 v[100:103], v[170:173], v[194:197], v[100:103]
	v_mfma_f32_16x16x32_bf16 v[92:95], v[178:181], v[194:197], v[92:95]
	v_mfma_f32_16x16x32_bf16 v[84:87], v[170:173], v[202:205], v[84:87]
	v_mfma_f32_16x16x32_bf16 v[76:79], v[178:181], v[202:205], v[76:79]
	v_mfma_f32_16x16x32_bf16 v[68:71], v[170:173], v[210:213], v[68:71]
	v_mfma_f32_16x16x32_bf16 v[64:67], v[178:181], v[210:213], v[64:67]
	s_barrier
; #define PG8_STAGE(bufoff, gbase, voff) do { _Pragma("unroll") for (int _i = 0; _i < 2; ++_i) \
;         __builtin_amdgcn_global_load_lds((const unsigned*)((const char*)(gbase) + (voff)[_i]), (PG8_LAS unsigned*)(lds + (bufoff) + ldsw + _i * 8192), 16, 0, 0); } while (0)
; #define PG8_LDA(dst, b, h) do { _Pragma("unroll") for (int m = 0; m < 4; ++m) _Pragma("unroll") for (int k = 0; k < 2; ++k) dst[m][k] = *(const PG8_LAS bf16x8*)(lds + PG8_SA(b, h) + aoff + m * 2048 + k * 1024); } while (0)
; #define PG8_MMA(ai, bj, At, Bt) do { __builtin_amdgcn_s_setprio(1); _Pragma("unroll") for (int m = 0; m < 4; ++m) _Pragma("unroll") for (int n = 0; n < 2; ++n) _Pragma("unroll") for (int k = 0; k < 2; ++k) \
;         acc[ai][bj][m][n] = __builtin_amdgcn_mfma_f32_16x16x32_bf16(Bt[n][k], At[m][k], acc[ai][bj][m][n], 0, 0, 0); __builtin_amdgcn_s_setprio(0); } while (0)
; #define PG8_WAIT_V(n) asm volatile("s_waitcnt vmcnt(" #n ")" ::: "memory")
; #define PG8_WAIT_L(n) asm volatile("s_waitcnt lgkmcnt(" #n ")" ::: "memory")
; #define PG8_BAR __builtin_amdgcn_s_barrier()
; #define PG8_SCHED __builtin_amdgcn_sched_barrier(0)
; template <class Epi, class Sched, bool ALIGN_EPI = false, bool SP2 = false>
; __device__ __forceinline__ void gemm_phase(PG8_LAS unsigned char* lds, const Gemm g, const Sched& S, const Epi& E, const int wid) {
;     ...
;             PG8_LDA(At, 1, 1); PG8_STAGE(PG8_SB(1, 0), b3, voffB); PG8_STAGE(PG8_SB(1, 1), b3 + hstep, voffB); PG8_STAGE(PG8_SA(1, 0), a3, voffA);
;             PG8_WAIT_V(8); PG8_WAIT_L(0); PG8_BAR; PG8_MMA(1, 0, At, B0); PG8_MMA(1, 1, At, B1); PG8_BAR; PG8_SCHED;
	s_setprio 0
	s_add_i32 s12, s43, s23
	v_lshl_add_u64 v[214:215], v[214:215], 0, s[6:7]
	s_mov_b32 m0, s12
	ds_read_b128 v[182:185], v157 offset:49152
	ds_read_b128 v[186:189], v157 offset:50176
	ds_read_b128 v[190:193], v157 offset:51200
	ds_read_b128 v[194:197], v157 offset:52224
	ds_read_b128 v[198:201], v157 offset:53248
	ds_read_b128 v[202:205], v157 offset:54272
	ds_read_b128 v[206:209], v157 offset:55296
	ds_read_b128 v[210:213], v157 offset:56320
	global_load_lds_dwordx4 v[214:215], off
	s_add_i32 m0, s12, 0x2000
	s_add_u32 s12, s16, 0x2b0080
	v_lshl_add_u64 v[214:215], v[216:217], 0, s[6:7]
	s_addc_u32 s13, s17, 0
	s_add_i32 s16, s44, s23
	global_load_lds_dwordx4 v[214:215], off
	v_lshl_add_u64 v[214:215], s[12:13], 0, v[130:131]
	s_mov_b32 m0, s16
	s_nop 0
	global_load_lds_dwordx4 v[214:215], off
	v_lshl_add_u64 v[214:215], s[12:13], 0, v[134:135]
	s_add_i32 m0, s16, 0x2000
	s_nop 0
	global_load_lds_dwordx4 v[214:215], off
	v_lshl_add_u64 v[214:215], v[218:219], 0, s[6:7]
	s_mov_b32 m0, s29
	s_nop 0
	global_load_lds_dwordx4 v[214:215], off
	v_lshl_add_u64 v[214:215], v[220:221], 0, s[6:7]
	s_mov_b32 m0, s30
	s_nop 0
	global_load_lds_dwordx4 v[214:215], off
	s_waitcnt vmcnt(8)
	s_waitcnt lgkmcnt(0)
	s_setprio 1
	s_barrier
	v_mfma_f32_16x16x32_bf16 v[60:63], v[144:147], v[182:185], v[60:63]
	v_mfma_f32_16x16x32_bf16 v[56:59], v[158:161], v[182:185], v[56:59]
	v_mfma_f32_16x16x32_bf16 v[48:51], v[144:147], v[190:193], v[48:51]
	v_mfma_f32_16x16x32_bf16 v[40:43], v[158:161], v[190:193], v[40:43]
	v_mfma_f32_16x16x32_bf16 v[32:35], v[144:147], v[198:201], v[32:35]
	v_mfma_f32_16x16x32_bf16 v[24:27], v[158:161], v[198:201], v[24:27]
	v_mfma_f32_16x16x32_bf16 v[16:19], v[144:147], v[206:209], v[16:19]
	v_mfma_f32_16x16x32_bf16 v[8:11], v[158:161], v[206:209], v[8:11]
	v_mfma_f32_16x16x32_bf16 v[60:63], v[148:151], v[186:189], v[60:63]
	v_mfma_f32_16x16x32_bf16 v[56:59], v[162:165], v[186:189], v[56:59]
	v_mfma_f32_16x16x32_bf16 v[48:51], v[148:151], v[194:197], v[48:51]
	v_mfma_f32_16x16x32_bf16 v[40:43], v[162:165], v[194:197], v[40:43]
	v_mfma_f32_16x16x32_bf16 v[32:35], v[148:151], v[202:205], v[32:35]
	v_mfma_f32_16x16x32_bf16 v[24:27], v[162:165], v[202:205], v[24:27]
	v_mfma_f32_16x16x32_bf16 v[16:19], v[148:151], v[210:213], v[16:19]
	v_mfma_f32_16x16x32_bf16 v[8:11], v[162:165], v[210:213], v[8:11]
	v_mfma_f32_16x16x32_bf16 v[52:55], v[166:169], v[182:185], v[52:55]
	v_mfma_f32_16x16x32_bf16 v[44:47], v[174:177], v[182:185], v[44:47]
	v_mfma_f32_16x16x32_bf16 v[36:39], v[166:169], v[190:193], v[36:39]
	v_mfma_f32_16x16x32_bf16 v[28:31], v[174:177], v[190:193], v[28:31]
	v_mfma_f32_16x16x32_bf16 v[20:23], v[166:169], v[198:201], v[20:23]
	v_mfma_f32_16x16x32_bf16 v[12:15], v[174:177], v[198:201], v[12:15]
	v_mfma_f32_16x16x32_bf16 v[4:7], v[166:169], v[206:209], v[4:7]
	v_mfma_f32_16x16x32_bf16 v[0:3], v[174:177], v[206:209], v[0:3]
	v_mfma_f32_16x16x32_bf16 v[52:55], v[170:173], v[186:189], v[52:55]
	v_mfma_f32_16x16x32_bf16 v[44:47], v[178:181], v[186:189], v[44:47]
	v_mfma_f32_16x16x32_bf16 v[36:39], v[170:173], v[194:197], v[36:39]
	v_mfma_f32_16x16x32_bf16 v[28:31], v[178:181], v[194:197], v[28:31]
	v_mfma_f32_16x16x32_bf16 v[20:23], v[170:173], v[202:205], v[20:23]
	v_mfma_f32_16x16x32_bf16 v[12:15], v[178:181], v[202:205], v[12:15]
	v_mfma_f32_16x16x32_bf16 v[4:7], v[170:173], v[210:213], v[4:7]
	v_mfma_f32_16x16x32_bf16 v[0:3], v[178:181], v[210:213], v[0:3]
	s_barrier
	s_setprio 0
	s_add_i32 s42, s42, 2
	s_add_u32 s40, s40, 0x100
	s_addc_u32 s41, s41, 0
	s_cmpk_gt_u32 s42, 0xa9
	s_mov_b64 s[12:13], s[14:15]
	s_cbranch_scc0 .LBB0_2055
	s_and_b64 vcc, exec, s[8:9]
	s_cbranch_vccz .LBB0_2058
	s_barrier
